# next unit's SA(1,1) tile staged at the epilogue start; first k-iteration of non-first units skips that stage and its first vmcnt wait so the write-through store drain overlaps MFMA work (kinds 0,2,3)
# baseline (speedup 1.0000x reference)
.LBB0_211:
	s_add_i32 s60, s60, 1
	s_mov_b64 s[36:37], s[18:19]
	s_mul_i32 s18, s60, s26
	s_add_i32 s38, s18, s2
	s_cmpk_gt_i32 s38, 0x1ff
	s_cselect_b64 s[44:45], -1, 0
	s_lshl_b32 s18, s38, 3
	s_and_b32 s18, s18, 56
	s_bfe_u32 s19, s38, 0x30003
	s_mov_b32 s27, s61
	s_or_b32 s61, s18, s19
	s_mov_b32 s3, s42
	s_ashr_i32 s42, s38, 6
	s_lshl_b32 s18, s61, 19
	s_mov_b64 s[4:5], s[20:21]
	s_add_u32 s20, s14, s18
	s_addc_u32 s21, s15, 0
	s_ashr_i32 s43, s42, 31
	s_lshl_b64 s[18:19], s[42:43], 19
	s_add_u32 s18, s16, s18
	s_addc_u32 s19, s17, s19
	s_cmpk_lt_i32 s38, 0x200
	s_cselect_b32 s38, s21, s5
	s_cselect_b32 s43, s20, s4
	s_cselect_b32 s62, s19, s37
	s_cselect_b32 s63, s18, s36
	s_add_u32 s64, s36, 0x100
	s_addc_u32 s65, s37, 0
	s_mov_b32 s66, -2
	s_waitcnt lgkmcnt(0)
	s_add_u32 s36, s4, 0x100
	s_addc_u32 s37, s5, 0
	s_add_i32 s67, 0, 0x10000
	v_add_u32_e32 v1, s67, v191
	ds_read_b128 v[34:37], v1
	ds_read_b128 v[38:41], v1 offset:1024
	ds_read_b128 v[42:45], v1 offset:2048
	ds_read_b128 v[46:49], v1 offset:3072
	s_cmp_eq_u32 s66, 12
	s_cselect_b32 s49, s38, s37
	s_cselect_b32 s48, s43, s36
	s_cselect_b32 s47, s62, s65
	s_cselect_b32 s46, s63, s64
	v_lshl_add_u64 v[186:187], s[4:5], 0, v[168:169]
	s_add_i32 m0, s53, 0xc000
	ds_read_b128 v[50:53], v206
	ds_read_b128 v[58:61], v206 offset:1024
	ds_read_b128 v[62:65], v206 offset:2048
	ds_read_b128 v[66:69], v206 offset:3072
	ds_read_b128 v[170:173], v206 offset:4096
	ds_read_b128 v[174:177], v206 offset:5120
	ds_read_b128 v[178:181], v206 offset:6144
	ds_read_b128 v[182:185], v206 offset:7168
	s_cmp_lg_u32 s60, 1
	s_cbranch_scc1 .Lpk3_d0
	global_load_lds_dwordx4 v[186:187], off
.Lpk3_d0:
	v_lshl_add_u64 v[186:187], s[4:5], 0, v[166:167]
	s_add_i32 m0, s53, 0xe000
	s_nop 0
	s_cmp_lg_u32 s60, 1
	s_cbranch_scc1 .Lpk3_d1
	global_load_lds_dwordx4 v[186:187], off
.Lpk3_d1:
	s_waitcnt lgkmcnt(8)
	s_barrier
	s_waitcnt lgkmcnt(0)
	s_setprio 1
	s_waitcnt lgkmcnt(0)
	v_mfma_f32_16x16x32_bf16 v[158:161], v[34:37], v[50:53], 0
	v_mfma_f32_16x16x32_bf16 v[154:157], v[42:45], v[50:53], 0
	v_mfma_f32_16x16x32_bf16 v[142:145], v[34:37], v[62:65], 0
	v_mfma_f32_16x16x32_bf16 v[138:141], v[42:45], v[62:65], 0
	v_mfma_f32_16x16x32_bf16 v[126:129], v[34:37], v[170:173], 0
	v_mfma_f32_16x16x32_bf16 v[122:125], v[42:45], v[170:173], 0
	v_mfma_f32_16x16x32_bf16 v[110:113], v[34:37], v[178:181], 0
	v_mfma_f32_16x16x32_bf16 v[106:109], v[42:45], v[178:181], 0
	v_mfma_f32_16x16x32_bf16 v[158:161], v[38:41], v[58:61], v[158:161]
	v_mfma_f32_16x16x32_bf16 v[154:157], v[46:49], v[58:61], v[154:157]
	v_mfma_f32_16x16x32_bf16 v[142:145], v[38:41], v[66:69], v[142:145]
	v_mfma_f32_16x16x32_bf16 v[138:141], v[46:49], v[66:69], v[138:141]
	v_mfma_f32_16x16x32_bf16 v[126:129], v[38:41], v[174:177], v[126:129]
	v_mfma_f32_16x16x32_bf16 v[122:125], v[46:49], v[174:177], v[122:125]
	v_mfma_f32_16x16x32_bf16 v[110:113], v[38:41], v[182:185], v[110:113]
	v_mfma_f32_16x16x32_bf16 v[106:109], v[46:49], v[182:185], v[106:109]
	s_setprio 0
	s_barrier
	s_add_i32 s68, 0, 0x14000
	s_add_i32 s4, s67, s52
	v_add_u32_e32 v1, s68, v191
	v_lshl_add_u64 v[214:215], s[46:47], 0, v[164:165]
	s_mov_b32 m0, s4
	ds_read_b128 v[186:189], v1
	ds_read_b128 v[208:211], v1 offset:1024
	ds_read_b128 v[222:225], v1 offset:2048
	ds_read_b128 v[226:229], v1 offset:3072
	global_load_lds_dwordx4 v[214:215], off
	v_lshl_add_u64 v[238:239], s[46:47], 0, v[162:163]
	s_add_i32 m0, s4, 0x2000
	s_nop 0
	global_load_lds_dwordx4 v[238:239], off
	s_barrier
	s_waitcnt lgkmcnt(0)
	s_setprio 1
	s_waitcnt lgkmcnt(0)
	v_mfma_f32_16x16x32_bf16 v[150:153], v[186:189], v[50:53], 0
	v_mfma_f32_16x16x32_bf16 v[50:53], v[222:225], v[50:53], 0
	v_mfma_f32_16x16x32_bf16 v[150:153], v[208:211], v[58:61], v[150:153]
	v_mfma_f32_16x16x32_bf16 v[50:53], v[226:229], v[58:61], v[50:53]
	v_mfma_f32_16x16x32_bf16 v[58:61], v[186:189], v[62:65], 0
	v_mfma_f32_16x16x32_bf16 v[62:65], v[222:225], v[62:65], 0
	v_mfma_f32_16x16x32_bf16 v[114:117], v[222:225], v[170:173], 0
	v_mfma_f32_16x16x32_bf16 v[102:105], v[186:189], v[178:181], 0
	v_mfma_f32_16x16x32_bf16 v[98:101], v[222:225], v[178:181], 0
	v_mfma_f32_16x16x32_bf16 v[58:61], v[208:211], v[66:69], v[58:61]
	v_mfma_f32_16x16x32_bf16 v[62:65], v[226:229], v[66:69], v[62:65]
	v_mfma_f32_16x16x32_bf16 v[66:69], v[186:189], v[170:173], 0
	v_mfma_f32_16x16x32_bf16 v[114:117], v[226:229], v[174:177], v[114:117]
	v_mfma_f32_16x16x32_bf16 v[102:105], v[208:211], v[182:185], v[102:105]
	v_mfma_f32_16x16x32_bf16 v[98:101], v[226:229], v[182:185], v[98:101]
	v_mfma_f32_16x16x32_bf16 v[66:69], v[208:211], v[174:177], v[66:69]
	s_setprio 0
	s_mov_b32 m0, s53
	v_lshl_add_u64 v[240:241], s[48:49], 0, v[164:165]
	s_barrier
	ds_read_b128 v[118:121], v206 offset:16384
	ds_read_b128 v[130:133], v206 offset:17408
	ds_read_b128 v[134:137], v206 offset:18432
	ds_read_b128 v[146:149], v206 offset:19456
	ds_read_b128 v[170:173], v206 offset:20480
	ds_read_b128 v[174:177], v206 offset:21504
	ds_read_b128 v[178:181], v206 offset:22528
	ds_read_b128 v[182:185], v206 offset:23552
	global_load_lds_dwordx4 v[240:241], off
	v_lshl_add_u64 v[242:243], s[48:49], 0, v[162:163]
	s_mov_b32 m0, s54
	s_nop 0
	global_load_lds_dwordx4 v[242:243], off
	s_barrier
	s_waitcnt lgkmcnt(0)
	s_setprio 1
	s_waitcnt lgkmcnt(0)
	v_mfma_f32_16x16x32_bf16 v[94:97], v[34:37], v[118:121], 0
	v_mfma_f32_16x16x32_bf16 v[90:93], v[42:45], v[118:121], 0
	v_mfma_f32_16x16x32_bf16 v[78:81], v[34:37], v[134:137], 0
	v_mfma_f32_16x16x32_bf16 v[74:77], v[42:45], v[134:137], 0
	v_mfma_f32_16x16x32_bf16 v[30:33], v[34:37], v[170:173], 0
	v_mfma_f32_16x16x32_bf16 v[26:29], v[42:45], v[170:173], 0
	v_mfma_f32_16x16x32_bf16 v[14:17], v[34:37], v[178:181], 0
	v_mfma_f32_16x16x32_bf16 v[10:13], v[42:45], v[178:181], 0
	v_mfma_f32_16x16x32_bf16 v[94:97], v[38:41], v[130:133], v[94:97]
	v_mfma_f32_16x16x32_bf16 v[90:93], v[46:49], v[130:133], v[90:93]
	v_mfma_f32_16x16x32_bf16 v[78:81], v[38:41], v[146:149], v[78:81]
	v_mfma_f32_16x16x32_bf16 v[74:77], v[46:49], v[146:149], v[74:77]
	v_mfma_f32_16x16x32_bf16 v[30:33], v[38:41], v[174:177], v[30:33]
	v_mfma_f32_16x16x32_bf16 v[26:29], v[46:49], v[174:177], v[26:29]
	v_mfma_f32_16x16x32_bf16 v[14:17], v[38:41], v[182:185], v[14:17]
	v_mfma_f32_16x16x32_bf16 v[10:13], v[46:49], v[182:185], v[10:13]
	s_setprio 0
	s_barrier
	s_add_u32 s4, s46, 0x40000
	s_addc_u32 s5, s47, 0
	s_add_i32 s67, s68, s52
	v_lshl_add_u64 v[34:35], s[4:5], 0, v[164:165]
	s_mov_b32 m0, s67
	s_nop 0
	global_load_lds_dwordx4 v[34:35], off
	v_lshl_add_u64 v[34:35], s[4:5], 0, v[162:163]
	s_add_i32 m0, s67, 0x2000
	s_nop 0
	global_load_lds_dwordx4 v[34:35], off
	s_cmp_lg_u32 s60, 1
	s_cbranch_scc1 .Lpk3_w
	s_waitcnt vmcnt(6)
.Lpk3_w:
	s_barrier
	s_setprio 1
	v_mfma_f32_16x16x32_bf16 v[22:25], v[186:189], v[170:173], 0
	v_mfma_f32_16x16x32_bf16 v[18:21], v[222:225], v[170:173], 0
	v_mfma_f32_16x16x32_bf16 v[6:9], v[186:189], v[178:181], 0
	v_mfma_f32_16x16x32_bf16 v[2:5], v[222:225], v[178:181], 0
	v_mfma_f32_16x16x32_bf16 v[34:37], v[186:189], v[118:121], 0
	v_mfma_f32_16x16x32_bf16 v[38:41], v[222:225], v[118:121], 0
	v_mfma_f32_16x16x32_bf16 v[42:45], v[186:189], v[134:137], 0
	v_mfma_f32_16x16x32_bf16 v[46:49], v[222:225], v[134:137], 0
	v_mfma_f32_16x16x32_bf16 v[22:25], v[208:211], v[174:177], v[22:25]
	v_mfma_f32_16x16x32_bf16 v[18:21], v[226:229], v[174:177], v[18:21]
	v_mfma_f32_16x16x32_bf16 v[6:9], v[208:211], v[182:185], v[6:9]
	v_mfma_f32_16x16x32_bf16 v[2:5], v[226:229], v[182:185], v[2:5]
	v_mfma_f32_16x16x32_bf16 v[34:37], v[208:211], v[130:133], v[34:37]
	v_mfma_f32_16x16x32_bf16 v[38:41], v[226:229], v[130:133], v[38:41]
	v_mfma_f32_16x16x32_bf16 v[42:45], v[208:211], v[146:149], v[42:45]
	v_mfma_f32_16x16x32_bf16 v[46:49], v[226:229], v[146:149], v[46:49]
	s_setprio 0
	s_add_i32 s67, 0, 0x18000
	v_add_u32_e32 v1, s67, v191
	s_barrier
	ds_read_b128 v[54:57], v1
	ds_read_b128 v[70:73], v1 offset:1024
	ds_read_b128 v[82:85], v1 offset:2048
	ds_read_b128 v[86:89], v1 offset:3072
	s_add_u32 s4, s48, 0x40000
	s_addc_u32 s5, s49, 0
	s_mov_b32 m0, s55
	v_lshl_add_u64 v[134:135], s[4:5], 0, v[164:165]
	ds_read_b128 v[118:121], v206 offset:32768
	ds_read_b128 v[130:133], v206 offset:33792
	ds_read_b128 v[170:173], v206 offset:34816
	ds_read_b128 v[174:177], v206 offset:35840
	ds_read_b128 v[178:181], v206 offset:36864
	ds_read_b128 v[182:185], v206 offset:37888
	ds_read_b128 v[186:189], v206 offset:38912
	ds_read_b128 v[208:211], v206 offset:39936
	global_load_lds_dwordx4 v[134:135], off
	v_lshl_add_u64 v[134:135], s[4:5], 0, v[162:163]
	s_mov_b32 m0, s56
	s_nop 0
	global_load_lds_dwordx4 v[134:135], off
	s_waitcnt lgkmcnt(8)
	s_barrier
	s_waitcnt lgkmcnt(0)
	s_setprio 1
	s_waitcnt lgkmcnt(0)
	v_mfma_f32_16x16x32_bf16 v[134:137], v[54:57], v[118:121], v[158:161]
	v_mfma_f32_16x16x32_bf16 v[158:161], v[70:73], v[130:133], v[134:137]
	v_mfma_f32_16x16x32_bf16 v[134:137], v[82:85], v[118:121], v[154:157]
	v_mfma_f32_16x16x32_bf16 v[154:157], v[86:89], v[130:133], v[134:137]
	v_mfma_f32_16x16x32_bf16 v[134:137], v[54:57], v[170:173], v[142:145]
	v_mfma_f32_16x16x32_bf16 v[142:145], v[70:73], v[174:177], v[134:137]
	v_mfma_f32_16x16x32_bf16 v[134:137], v[82:85], v[170:173], v[138:141]
	v_mfma_f32_16x16x32_bf16 v[126:129], v[54:57], v[178:181], v[126:129]
	v_mfma_f32_16x16x32_bf16 v[122:125], v[82:85], v[178:181], v[122:125]
	v_mfma_f32_16x16x32_bf16 v[110:113], v[54:57], v[186:189], v[110:113]
	v_mfma_f32_16x16x32_bf16 v[106:109], v[82:85], v[186:189], v[106:109]
	v_mfma_f32_16x16x32_bf16 v[138:141], v[86:89], v[174:177], v[134:137]
	v_mfma_f32_16x16x32_bf16 v[126:129], v[70:73], v[182:185], v[126:129]
	v_mfma_f32_16x16x32_bf16 v[122:125], v[86:89], v[182:185], v[122:125]
	v_mfma_f32_16x16x32_bf16 v[110:113], v[70:73], v[208:211], v[110:113]
	v_mfma_f32_16x16x32_bf16 v[106:109], v[86:89], v[208:211], v[106:109]
	s_setprio 0
	s_barrier
	s_add_i32 s48, 0, 0x1c000
	s_add_i32 s4, s67, s52
	v_add_u32_e32 v1, s48, v191
	v_lshl_add_u64 v[134:135], v[214:215], 0, s[22:23]
	s_mov_b32 m0, s4
	ds_read_b128 v[222:225], v1
	ds_read_b128 v[226:229], v1 offset:1024
	ds_read_b128 v[230:233], v1 offset:2048
	ds_read_b128 v[234:237], v1 offset:3072
	global_load_lds_dwordx4 v[134:135], off
	v_lshl_add_u64 v[134:135], v[238:239], 0, s[22:23]
	s_add_i32 m0, s4, 0x2000
	s_nop 0
	global_load_lds_dwordx4 v[134:135], off
	s_barrier
	s_waitcnt lgkmcnt(0)
	s_setprio 1
	s_waitcnt lgkmcnt(0)
	v_mfma_f32_16x16x32_bf16 v[50:53], v[230:233], v[118:121], v[50:53]
	v_mfma_f32_16x16x32_bf16 v[134:137], v[222:225], v[118:121], v[150:153]
	v_mfma_f32_16x16x32_bf16 v[146:149], v[234:237], v[130:133], v[50:53]
	v_mfma_f32_16x16x32_bf16 v[50:53], v[222:225], v[170:173], v[58:61]
	v_mfma_f32_16x16x32_bf16 v[150:153], v[226:229], v[130:133], v[134:137]
	v_mfma_f32_16x16x32_bf16 v[134:137], v[226:229], v[174:177], v[50:53]
	v_mfma_f32_16x16x32_bf16 v[50:53], v[230:233], v[170:173], v[62:65]
	v_mfma_f32_16x16x32_bf16 v[130:133], v[234:237], v[174:177], v[50:53]
	v_mfma_f32_16x16x32_bf16 v[50:53], v[222:225], v[178:181], v[66:69]
	v_mfma_f32_16x16x32_bf16 v[118:121], v[226:229], v[182:185], v[50:53]
	v_mfma_f32_16x16x32_bf16 v[50:53], v[230:233], v[178:181], v[114:117]
	v_mfma_f32_16x16x32_bf16 v[114:117], v[234:237], v[182:185], v[50:53]
	v_mfma_f32_16x16x32_bf16 v[50:53], v[222:225], v[186:189], v[102:105]
	v_mfma_f32_16x16x32_bf16 v[102:105], v[226:229], v[208:211], v[50:53]
	v_mfma_f32_16x16x32_bf16 v[50:53], v[230:233], v[186:189], v[98:101]
	v_mfma_f32_16x16x32_bf16 v[98:101], v[234:237], v[208:211], v[50:53]
	s_setprio 0
	s_mov_b32 m0, s58
	v_lshl_add_u64 v[186:187], v[240:241], 0, s[22:23]
	s_barrier
	s_nop 2
	ds_read_b128 v[50:53], v206 offset:49152
	ds_read_b128 v[58:61], v206 offset:50176
	ds_read_b128 v[62:65], v206 offset:51200
	ds_read_b128 v[66:69], v206 offset:52224
	ds_read_b128 v[170:173], v206 offset:53248
	ds_read_b128 v[174:177], v206 offset:54272
	ds_read_b128 v[178:181], v206 offset:55296
	ds_read_b128 v[182:185], v206 offset:56320
	global_load_lds_dwordx4 v[186:187], off
	v_lshl_add_u64 v[186:187], v[242:243], 0, s[22:23]
	s_mov_b32 m0, s59
	s_nop 0
	global_load_lds_dwordx4 v[186:187], off
	s_barrier
	s_waitcnt lgkmcnt(0)
	s_setprio 1
	s_waitcnt lgkmcnt(0)
	v_mfma_f32_16x16x32_bf16 v[94:97], v[54:57], v[50:53], v[94:97]
	v_mfma_f32_16x16x32_bf16 v[90:93], v[82:85], v[50:53], v[90:93]
	v_mfma_f32_16x16x32_bf16 v[78:81], v[54:57], v[62:65], v[78:81]
	v_mfma_f32_16x16x32_bf16 v[74:77], v[82:85], v[62:65], v[74:77]
	v_mfma_f32_16x16x32_bf16 v[30:33], v[54:57], v[170:173], v[30:33]
	v_mfma_f32_16x16x32_bf16 v[26:29], v[82:85], v[170:173], v[26:29]
	v_mfma_f32_16x16x32_bf16 v[14:17], v[54:57], v[178:181], v[14:17]
	v_mfma_f32_16x16x32_bf16 v[10:13], v[82:85], v[178:181], v[10:13]
	v_mfma_f32_16x16x32_bf16 v[94:97], v[70:73], v[58:61], v[94:97]
	v_mfma_f32_16x16x32_bf16 v[90:93], v[86:89], v[58:61], v[90:93]
	v_mfma_f32_16x16x32_bf16 v[78:81], v[70:73], v[66:69], v[78:81]
	v_mfma_f32_16x16x32_bf16 v[74:77], v[86:89], v[66:69], v[74:77]
	v_mfma_f32_16x16x32_bf16 v[30:33], v[70:73], v[174:177], v[30:33]
	v_mfma_f32_16x16x32_bf16 v[26:29], v[86:89], v[174:177], v[26:29]
	v_mfma_f32_16x16x32_bf16 v[14:17], v[70:73], v[182:185], v[14:17]
	v_mfma_f32_16x16x32_bf16 v[10:13], v[86:89], v[182:185], v[10:13]
	s_setprio 0
	s_barrier
	s_add_u32 s4, s46, 0x40080
	s_addc_u32 s5, s47, 0
	s_add_i32 s46, s48, s52
	v_lshl_add_u64 v[54:55], s[4:5], 0, v[164:165]
	s_mov_b32 m0, s46
	s_nop 0
	global_load_lds_dwordx4 v[54:55], off
	v_lshl_add_u64 v[54:55], s[4:5], 0, v[162:163]
	s_add_i32 m0, s46, 0x2000
	s_nop 0
	global_load_lds_dwordx4 v[54:55], off
	s_waitcnt vmcnt(6)
	s_barrier
	s_setprio 1
	v_mfma_f32_16x16x32_bf16 v[34:37], v[222:225], v[50:53], v[34:37]
	v_mfma_f32_16x16x32_bf16 v[86:89], v[226:229], v[58:61], v[34:37]
	v_mfma_f32_16x16x32_bf16 v[34:37], v[230:233], v[50:53], v[38:41]
	v_mfma_f32_16x16x32_bf16 v[82:85], v[234:237], v[58:61], v[34:37]
	v_mfma_f32_16x16x32_bf16 v[34:37], v[222:225], v[62:65], v[42:45]
	v_mfma_f32_16x16x32_bf16 v[70:73], v[226:229], v[66:69], v[34:37]
	v_mfma_f32_16x16x32_bf16 v[34:37], v[230:233], v[62:65], v[46:49]
	v_mfma_f32_16x16x32_bf16 v[22:25], v[222:225], v[170:173], v[22:25]
	v_mfma_f32_16x16x32_bf16 v[18:21], v[230:233], v[170:173], v[18:21]
	v_mfma_f32_16x16x32_bf16 v[6:9], v[222:225], v[178:181], v[6:9]
	v_mfma_f32_16x16x32_bf16 v[2:5], v[230:233], v[178:181], v[2:5]
	v_mfma_f32_16x16x32_bf16 v[54:57], v[234:237], v[66:69], v[34:37]
	v_mfma_f32_16x16x32_bf16 v[22:25], v[226:229], v[174:177], v[22:25]
	v_mfma_f32_16x16x32_bf16 v[18:21], v[234:237], v[174:177], v[18:21]
	v_mfma_f32_16x16x32_bf16 v[6:9], v[226:229], v[182:185], v[6:9]
	v_mfma_f32_16x16x32_bf16 v[2:5], v[234:237], v[182:185], v[2:5]
	s_setprio 0
	s_add_i32 s66, s66, 2
	s_add_u32 s64, s64, 0x100
	s_addc_u32 s65, s65, 0
	s_cmp_gt_u32 s66, 13
	s_mov_b64 s[4:5], s[36:37]
	s_barrier
.LBB0_212:
	s_add_u32 s36, s4, 0x100
	s_addc_u32 s37, s5, 0
	s_add_i32 s67, 0, 0x10000
	v_add_u32_e32 v1, s67, v191
	ds_read_b128 v[34:37], v1
	ds_read_b128 v[38:41], v1 offset:1024
	ds_read_b128 v[42:45], v1 offset:2048
	ds_read_b128 v[46:49], v1 offset:3072
	s_cmp_eq_u32 s66, 12
	s_cselect_b32 s49, s38, s37
	s_cselect_b32 s48, s43, s36
	s_cselect_b32 s47, s62, s65
	s_cselect_b32 s46, s63, s64
	v_lshl_add_u64 v[186:187], s[4:5], 0, v[168:169]
	s_add_i32 m0, s53, 0xc000
	ds_read_b128 v[50:53], v206
	ds_read_b128 v[58:61], v206 offset:1024
	ds_read_b128 v[62:65], v206 offset:2048
	ds_read_b128 v[66:69], v206 offset:3072
	ds_read_b128 v[170:173], v206 offset:4096
	ds_read_b128 v[174:177], v206 offset:5120
	ds_read_b128 v[178:181], v206 offset:6144
	ds_read_b128 v[182:185], v206 offset:7168
	global_load_lds_dwordx4 v[186:187], off
	v_lshl_add_u64 v[186:187], s[4:5], 0, v[166:167]
	s_add_i32 m0, s53, 0xe000
	s_nop 0
	global_load_lds_dwordx4 v[186:187], off
	s_waitcnt lgkmcnt(8)
	s_barrier
	s_waitcnt lgkmcnt(0)
	s_setprio 1
	s_waitcnt lgkmcnt(0)
	v_mfma_f32_16x16x32_bf16 v[158:161], v[34:37], v[50:53], v[158:161]
	v_mfma_f32_16x16x32_bf16 v[154:157], v[42:45], v[50:53], v[154:157]
	v_mfma_f32_16x16x32_bf16 v[142:145], v[34:37], v[62:65], v[142:145]
	v_mfma_f32_16x16x32_bf16 v[138:141], v[42:45], v[62:65], v[138:141]
	v_mfma_f32_16x16x32_bf16 v[126:129], v[34:37], v[170:173], v[126:129]
	v_mfma_f32_16x16x32_bf16 v[122:125], v[42:45], v[170:173], v[122:125]
	v_mfma_f32_16x16x32_bf16 v[110:113], v[34:37], v[178:181], v[110:113]
	v_mfma_f32_16x16x32_bf16 v[106:109], v[42:45], v[178:181], v[106:109]
	v_mfma_f32_16x16x32_bf16 v[158:161], v[38:41], v[58:61], v[158:161]
	v_mfma_f32_16x16x32_bf16 v[154:157], v[46:49], v[58:61], v[154:157]
	v_mfma_f32_16x16x32_bf16 v[142:145], v[38:41], v[66:69], v[142:145]
	v_mfma_f32_16x16x32_bf16 v[138:141], v[46:49], v[66:69], v[138:141]
	v_mfma_f32_16x16x32_bf16 v[126:129], v[38:41], v[174:177], v[126:129]
	v_mfma_f32_16x16x32_bf16 v[122:125], v[46:49], v[174:177], v[122:125]
	v_mfma_f32_16x16x32_bf16 v[110:113], v[38:41], v[182:185], v[110:113]
	v_mfma_f32_16x16x32_bf16 v[106:109], v[46:49], v[182:185], v[106:109]
	s_setprio 0
	s_barrier
	s_add_i32 s68, 0, 0x14000
	s_add_i32 s4, s67, s52
	v_add_u32_e32 v1, s68, v191
	v_lshl_add_u64 v[214:215], s[46:47], 0, v[164:165]
	s_mov_b32 m0, s4
	ds_read_b128 v[186:189], v1
	ds_read_b128 v[208:211], v1 offset:1024
	ds_read_b128 v[222:225], v1 offset:2048
	ds_read_b128 v[226:229], v1 offset:3072
	global_load_lds_dwordx4 v[214:215], off
	v_lshl_add_u64 v[238:239], s[46:47], 0, v[162:163]
	s_add_i32 m0, s4, 0x2000
	s_nop 0
	global_load_lds_dwordx4 v[238:239], off
	s_barrier
	s_waitcnt lgkmcnt(0)
	s_setprio 1
	s_waitcnt lgkmcnt(0)
	v_mfma_f32_16x16x32_bf16 v[150:153], v[186:189], v[50:53], v[150:153]
	v_mfma_f32_16x16x32_bf16 v[50:53], v[222:225], v[50:53], v[146:149]
	v_mfma_f32_16x16x32_bf16 v[150:153], v[208:211], v[58:61], v[150:153]
	v_mfma_f32_16x16x32_bf16 v[50:53], v[226:229], v[58:61], v[50:53]
	v_mfma_f32_16x16x32_bf16 v[58:61], v[186:189], v[62:65], v[134:137]
	v_mfma_f32_16x16x32_bf16 v[62:65], v[222:225], v[62:65], v[130:133]
	v_mfma_f32_16x16x32_bf16 v[114:117], v[222:225], v[170:173], v[114:117]
	v_mfma_f32_16x16x32_bf16 v[102:105], v[186:189], v[178:181], v[102:105]
	v_mfma_f32_16x16x32_bf16 v[98:101], v[222:225], v[178:181], v[98:101]
	v_mfma_f32_16x16x32_bf16 v[58:61], v[208:211], v[66:69], v[58:61]
	v_mfma_f32_16x16x32_bf16 v[62:65], v[226:229], v[66:69], v[62:65]
	v_mfma_f32_16x16x32_bf16 v[66:69], v[186:189], v[170:173], v[118:121]
	v_mfma_f32_16x16x32_bf16 v[114:117], v[226:229], v[174:177], v[114:117]
	v_mfma_f32_16x16x32_bf16 v[102:105], v[208:211], v[182:185], v[102:105]
	v_mfma_f32_16x16x32_bf16 v[98:101], v[226:229], v[182:185], v[98:101]
	v_mfma_f32_16x16x32_bf16 v[66:69], v[208:211], v[174:177], v[66:69]
	s_setprio 0
	s_mov_b32 m0, s53
	v_lshl_add_u64 v[240:241], s[48:49], 0, v[164:165]
	s_barrier
	ds_read_b128 v[118:121], v206 offset:16384
	ds_read_b128 v[130:133], v206 offset:17408
	ds_read_b128 v[134:137], v206 offset:18432
	ds_read_b128 v[146:149], v206 offset:19456
	ds_read_b128 v[170:173], v206 offset:20480
	ds_read_b128 v[174:177], v206 offset:21504
	ds_read_b128 v[178:181], v206 offset:22528
	ds_read_b128 v[182:185], v206 offset:23552
	global_load_lds_dwordx4 v[240:241], off
	v_lshl_add_u64 v[242:243], s[48:49], 0, v[162:163]
	s_mov_b32 m0, s54
	s_nop 0
	global_load_lds_dwordx4 v[242:243], off
	s_barrier
	s_waitcnt lgkmcnt(0)
	s_setprio 1
	s_waitcnt lgkmcnt(0)
	v_mfma_f32_16x16x32_bf16 v[94:97], v[34:37], v[118:121], v[94:97]
	v_mfma_f32_16x16x32_bf16 v[90:93], v[42:45], v[118:121], v[90:93]
	v_mfma_f32_16x16x32_bf16 v[78:81], v[34:37], v[134:137], v[78:81]
	v_mfma_f32_16x16x32_bf16 v[74:77], v[42:45], v[134:137], v[74:77]
	v_mfma_f32_16x16x32_bf16 v[30:33], v[34:37], v[170:173], v[30:33]
	v_mfma_f32_16x16x32_bf16 v[26:29], v[42:45], v[170:173], v[26:29]
	v_mfma_f32_16x16x32_bf16 v[14:17], v[34:37], v[178:181], v[14:17]
	v_mfma_f32_16x16x32_bf16 v[10:13], v[42:45], v[178:181], v[10:13]
	v_mfma_f32_16x16x32_bf16 v[94:97], v[38:41], v[130:133], v[94:97]
	v_mfma_f32_16x16x32_bf16 v[90:93], v[46:49], v[130:133], v[90:93]
	v_mfma_f32_16x16x32_bf16 v[78:81], v[38:41], v[146:149], v[78:81]
	v_mfma_f32_16x16x32_bf16 v[74:77], v[46:49], v[146:149], v[74:77]
	v_mfma_f32_16x16x32_bf16 v[30:33], v[38:41], v[174:177], v[30:33]
	v_mfma_f32_16x16x32_bf16 v[26:29], v[46:49], v[174:177], v[26:29]
	v_mfma_f32_16x16x32_bf16 v[14:17], v[38:41], v[182:185], v[14:17]
	v_mfma_f32_16x16x32_bf16 v[10:13], v[46:49], v[182:185], v[10:13]
	s_setprio 0
	s_barrier
	s_add_u32 s4, s46, 0x40000
	s_addc_u32 s5, s47, 0
	s_add_i32 s67, s68, s52
	v_lshl_add_u64 v[34:35], s[4:5], 0, v[164:165]
	s_mov_b32 m0, s67
	s_nop 0
	global_load_lds_dwordx4 v[34:35], off
	v_lshl_add_u64 v[34:35], s[4:5], 0, v[162:163]
	s_add_i32 m0, s67, 0x2000
	s_nop 0
	global_load_lds_dwordx4 v[34:35], off
	s_waitcnt vmcnt(6)
	s_barrier
	s_setprio 1
	v_mfma_f32_16x16x32_bf16 v[22:25], v[186:189], v[170:173], v[22:25]
	v_mfma_f32_16x16x32_bf16 v[18:21], v[222:225], v[170:173], v[18:21]
	v_mfma_f32_16x16x32_bf16 v[6:9], v[186:189], v[178:181], v[6:9]
	v_mfma_f32_16x16x32_bf16 v[2:5], v[222:225], v[178:181], v[2:5]
	v_mfma_f32_16x16x32_bf16 v[34:37], v[186:189], v[118:121], v[86:89]
	v_mfma_f32_16x16x32_bf16 v[38:41], v[222:225], v[118:121], v[82:85]
	v_mfma_f32_16x16x32_bf16 v[42:45], v[186:189], v[134:137], v[70:73]
	v_mfma_f32_16x16x32_bf16 v[46:49], v[222:225], v[134:137], v[54:57]
	v_mfma_f32_16x16x32_bf16 v[22:25], v[208:211], v[174:177], v[22:25]
	v_mfma_f32_16x16x32_bf16 v[18:21], v[226:229], v[174:177], v[18:21]
	v_mfma_f32_16x16x32_bf16 v[6:9], v[208:211], v[182:185], v[6:9]
	v_mfma_f32_16x16x32_bf16 v[2:5], v[226:229], v[182:185], v[2:5]
	v_mfma_f32_16x16x32_bf16 v[34:37], v[208:211], v[130:133], v[34:37]
	v_mfma_f32_16x16x32_bf16 v[38:41], v[226:229], v[130:133], v[38:41]
	v_mfma_f32_16x16x32_bf16 v[42:45], v[208:211], v[146:149], v[42:45]
	v_mfma_f32_16x16x32_bf16 v[46:49], v[226:229], v[146:149], v[46:49]
	s_setprio 0
	s_add_i32 s67, 0, 0x18000
	v_add_u32_e32 v1, s67, v191
	s_barrier
	ds_read_b128 v[54:57], v1
	ds_read_b128 v[70:73], v1 offset:1024
	ds_read_b128 v[82:85], v1 offset:2048
	ds_read_b128 v[86:89], v1 offset:3072
	s_add_u32 s4, s48, 0x40000
	s_addc_u32 s5, s49, 0
	s_mov_b32 m0, s55
	v_lshl_add_u64 v[134:135], s[4:5], 0, v[164:165]
	ds_read_b128 v[118:121], v206 offset:32768
	ds_read_b128 v[130:133], v206 offset:33792
	ds_read_b128 v[170:173], v206 offset:34816
	ds_read_b128 v[174:177], v206 offset:35840
	ds_read_b128 v[178:181], v206 offset:36864
	ds_read_b128 v[182:185], v206 offset:37888
	ds_read_b128 v[186:189], v206 offset:38912
	ds_read_b128 v[208:211], v206 offset:39936
	global_load_lds_dwordx4 v[134:135], off
	v_lshl_add_u64 v[134:135], s[4:5], 0, v[162:163]
	s_mov_b32 m0, s56
	s_nop 0
	global_load_lds_dwordx4 v[134:135], off
	s_waitcnt lgkmcnt(8)
	s_barrier
	s_waitcnt lgkmcnt(0)
	s_setprio 1
	s_waitcnt lgkmcnt(0)
	v_mfma_f32_16x16x32_bf16 v[134:137], v[54:57], v[118:121], v[158:161]
	v_mfma_f32_16x16x32_bf16 v[158:161], v[70:73], v[130:133], v[134:137]
	v_mfma_f32_16x16x32_bf16 v[134:137], v[82:85], v[118:121], v[154:157]
	v_mfma_f32_16x16x32_bf16 v[154:157], v[86:89], v[130:133], v[134:137]
	v_mfma_f32_16x16x32_bf16 v[134:137], v[54:57], v[170:173], v[142:145]
	v_mfma_f32_16x16x32_bf16 v[142:145], v[70:73], v[174:177], v[134:137]
	v_mfma_f32_16x16x32_bf16 v[134:137], v[82:85], v[170:173], v[138:141]
	v_mfma_f32_16x16x32_bf16 v[126:129], v[54:57], v[178:181], v[126:129]
	v_mfma_f32_16x16x32_bf16 v[122:125], v[82:85], v[178:181], v[122:125]
	v_mfma_f32_16x16x32_bf16 v[110:113], v[54:57], v[186:189], v[110:113]
	v_mfma_f32_16x16x32_bf16 v[106:109], v[82:85], v[186:189], v[106:109]
	v_mfma_f32_16x16x32_bf16 v[138:141], v[86:89], v[174:177], v[134:137]
	v_mfma_f32_16x16x32_bf16 v[126:129], v[70:73], v[182:185], v[126:129]
	v_mfma_f32_16x16x32_bf16 v[122:125], v[86:89], v[182:185], v[122:125]
	v_mfma_f32_16x16x32_bf16 v[110:113], v[70:73], v[208:211], v[110:113]
	v_mfma_f32_16x16x32_bf16 v[106:109], v[86:89], v[208:211], v[106:109]
	s_setprio 0
	s_barrier
	s_add_i32 s48, 0, 0x1c000
	s_add_i32 s4, s67, s52
	v_add_u32_e32 v1, s48, v191
	v_lshl_add_u64 v[134:135], v[214:215], 0, s[22:23]
	s_mov_b32 m0, s4
	ds_read_b128 v[222:225], v1
	ds_read_b128 v[226:229], v1 offset:1024
	ds_read_b128 v[230:233], v1 offset:2048
	ds_read_b128 v[234:237], v1 offset:3072
	global_load_lds_dwordx4 v[134:135], off
	v_lshl_add_u64 v[134:135], v[238:239], 0, s[22:23]
	s_add_i32 m0, s4, 0x2000
	s_nop 0
	global_load_lds_dwordx4 v[134:135], off
	s_barrier
	s_waitcnt lgkmcnt(0)
	s_setprio 1
	s_waitcnt lgkmcnt(0)
	v_mfma_f32_16x16x32_bf16 v[50:53], v[230:233], v[118:121], v[50:53]
	v_mfma_f32_16x16x32_bf16 v[134:137], v[222:225], v[118:121], v[150:153]
	v_mfma_f32_16x16x32_bf16 v[146:149], v[234:237], v[130:133], v[50:53]
	v_mfma_f32_16x16x32_bf16 v[50:53], v[222:225], v[170:173], v[58:61]
	v_mfma_f32_16x16x32_bf16 v[150:153], v[226:229], v[130:133], v[134:137]
	v_mfma_f32_16x16x32_bf16 v[134:137], v[226:229], v[174:177], v[50:53]
	v_mfma_f32_16x16x32_bf16 v[50:53], v[230:233], v[170:173], v[62:65]
	v_mfma_f32_16x16x32_bf16 v[130:133], v[234:237], v[174:177], v[50:53]
	v_mfma_f32_16x16x32_bf16 v[50:53], v[222:225], v[178:181], v[66:69]
	v_mfma_f32_16x16x32_bf16 v[118:121], v[226:229], v[182:185], v[50:53]
	v_mfma_f32_16x16x32_bf16 v[50:53], v[230:233], v[178:181], v[114:117]
	v_mfma_f32_16x16x32_bf16 v[114:117], v[234:237], v[182:185], v[50:53]
	v_mfma_f32_16x16x32_bf16 v[50:53], v[222:225], v[186:189], v[102:105]
	v_mfma_f32_16x16x32_bf16 v[102:105], v[226:229], v[208:211], v[50:53]
	v_mfma_f32_16x16x32_bf16 v[50:53], v[230:233], v[186:189], v[98:101]
	v_mfma_f32_16x16x32_bf16 v[98:101], v[234:237], v[208:211], v[50:53]
	s_setprio 0
	s_mov_b32 m0, s58
	v_lshl_add_u64 v[186:187], v[240:241], 0, s[22:23]
	s_barrier
	s_nop 2
	ds_read_b128 v[50:53], v206 offset:49152
	ds_read_b128 v[58:61], v206 offset:50176
	ds_read_b128 v[62:65], v206 offset:51200
	ds_read_b128 v[66:69], v206 offset:52224
	ds_read_b128 v[170:173], v206 offset:53248
	ds_read_b128 v[174:177], v206 offset:54272
	ds_read_b128 v[178:181], v206 offset:55296
	ds_read_b128 v[182:185], v206 offset:56320
	global_load_lds_dwordx4 v[186:187], off
	v_lshl_add_u64 v[186:187], v[242:243], 0, s[22:23]
	s_mov_b32 m0, s59
	s_nop 0
	global_load_lds_dwordx4 v[186:187], off
	s_barrier
	s_waitcnt lgkmcnt(0)
	s_setprio 1
	s_waitcnt lgkmcnt(0)
	v_mfma_f32_16x16x32_bf16 v[94:97], v[54:57], v[50:53], v[94:97]
	v_mfma_f32_16x16x32_bf16 v[90:93], v[82:85], v[50:53], v[90:93]
	v_mfma_f32_16x16x32_bf16 v[78:81], v[54:57], v[62:65], v[78:81]
	v_mfma_f32_16x16x32_bf16 v[74:77], v[82:85], v[62:65], v[74:77]
	v_mfma_f32_16x16x32_bf16 v[30:33], v[54:57], v[170:173], v[30:33]
	v_mfma_f32_16x16x32_bf16 v[26:29], v[82:85], v[170:173], v[26:29]
	v_mfma_f32_16x16x32_bf16 v[14:17], v[54:57], v[178:181], v[14:17]
	v_mfma_f32_16x16x32_bf16 v[10:13], v[82:85], v[178:181], v[10:13]
	v_mfma_f32_16x16x32_bf16 v[94:97], v[70:73], v[58:61], v[94:97]
	v_mfma_f32_16x16x32_bf16 v[90:93], v[86:89], v[58:61], v[90:93]
	v_mfma_f32_16x16x32_bf16 v[78:81], v[70:73], v[66:69], v[78:81]
	v_mfma_f32_16x16x32_bf16 v[74:77], v[86:89], v[66:69], v[74:77]
	v_mfma_f32_16x16x32_bf16 v[30:33], v[70:73], v[174:177], v[30:33]
	v_mfma_f32_16x16x32_bf16 v[26:29], v[86:89], v[174:177], v[26:29]
	v_mfma_f32_16x16x32_bf16 v[14:17], v[70:73], v[182:185], v[14:17]
	v_mfma_f32_16x16x32_bf16 v[10:13], v[86:89], v[182:185], v[10:13]
	s_setprio 0
	s_barrier
	s_add_u32 s4, s46, 0x40080
	s_addc_u32 s5, s47, 0
	s_add_i32 s46, s48, s52
	v_lshl_add_u64 v[54:55], s[4:5], 0, v[164:165]
	s_mov_b32 m0, s46
	s_nop 0
	global_load_lds_dwordx4 v[54:55], off
	v_lshl_add_u64 v[54:55], s[4:5], 0, v[162:163]
	s_add_i32 m0, s46, 0x2000
	s_nop 0
	global_load_lds_dwordx4 v[54:55], off
	s_waitcnt vmcnt(6)
	s_barrier
	s_setprio 1
	v_mfma_f32_16x16x32_bf16 v[34:37], v[222:225], v[50:53], v[34:37]
	v_mfma_f32_16x16x32_bf16 v[86:89], v[226:229], v[58:61], v[34:37]
	v_mfma_f32_16x16x32_bf16 v[34:37], v[230:233], v[50:53], v[38:41]
	v_mfma_f32_16x16x32_bf16 v[82:85], v[234:237], v[58:61], v[34:37]
	v_mfma_f32_16x16x32_bf16 v[34:37], v[222:225], v[62:65], v[42:45]
	v_mfma_f32_16x16x32_bf16 v[70:73], v[226:229], v[66:69], v[34:37]
	v_mfma_f32_16x16x32_bf16 v[34:37], v[230:233], v[62:65], v[46:49]
	v_mfma_f32_16x16x32_bf16 v[22:25], v[222:225], v[170:173], v[22:25]
	v_mfma_f32_16x16x32_bf16 v[18:21], v[230:233], v[170:173], v[18:21]
	v_mfma_f32_16x16x32_bf16 v[6:9], v[222:225], v[178:181], v[6:9]
	v_mfma_f32_16x16x32_bf16 v[2:5], v[230:233], v[178:181], v[2:5]
	v_mfma_f32_16x16x32_bf16 v[54:57], v[234:237], v[66:69], v[34:37]
	v_mfma_f32_16x16x32_bf16 v[22:25], v[226:229], v[174:177], v[22:25]
	v_mfma_f32_16x16x32_bf16 v[18:21], v[234:237], v[174:177], v[18:21]
	v_mfma_f32_16x16x32_bf16 v[6:9], v[226:229], v[182:185], v[6:9]
	v_mfma_f32_16x16x32_bf16 v[2:5], v[234:237], v[182:185], v[2:5]
	s_setprio 0
	s_add_i32 s66, s66, 2
	s_add_u32 s64, s64, 0x100
	s_addc_u32 s65, s65, 0
	s_cmp_gt_u32 s66, 13
	s_mov_b64 s[4:5], s[36:37]
	s_barrier
	s_cbranch_scc0 .LBB0_212
	s_and_b64 vcc, exec, s[44:45]
	s_cbranch_vccnz .Lpk3_nonext
	v_lshl_add_u64 v[246:247], s[20:21], 0, v[168:169]
	s_add_i32 m0, s53, 0xc000
	s_nop 0
	global_load_lds_dwordx4 v[246:247], off
	v_lshl_add_u64 v[248:249], s[20:21], 0, v[166:167]
	s_add_i32 m0, s53, 0xe000
	s_nop 0
	global_load_lds_dwordx4 v[248:249], off
.Lpk3_nonext:
	v_lshl_or_b32 v208, s3, 8, v192
	v_mov_b32_e32 v1, v190
	v_ashrrev_i32_e32 v209, 31, v208
	v_lshlrev_b64 v[34:35], 2, v[208:209]
	v_lshl_add_u64 v[36:37], s[8:9], 0, v[34:35]
	flat_load_dwordx4 v[62:65], v[36:37]
	flat_load_dwordx4 v[50:53], v[36:37] offset:16
	v_lshl_add_u64 v[34:35], s[10:11], 0, v[34:35]
	flat_load_dwordx4 v[66:69], v[34:35]
	flat_load_dwordx4 v[42:45], v[34:35] offset:16
	flat_load_dwordx4 v[58:61], v[36:37] offset:512
	flat_load_dwordx4 v[38:41], v[36:37] offset:528
	flat_load_dwordx4 v[46:49], v[34:35] offset:512
	s_nop 0
	flat_load_dwordx4 v[34:37], v[34:35] offset:528
	s_lshl_b32 s37, s27, 8
	v_lshl_add_u32 v170, v1, 3, 0
	v_add_u32_e32 v170, 0x20040, v170
	s_waitcnt vmcnt(0)
	ds_read_b64 v[188:189], v170
	s_mov_b32 s4, 0xbf3a00e3
	s_cmp_gt_i32 s3, 3
	v_mov_b64_e32 v[176:177], s[4:5]
	s_cselect_b64 s[4:5], -1, 0
	s_and_b64 s[46:47], s[40:41], s[4:5]
	s_mov_b32 s4, 0x3f07dc22
	s_mov_b32 s38, 0x3f35f0e3
	s_mov_b32 s48, 0xbe11a98e
	s_mov_b32 s62, 0x3e027906
	s_lshl_b32 s3, s3, 2
	s_and_b32 s36, s3, 12
	s_mov_b32 s3, 0x1020000
	v_add_u32_e32 v170, s37, v1
	v_lshlrev_b32_e32 v1, 10, v170
	s_waitcnt lgkmcnt(0)
	v_xor_b32_e32 v65, 0x80000000, v65
	v_xor_b32_e32 v64, 0x80000000, v64
	v_pk_fma_f32 v[158:159], v[62:63], v[188:189], v[158:159] op_sel_hi:[1,0,1] neg_lo:[1,0,0] neg_hi:[1,0,0]
	v_xor_b32_e32 v53, 0x80000000, v53
	v_xor_b32_e32 v52, 0x80000000, v52
	v_pk_fma_f32 v[154:155], v[50:51], v[188:189], v[154:155] op_sel_hi:[1,0,1] neg_lo:[1,0,0] neg_hi:[1,0,0]
	v_pk_fma_f32 v[160:161], v[64:65], v[188:189], v[160:161] op_sel_hi:[1,0,1]
	v_pk_fma_f32 v[158:159], v[188:189], v[158:159], v[66:67] op_sel:[1,0,0]
	v_pk_fma_f32 v[172:173], v[52:53], v[188:189], v[156:157] op_sel_hi:[1,0,1]
	v_pk_fma_f32 v[156:157], v[188:189], v[154:155], v[42:43] op_sel:[1,0,0]
	v_pk_fma_f32 v[154:155], v[188:189], v[160:161], v[68:69] op_sel:[1,0,0]
	v_fma_f32 v175, |v159|, s1, 1.0
	v_fma_f32 v171, |v158|, s1, 1.0
	v_pk_fma_f32 v[160:161], v[188:189], v[172:173], v[44:45] op_sel:[1,0,0]
	v_fma_f32 v172, |v156|, s1, 1.0
	v_rcp_f32_e32 v175, v175
	v_fma_f32 v187, |v155|, s1, 1.0
	v_mul_f32_e32 v174, v158, v158
	v_rcp_f32_e32 v182, v171
	v_rcp_f32_e32 v183, v172
	v_rcp_f32_e32 v215, v187
	v_mul_f32_e32 v173, v156, v156
	v_fma_f32 v179, |v157|, s1, 1.0
	v_mul_f32_e32 v180, v157, v157
	v_mul_f32_e32 v171, 0xbf38aa3b, v174
	v_mul_f32_e32 v186, v154, v154
	v_fma_f32 v181, |v154|, s1, 1.0
	v_mul_f32_e32 v172, 0xbf38aa3b, v173
	v_rcp_f32_e32 v185, v179
	v_mul_f32_e32 v173, 0xbf38aa3b, v180
	v_fma_f32 v179, |v160|, s1, 1.0
	v_mul_f32_e32 v209, v160, v160
	v_exp_f32_e32 v180, v171
	v_mul_f32_e32 v171, 0xbf38aa3b, v186
	v_fma_f32 v211, |v161|, s1, 1.0
	v_rcp_f32_e32 v184, v181
	v_exp_f32_e32 v181, v172
	v_rcp_f32_e32 v210, v179
	v_mul_f32_e32 v179, 0xbf38aa3b, v209
	v_exp_f32_e32 v172, v171
	v_fmamk_f32 v171, v175, 0x3f07dc22, v218
	v_rcp_f32_e32 v211, v211
	v_exp_f32_e32 v214, v179
	v_pk_fma_f32 v[186:187], v[182:183], s[4:5], v[176:177] op_sel_hi:[1,0,0]
	v_fmaak_f32 v171, v175, v171, 0x3f35f0e3
	v_fmamk_f32 v179, v215, 0x3f07dc22, v218
	v_pk_fma_f32 v[186:187], v[182:183], v[186:187], s[38:39] op_sel_hi:[1,1,0]
	v_fmaak_f32 v171, v175, v171, 0xbe11a98e
	v_fmaak_f32 v179, v215, v179, 0x3f35f0e3
	v_pk_fma_f32 v[186:187], v[182:183], v[186:187], s[48:49] op_sel_hi:[1,1,0]
	v_fmaak_f32 v171, v175, v171, 0x3e027906
	v_fmaak_f32 v179, v215, v179, 0xbe11a98e
	v_mul_f32_e32 v212, v161, v161
	v_pk_fma_f32 v[224:225], v[182:183], v[186:187], s[62:63] op_sel_hi:[1,1,0]
	v_mul_f32_e32 v186, v175, v171
	v_fmaak_f32 v171, v215, v179, 0x3e027906
	v_pk_fma_f32 v[222:223], v[184:185], s[4:5], v[176:177] op_sel_hi:[1,0,0]
	v_pk_mul_f32 v[224:225], v[182:183], v[224:225]
	v_mul_f32_e32 v182, v215, v171
	v_mul_f32_e32 v171, 0xbf38aa3b, v212
	v_pk_fma_f32 v[176:177], v[210:211], s[4:5], v[176:177] op_sel_hi:[1,0,0]
	v_exp_f32_e32 v215, v171
	v_pk_fma_f32 v[176:177], v[210:211], v[176:177], s[38:39] op_sel_hi:[1,1,0]
	v_cmp_gt_f32_e32 vcc, 0, v161
	v_pk_fma_f32 v[176:177], v[210:211], v[176:177], s[48:49] op_sel_hi:[1,1,0]
	v_pk_fma_f32 v[150:151], v[58:59], v[188:189], v[150:151] op_sel_hi:[1,0,1] neg_lo:[1,0,0] neg_hi:[1,0,0]
	v_pk_fma_f32 v[176:177], v[210:211], v[176:177], s[62:63] op_sel_hi:[1,1,0]
	v_pk_fma_f32 v[150:151], v[188:189], v[150:151], v[46:47] op_sel:[1,0,0]
	v_pk_mul_f32 v[176:177], v[210:211], v[176:177]
	v_fma_f32 v175, |v150|, s1, 1.0
	v_pk_mul_f32 v[176:177], v[214:215], v[176:177]
	v_rcp_f32_e32 v175, v175
	v_pk_mul_f32 v[210:211], v[160:161], v[176:177]
	v_pk_fma_f32 v[176:177], v[160:161], v[176:177], v[160:161] neg_lo:[1,0,0] neg_hi:[1,0,0]
	v_mul_f32_e32 v178, v159, v159
	v_cndmask_b32_e32 v177, v177, v211, vcc
	v_cmp_gt_f32_e32 vcc, 0, v160
	v_xor_b32_e32 v61, 0x80000000, v61
	v_xor_b32_e32 v60, 0x80000000, v60
	v_cndmask_b32_e32 v176, v176, v210, vcc
	v_mul_f32_e32 v160, v176, v176
	v_pk_fma_f32 v[160:161], v[176:177], v[176:177], v[160:161] op_sel_hi:[1,1,0]
	v_mul_f32_e32 v174, 0xbf38aa3b, v178
	v_lshrrev_b32_e32 v160, 10, v208
	v_mul_f32_e32 v207, v155, v155
	v_mul_lo_u32 v160, v160, s3
	s_movk_i32 s4, 0x3ff
	v_pk_fma_f32 v[152:153], v[60:61], v[188:189], v[152:153] op_sel_hi:[1,0,1]
	v_exp_f32_e32 v178, v174
	v_mul_f32_e32 v174, 0xbf38aa3b, v207
	v_and_or_b32 v207, v208, s4, v160
	v_add_u32_e32 v171, 0x80, v208
	v_pk_fma_f32 v[208:209], v[188:189], v[152:153], v[48:49] op_sel:[1,0,0]
	v_fmamk_f32 v152, v175, 0x3f07dc22, v218
	v_fmaak_f32 v152, v175, v152, 0x3f35f0e3
	v_mul_f32_e32 v153, v150, v150
	v_mul_f32_e32 v153, 0xbf38aa3b, v153
	v_fmaak_f32 v152, v175, v152, 0xbe11a98e
	v_exp_f32_e32 v153, v153
	v_fmaak_f32 v152, v175, v152, 0x3e027906
	v_mul_f32_e32 v152, v175, v152
	v_fma_f32 v175, |v151|, s1, 1.0
	v_rcp_f32_e32 v175, v175
	v_mul_f32_e32 v152, v153, v152
	v_mul_f32_e32 v153, v150, v152
	v_fma_f32 v152, -v150, v152, v150
	v_cmp_gt_f32_e32 vcc, 0, v150
	v_pk_fma_f32 v[146:147], v[38:39], v[188:189], v[146:147] op_sel_hi:[1,0,1] neg_lo:[1,0,0] neg_hi:[1,0,0]
	v_xor_b32_e32 v41, 0x80000000, v41
	v_cndmask_b32_e32 v150, v152, v153, vcc
	v_fmamk_f32 v152, v175, 0x3f07dc22, v218
	v_fmaak_f32 v152, v175, v152, 0x3f35f0e3
	v_mul_f32_e32 v153, v151, v151
	v_fmaak_f32 v152, v175, v152, 0xbe11a98e
	v_mul_f32_e32 v153, 0xbf38aa3b, v153
	v_fmaak_f32 v152, v175, v152, 0x3e027906
	v_exp_f32_e32 v153, v153
	v_mul_f32_e32 v152, v175, v152
	v_fma_f32 v175, |v208|, s1, 1.0
	v_rcp_f32_e32 v175, v175
	v_mul_f32_e32 v152, v153, v152
	v_mul_f32_e32 v153, v151, v152
	v_fma_f32 v152, -v151, v152, v151
	v_cmp_gt_f32_e32 vcc, 0, v151
	v_fmamk_f32 v151, v175, 0x3f07dc22, v218
	v_fmaak_f32 v151, v175, v151, 0x3f35f0e3
	v_cndmask_b32_e32 v152, v152, v153, vcc
	v_mul_f32_e32 v153, v208, v208
	v_mul_f32_e32 v153, 0xbf38aa3b, v153
	v_fmaak_f32 v151, v175, v151, 0xbe11a98e
	v_exp_f32_e32 v153, v153
	v_fmaak_f32 v151, v175, v151, 0x3e027906
	v_mul_f32_e32 v151, v175, v151
	v_fma_f32 v175, |v209|, s1, 1.0
	v_rcp_f32_e32 v175, v175
	v_mul_f32_e32 v151, v153, v151
	v_mul_f32_e32 v153, v208, v151
	v_fma_f32 v151, -v208, v151, v208
	v_cmp_gt_f32_e32 vcc, 0, v208
	v_pk_fma_f32 v[146:147], v[188:189], v[146:147], v[34:35] op_sel:[1,0,0]
	v_xor_b32_e32 v40, 0x80000000, v40
	v_cndmask_b32_e32 v208, v151, v153, vcc
	v_fmamk_f32 v151, v175, 0x3f07dc22, v218
	v_fmaak_f32 v151, v175, v151, 0x3f35f0e3
	v_fmaak_f32 v151, v175, v151, 0xbe11a98e
	v_fmaak_f32 v151, v175, v151, 0x3e027906
	v_mul_f32_e32 v151, v175, v151
	v_fma_f32 v175, |v146|, s1, 1.0
	v_rcp_f32_e32 v175, v175
	v_mul_f32_e32 v183, v146, v146
	v_mul_f32_e32 v153, v209, v209
	v_mul_f32_e32 v183, 0xbf38aa3b, v183
	v_fmamk_f32 v179, v175, 0x3f07dc22, v218
	v_mul_f32_e32 v153, 0xbf38aa3b, v153
	v_fmaak_f32 v179, v175, v179, 0x3f35f0e3
	v_exp_f32_e32 v183, v183
	v_exp_f32_e32 v153, v153
	v_fmaak_f32 v179, v175, v179, 0xbe11a98e
	v_fmaak_f32 v179, v175, v179, 0x3e027906
	v_mul_f32_e32 v175, v175, v179
	v_mul_f32_e32 v175, v183, v175
	v_fma_f32 v183, |v147|, s1, 1.0
	v_mul_f32_e32 v151, v153, v151
	v_rcp_f32_e32 v183, v183
	v_mul_f32_e32 v153, v209, v151
	v_fma_f32 v151, -v209, v151, v209
	v_cmp_gt_f32_e32 vcc, 0, v209
	v_mul_f32_e32 v179, v146, v175
	v_fma_f32 v175, -v146, v175, v146
	v_cndmask_b32_e32 v210, v151, v153, vcc
	v_cmp_gt_f32_e32 vcc, 0, v146
	v_pk_fma_f32 v[148:149], v[40:41], v[188:189], v[148:149] op_sel_hi:[1,0,1]
	v_fmamk_f32 v146, v183, 0x3f07dc22, v218
	v_cndmask_b32_e32 v214, v175, v179, vcc
	v_mul_f32_e32 v175, v147, v147
	v_mul_f32_e32 v175, 0xbf38aa3b, v175
	v_pk_fma_f32 v[148:149], v[188:189], v[148:149], v[36:37] op_sel:[1,0,0]
	v_fmaak_f32 v146, v183, v146, 0x3f35f0e3
	v_exp_f32_e32 v175, v175
	v_fmaak_f32 v146, v183, v146, 0xbe11a98e
	v_fma_f32 v179, |v148|, s1, 1.0
	v_fmaak_f32 v146, v183, v146, 0x3e027906
	v_rcp_f32_e32 v179, v179
	v_pk_fma_f32 v[222:223], v[184:185], v[222:223], s[38:39] op_sel_hi:[1,1,0]
	v_mul_f32_e32 v146, v183, v146
	v_pk_fma_f32 v[222:223], v[184:185], v[222:223], s[48:49] op_sel_hi:[1,1,0]
	v_mul_f32_e32 v146, v175, v146
	v_pk_fma_f32 v[222:223], v[184:185], v[222:223], s[62:63] op_sel_hi:[1,1,0]
	v_mul_f32_e32 v175, v147, v146
	v_fma_f32 v146, -v147, v146, v147
	v_cmp_gt_f32_e32 vcc, 0, v147
	v_mul_f32_e32 v147, v148, v148
	v_pk_mul_f32 v[184:185], v[184:185], v[222:223]
	v_cndmask_b32_e32 v222, v146, v175, vcc
	v_fmamk_f32 v146, v179, 0x3f07dc22, v218
	v_mul_f32_e32 v147, 0xbf38aa3b, v147
	v_fmaak_f32 v146, v179, v146, 0x3f35f0e3
	v_exp_f32_e32 v147, v147
	v_fmaak_f32 v146, v179, v146, 0xbe11a98e
	v_fmaak_f32 v146, v179, v146, 0x3e027906
	v_fma_f32 v175, |v149|, s1, 1.0
	v_mul_f32_e32 v146, v179, v146
	v_rcp_f32_e32 v175, v175
	v_mul_f32_e32 v146, v147, v146
	v_mul_f32_e32 v147, v148, v146
	v_fma_f32 v146, -v148, v146, v148
	v_cmp_gt_f32_e32 vcc, 0, v148
	v_exp_f32_e32 v173, v173
	v_exp_f32_e32 v174, v174
	v_cndmask_b32_e32 v226, v146, v147, vcc
	v_mul_f32_e32 v147, v149, v149
	v_fmamk_f32 v146, v175, 0x3f07dc22, v218
	v_mul_f32_e32 v147, 0xbf38aa3b, v147
	v_fmaak_f32 v146, v175, v146, 0x3f35f0e3
	v_exp_f32_e32 v147, v147
	v_fmaak_f32 v146, v175, v146, 0xbe11a98e
	v_fmaak_f32 v146, v175, v146, 0x3e027906
	v_mul_f32_e32 v146, v175, v146
	v_mul_f32_e32 v146, v147, v146
	v_mul_f32_e32 v147, v149, v146
	v_fma_f32 v146, -v149, v146, v149
	v_cmp_gt_f32_e32 vcc, 0, v149
	v_mov_b32_e32 v179, v181
	v_mov_b32_e32 v187, v225
	v_cndmask_b32_e32 v228, v146, v147, vcc
	v_lshrrev_b32_e32 v146, 10, v171
	v_mul_lo_u32 v146, v146, s3
	v_and_or_b32 v188, v171, s4, v146
	v_pk_mul_f32 v[146:147], v[180:181], v[224:225]
	v_pk_mul_f32 v[148:149], v[178:179], v[186:187]
	v_mov_b32_e32 v178, v158
	v_mov_b32_e32 v179, v156
	v_pk_mov_b32 v[186:187], v[158:159], v[156:157] op_sel:[1,0]
	v_pk_mul_f32 v[180:181], v[178:179], v[146:147]
	v_pk_mul_f32 v[224:225], v[186:187], v[148:149]
	v_pk_fma_f32 v[146:147], v[178:179], v[146:147], v[178:179] neg_lo:[1,0,0] neg_hi:[1,0,0]
	v_pk_fma_f32 v[148:149], v[186:187], v[148:149], v[186:187] neg_lo:[1,0,0] neg_hi:[1,0,0]
	v_cmp_gt_f32_e32 vcc, 0, v156
	v_cmp_gt_f32_e64 s[4:5], 0, v158
	v_mov_b32_e32 v175, v173
	v_cndmask_b32_e32 v179, v147, v181, vcc
	v_cndmask_b32_e32 v181, v149, v225, vcc
	v_cmp_gt_f32_e32 vcc, 0, v159
	v_mov_b32_e32 v183, v185
	v_cndmask_b32_e64 v178, v146, v180, s[4:5]
	v_cndmask_b32_e32 v180, v148, v224, vcc
	v_pk_mul_f32 v[148:149], v[172:173], v[184:185]
	v_pk_mul_f32 v[158:159], v[174:175], v[182:183]
	v_mov_b32_e32 v156, v154
	v_mov_b32_e32 v174, v155
	v_mov_b32_e32 v175, v157
	v_pk_mul_f32 v[172:173], v[156:157], v[148:149]
	v_pk_mul_f32 v[182:183], v[174:175], v[158:159]
	v_pk_fma_f32 v[148:149], v[156:157], v[148:149], v[156:157] neg_lo:[1,0,0] neg_hi:[1,0,0]
	v_pk_fma_f32 v[158:159], v[174:175], v[158:159], v[174:175] neg_lo:[1,0,0] neg_hi:[1,0,0]
	v_cmp_gt_f32_e32 vcc, 0, v157
	v_cmp_gt_f32_e64 s[4:5], 0, v154
	v_add_lshl_u32 v160, v1, v207, 1
	v_cndmask_b32_e32 v157, v149, v173, vcc
	v_cndmask_b32_e64 v156, v148, v172, s[4:5]
	v_cndmask_b32_e32 v159, v159, v183, vcc
	v_cmp_gt_f32_e32 vcc, 0, v155
	v_pk_mul_f32 v[174:175], v[156:157], v[156:157]
	v_mul_f32_e32 v151, v150, v150
	v_cndmask_b32_e32 v158, v158, v182, vcc
	v_mul_f32_e32 v153, v152, v152
	v_mul_f32_e32 v209, v208, v208
	v_mul_f32_e32 v211, v210, v210
	v_mul_f32_e32 v215, v214, v214
	v_mul_f32_e32 v223, v222, v222
	v_mul_f32_e32 v227, v226, v226
	v_mul_f32_e32 v229, v228, v228
	v_add_lshl_u32 v171, v1, v188, 1
	v_cvt_pk_bf16_f32 v146, v178, v180
	v_cvt_pk_bf16_f32 v147, v156, v158
	v_pk_mul_f32 v[154:155], v[178:179], v[178:179]
	v_pk_mul_f32 v[172:173], v[180:181], v[180:181]
	v_pk_mul_f32 v[182:183], v[158:159], v[158:159]
	v_pk_mov_b32 v[154:155], v[178:179], v[154:155] op_sel:[1,0]
	v_pk_mov_b32 v[172:173], v[156:157], v[172:173] op_sel:[1,0]
	v_cvt_pk_bf16_f32 v148, v179, v157
	v_mov_b32_e32 v1, v161
	v_pk_add_f32 v[154:155], v[154:155], v[172:173]
	v_mov_b32_e32 v172, v176
	v_mov_b32_e32 v173, v174
	v_pk_mov_b32 v[174:175], v[176:177], v[182:183] op_sel:[1,0]
	v_cvt_pk_bf16_f32 v149, v176, v177
	buffer_store_dwordx4 v[146:149], v160, s[28:31], 0 offen sc1
	v_pk_add_f32 v[172:173], v[172:173], v[174:175]
	v_pk_mul_f32 v[174:175], v[178:179], v[180:181]
	v_pk_add_f32 v[154:155], v[154:155], v[172:173]
	v_pk_add_f32 v[172:173], v[178:179], v[180:181]
	s_nop 0
	v_mov_b32_e32 v173, v175
	v_pk_add_f32 v[174:175], v[156:157], v[158:159]
	v_pk_mul_f32 v[156:157], v[156:157], v[158:159]
	s_nop 0
	v_mov_b32_e32 v175, v157
	v_pk_add_f32 v[156:157], v[172:173], v[174:175]
	s_nop 0
	v_pk_add_f32 v[156:157], v[156:157], v[0:1]
	s_nop 0
	v_pk_add_f32 v[154:155], v[154:155], v[156:157]
	v_cvt_pk_bf16_f32 v146, v150, v152
	v_pk_add_f32 v[148:149], v[150:151], v[152:153]
	v_pk_add_f32 v[150:151], v[208:209], v[210:211]
	v_cvt_pk_bf16_f32 v147, v208, v210
	s_nop 0
	v_pk_add_f32 v[148:149], v[148:149], v[150:151]
	s_nop 0
	v_pk_add_f32 v[150:151], v[148:149], v[154:155]
	v_pk_add_f32 v[152:153], v[214:215], v[222:223]
	v_pk_add_f32 v[154:155], v[226:227], v[228:229]
	v_cvt_pk_bf16_f32 v148, v214, v222
	v_cvt_pk_bf16_f32 v149, v226, v228
	buffer_store_dwordx4 v[146:149], v171, s[28:31], 0 offen sc1
	v_pk_add_f32 v[152:153], v[152:153], v[154:155]
	s_nop 0
	v_pk_add_f32 v[150:151], v[152:153], v[150:151]
	v_and_b32_e32 v146, 64, v216
	v_xor_b32_e32 v1, 16, v216
	v_add_u32_e32 v148, 64, v146
	v_cmp_lt_i32_e32 vcc, v1, v148
	s_nop 1
	v_cndmask_b32_e32 v1, v216, v1, vcc
	v_lshlrev_b32_e32 v174, 2, v1
	ds_bpermute_b32 v146, v174, v150
	ds_bpermute_b32 v147, v174, v151
	v_xor_b32_e32 v1, 32, v216
	v_cmp_lt_i32_e32 vcc, v1, v148
	s_waitcnt lgkmcnt(0)
	v_pk_add_f32 v[146:147], v[150:151], v[146:147]
	v_cndmask_b32_e32 v1, v216, v1, vcc
	v_lshlrev_b32_e32 v175, 2, v1
	ds_bpermute_b32 v148, v175, v146
	ds_bpermute_b32 v149, v175, v147
	s_and_saveexec_b64 s[4:5], s[46:47]
	s_cbranch_execz .LBB0_215
	v_ashrrev_i32_e32 v171, 31, v170
	v_lshlrev_b64 v[150:151], 7, v[170:171]
	v_lshl_add_u64 v[150:151], s[12:13], 0, v[150:151]
	s_lshl_b32 s38, s36, 3
	v_lshl_add_u64 v[150:151], v[150:151], 0, s[38:39]
	s_lshl_b32 s38, s57, 3
	v_lshl_add_u64 v[150:151], v[150:151], 0, s[38:39]
	s_waitcnt lgkmcnt(0)
	v_pk_add_f32 v[146:147], v[146:147], v[148:149]
	flat_store_dwordx2 v[150:151], v[146:147]

.LBB0_395:
	s_add_i32 s66, s66, 1
	s_mov_b64 s[36:37], s[20:21]
	s_mul_i32 s20, s66, s26
	s_add_i32 s42, s20, s2
	s_cmpk_gt_i32 s42, 0x3ff
	s_cselect_b64 s[52:53], -1, 0
	s_lshl_b32 s20, s42, 3
	s_and_b32 s20, s20, 56
	s_bfe_u32 s21, s42, 0x30003
	s_mov_b32 s3, s67
	s_or_b32 s67, s20, s21
	s_mov_b32 s27, s50
	s_ashr_i32 s50, s42, 6
	s_lshl_b32 s20, s67, 19
	s_mov_b64 s[4:5], s[48:49]
	s_add_u32 s48, s18, s20
	s_addc_u32 s49, s19, 0
	s_ashr_i32 s51, s50, 31
	s_lshl_b64 s[20:21], s[50:51], 19
	s_add_u32 s20, s16, s20
	s_addc_u32 s21, s17, s21
	s_cmpk_lt_i32 s42, 0x400
	s_cselect_b32 s46, s49, s5
	s_cselect_b32 s47, s48, s4
	s_cselect_b32 s51, s21, s37
	s_cselect_b32 s54, s20, s36
	s_add_u32 s55, s36, 0x100
	s_addc_u32 s56, s37, 0
	s_mov_b32 s57, -2
	s_add_u32 s36, s4, 0x100
	s_addc_u32 s37, s5, 0
	s_add_i32 s68, 0, 0x10000
	v_add_u32_e32 v30, s68, v204
	ds_read_b128 v[14:17], v30
	ds_read_b128 v[22:25], v30 offset:1024
	ds_read_b128 v[26:29], v30 offset:2048
	ds_read_b128 v[30:33], v30 offset:3072
	s_cmp_eq_u32 s57, 12
	s_cselect_b32 s45, s46, s37
	s_cselect_b32 s44, s47, s36
	s_cselect_b32 s43, s51, s56
	s_cselect_b32 s42, s54, s55
	v_lshl_add_u64 v[178:179], s[4:5], 0, v[188:189]
	s_add_i32 m0, s60, 0xc000
	ds_read_b128 v[38:41], v209
	ds_read_b128 v[42:45], v209 offset:1024
	ds_read_b128 v[46:49], v209 offset:2048
	ds_read_b128 v[54:57], v209 offset:3072
	ds_read_b128 v[58:61], v209 offset:4096
	ds_read_b128 v[62:65], v209 offset:5120
	ds_read_b128 v[66:69], v209 offset:6144
	ds_read_b128 v[70:73], v209 offset:7168
	s_cmp_lg_u32 s66, 1
	s_cbranch_scc1 .Lpk0_d0
	global_load_lds_dwordx4 v[178:179], off
.Lpk0_d0:
	v_lshl_add_u64 v[178:179], s[4:5], 0, v[186:187]
	s_add_i32 m0, s60, 0xe000
	s_nop 0
	s_cmp_lg_u32 s66, 1
	s_cbranch_scc1 .Lpk0_d1
	global_load_lds_dwordx4 v[178:179], off
.Lpk0_d1:
	s_waitcnt lgkmcnt(8)
	s_barrier
	s_waitcnt lgkmcnt(0)
	s_setprio 1
	s_waitcnt lgkmcnt(0)
	v_mfma_f32_16x16x32_bf16 v[174:177], v[14:17], v[38:41], 0
	v_mfma_f32_16x16x32_bf16 v[170:173], v[26:29], v[38:41], 0
	v_mfma_f32_16x16x32_bf16 v[158:161], v[14:17], v[46:49], 0
	v_mfma_f32_16x16x32_bf16 v[154:157], v[26:29], v[46:49], 0
	v_mfma_f32_16x16x32_bf16 v[142:145], v[14:17], v[58:61], 0
	v_mfma_f32_16x16x32_bf16 v[138:141], v[26:29], v[58:61], 0
	v_mfma_f32_16x16x32_bf16 v[126:129], v[14:17], v[66:69], 0
	v_mfma_f32_16x16x32_bf16 v[122:125], v[26:29], v[66:69], 0
	v_mfma_f32_16x16x32_bf16 v[174:177], v[22:25], v[42:45], v[174:177]
	v_mfma_f32_16x16x32_bf16 v[170:173], v[30:33], v[42:45], v[170:173]
	v_mfma_f32_16x16x32_bf16 v[158:161], v[22:25], v[54:57], v[158:161]
	v_mfma_f32_16x16x32_bf16 v[154:157], v[30:33], v[54:57], v[154:157]
	v_mfma_f32_16x16x32_bf16 v[142:145], v[22:25], v[62:65], v[142:145]
	v_mfma_f32_16x16x32_bf16 v[138:141], v[30:33], v[62:65], v[138:141]
	v_mfma_f32_16x16x32_bf16 v[126:129], v[22:25], v[70:73], v[126:129]
	v_mfma_f32_16x16x32_bf16 v[122:125], v[30:33], v[70:73], v[122:125]
	s_setprio 0
	s_barrier
	s_add_i32 s69, 0, 0x14000
	v_add_u32_e32 v210, s69, v204
	s_add_i32 s4, s68, s59
	ds_read_b128 v[178:181], v210
	ds_read_b128 v[190:193], v210 offset:1024
	ds_read_b128 v[200:203], v210 offset:2048
	ds_read_b128 v[222:225], v210 offset:3072
	v_lshl_add_u64 v[210:211], s[42:43], 0, v[184:185]
	s_mov_b32 m0, s4
	v_lshl_add_u64 v[214:215], s[42:43], 0, v[182:183]
	global_load_lds_dwordx4 v[210:211], off
	s_add_i32 m0, s4, 0x2000
	s_nop 0
	global_load_lds_dwordx4 v[214:215], off
	s_barrier
	s_waitcnt lgkmcnt(0)
	s_setprio 1
	s_waitcnt lgkmcnt(0)
	v_mfma_f32_16x16x32_bf16 v[166:169], v[178:181], v[38:41], 0
	v_mfma_f32_16x16x32_bf16 v[38:41], v[200:203], v[38:41], 0
	v_mfma_f32_16x16x32_bf16 v[166:169], v[190:193], v[42:45], v[166:169]
	v_mfma_f32_16x16x32_bf16 v[38:41], v[222:225], v[42:45], v[38:41]
	v_mfma_f32_16x16x32_bf16 v[42:45], v[178:181], v[46:49], 0
	v_mfma_f32_16x16x32_bf16 v[46:49], v[200:203], v[46:49], 0
	v_mfma_f32_16x16x32_bf16 v[42:45], v[190:193], v[54:57], v[42:45]
	v_mfma_f32_16x16x32_bf16 v[46:49], v[222:225], v[54:57], v[46:49]
	v_mfma_f32_16x16x32_bf16 v[54:57], v[178:181], v[58:61], 0
	v_mfma_f32_16x16x32_bf16 v[58:61], v[200:203], v[58:61], 0
	v_mfma_f32_16x16x32_bf16 v[54:57], v[190:193], v[62:65], v[54:57]
	v_mfma_f32_16x16x32_bf16 v[58:61], v[222:225], v[62:65], v[58:61]
	v_mfma_f32_16x16x32_bf16 v[62:65], v[178:181], v[66:69], 0
	v_mfma_f32_16x16x32_bf16 v[66:69], v[200:203], v[66:69], 0
	v_mfma_f32_16x16x32_bf16 v[62:65], v[190:193], v[70:73], v[62:65]
	v_mfma_f32_16x16x32_bf16 v[66:69], v[222:225], v[70:73], v[66:69]
	s_setprio 0
	s_mov_b32 m0, s60
	v_lshl_add_u64 v[242:243], s[44:45], 0, v[184:185]
	s_barrier
	ds_read_b128 v[70:73], v209 offset:16384
	ds_read_b128 v[114:117], v209 offset:17408
	ds_read_b128 v[118:121], v209 offset:18432
	ds_read_b128 v[130:133], v209 offset:19456
	ds_read_b128 v[134:137], v209 offset:20480
	ds_read_b128 v[146:149], v209 offset:21504
	ds_read_b128 v[150:153], v209 offset:22528
	ds_read_b128 v[162:165], v209 offset:23552
	global_load_lds_dwordx4 v[242:243], off
	v_lshl_add_u64 v[244:245], s[44:45], 0, v[182:183]
	s_mov_b32 m0, s61
	s_nop 0
	global_load_lds_dwordx4 v[244:245], off
	s_barrier
	s_waitcnt lgkmcnt(0)
	s_setprio 1
	s_waitcnt lgkmcnt(0)
	v_mfma_f32_16x16x32_bf16 v[110:113], v[14:17], v[70:73], 0
	v_mfma_f32_16x16x32_bf16 v[106:109], v[26:29], v[70:73], 0
	v_mfma_f32_16x16x32_bf16 v[94:97], v[14:17], v[118:121], 0
	v_mfma_f32_16x16x32_bf16 v[90:93], v[26:29], v[118:121], 0
	v_mfma_f32_16x16x32_bf16 v[78:81], v[14:17], v[134:137], 0
	v_mfma_f32_16x16x32_bf16 v[74:77], v[26:29], v[134:137], 0
	v_mfma_f32_16x16x32_bf16 v[10:13], v[26:29], v[150:153], 0
	v_mfma_f32_16x16x32_bf16 v[110:113], v[22:25], v[114:117], v[110:113]
	v_mfma_f32_16x16x32_bf16 v[106:109], v[30:33], v[114:117], v[106:109]
	v_mfma_f32_16x16x32_bf16 v[94:97], v[22:25], v[130:133], v[94:97]
	v_mfma_f32_16x16x32_bf16 v[90:93], v[30:33], v[130:133], v[90:93]
	v_mfma_f32_16x16x32_bf16 v[78:81], v[22:25], v[146:149], v[78:81]
	v_mfma_f32_16x16x32_bf16 v[74:77], v[30:33], v[146:149], v[74:77]
	v_mfma_f32_16x16x32_bf16 v[14:17], v[14:17], v[150:153], 0
	v_mfma_f32_16x16x32_bf16 v[10:13], v[30:33], v[162:165], v[10:13]
	v_mfma_f32_16x16x32_bf16 v[14:17], v[22:25], v[162:165], v[14:17]
	s_setprio 0
	s_barrier
	s_add_u32 s4, s42, 0x40000
	s_addc_u32 s5, s43, 0
	s_add_i32 s68, s69, s59
	v_lshl_add_u64 v[18:19], s[4:5], 0, v[184:185]
	s_mov_b32 m0, s68
	s_nop 0
	global_load_lds_dwordx4 v[18:19], off
	v_lshl_add_u64 v[18:19], s[4:5], 0, v[182:183]
	s_add_i32 m0, s68, 0x2000
	s_nop 0
	global_load_lds_dwordx4 v[18:19], off
	s_cmp_lg_u32 s66, 1
	s_cbranch_scc1 .Lpk0_w
	s_waitcnt vmcnt(6)
.Lpk0_w:
	s_barrier
	s_setprio 1
	v_mfma_f32_16x16x32_bf16 v[18:21], v[178:181], v[70:73], 0
	v_mfma_f32_16x16x32_bf16 v[22:25], v[190:193], v[114:117], v[18:21]
	v_mfma_f32_16x16x32_bf16 v[18:21], v[200:203], v[70:73], 0
	v_mfma_f32_16x16x32_bf16 v[26:29], v[222:225], v[114:117], v[18:21]
	v_mfma_f32_16x16x32_bf16 v[18:21], v[178:181], v[118:121], 0
	v_mfma_f32_16x16x32_bf16 v[30:33], v[190:193], v[130:133], v[18:21]
	v_mfma_f32_16x16x32_bf16 v[18:21], v[200:203], v[118:121], 0
	v_mfma_f32_16x16x32_bf16 v[70:73], v[222:225], v[130:133], v[18:21]
	v_mfma_f32_16x16x32_bf16 v[18:21], v[178:181], v[134:137], 0
	v_mfma_f32_16x16x32_bf16 v[50:53], v[190:193], v[146:149], v[18:21]
	v_mfma_f32_16x16x32_bf16 v[18:21], v[200:203], v[134:137], 0
	v_mfma_f32_16x16x32_bf16 v[6:9], v[178:181], v[150:153], 0
	v_mfma_f32_16x16x32_bf16 v[2:5], v[200:203], v[150:153], 0
	v_mfma_f32_16x16x32_bf16 v[34:37], v[222:225], v[146:149], v[18:21]
	v_mfma_f32_16x16x32_bf16 v[6:9], v[190:193], v[162:165], v[6:9]
	v_mfma_f32_16x16x32_bf16 v[2:5], v[222:225], v[162:165], v[2:5]
	s_setprio 0
	s_add_i32 s68, 0, 0x18000
	v_add_u32_e32 v98, s68, v204
	s_barrier
	ds_read_b128 v[18:21], v98
	ds_read_b128 v[82:85], v98 offset:1024
	ds_read_b128 v[86:89], v98 offset:2048
	ds_read_b128 v[98:101], v98 offset:3072
	s_add_u32 s4, s44, 0x40000
	s_addc_u32 s5, s45, 0
	s_mov_b32 m0, s62
	v_lshl_add_u64 v[134:135], s[4:5], 0, v[184:185]
	ds_read_b128 v[102:105], v209 offset:32768
	ds_read_b128 v[114:117], v209 offset:33792
	ds_read_b128 v[118:121], v209 offset:34816
	ds_read_b128 v[130:133], v209 offset:35840
	ds_read_b128 v[178:181], v209 offset:36864
	ds_read_b128 v[190:193], v209 offset:37888
	ds_read_b128 v[200:203], v209 offset:38912
	ds_read_b128 v[222:225], v209 offset:39936
	global_load_lds_dwordx4 v[134:135], off
	v_lshl_add_u64 v[134:135], s[4:5], 0, v[182:183]
	s_mov_b32 m0, s63
	s_nop 0
	global_load_lds_dwordx4 v[134:135], off
	s_waitcnt lgkmcnt(8)
	s_barrier
	s_waitcnt lgkmcnt(0)
	s_setprio 1
	s_waitcnt lgkmcnt(0)
	v_mfma_f32_16x16x32_bf16 v[134:137], v[18:21], v[102:105], v[174:177]
	v_mfma_f32_16x16x32_bf16 v[174:177], v[82:85], v[114:117], v[134:137]
	v_mfma_f32_16x16x32_bf16 v[134:137], v[86:89], v[102:105], v[170:173]
	v_mfma_f32_16x16x32_bf16 v[170:173], v[98:101], v[114:117], v[134:137]
	v_mfma_f32_16x16x32_bf16 v[134:137], v[18:21], v[118:121], v[158:161]
	v_mfma_f32_16x16x32_bf16 v[158:161], v[82:85], v[130:133], v[134:137]
	v_mfma_f32_16x16x32_bf16 v[134:137], v[86:89], v[118:121], v[154:157]
	v_mfma_f32_16x16x32_bf16 v[154:157], v[98:101], v[130:133], v[134:137]
	v_mfma_f32_16x16x32_bf16 v[134:137], v[18:21], v[178:181], v[142:145]
	v_mfma_f32_16x16x32_bf16 v[142:145], v[82:85], v[190:193], v[134:137]
	v_mfma_f32_16x16x32_bf16 v[134:137], v[86:89], v[178:181], v[138:141]
	v_mfma_f32_16x16x32_bf16 v[126:129], v[18:21], v[200:203], v[126:129]
	v_mfma_f32_16x16x32_bf16 v[122:125], v[86:89], v[200:203], v[122:125]
	v_mfma_f32_16x16x32_bf16 v[138:141], v[98:101], v[190:193], v[134:137]
	v_mfma_f32_16x16x32_bf16 v[126:129], v[82:85], v[222:225], v[126:129]
	v_mfma_f32_16x16x32_bf16 v[122:125], v[98:101], v[222:225], v[122:125]
	s_setprio 0
	s_barrier
	s_add_i32 s44, 0, 0x1c000
	v_add_u32_e32 v134, s44, v204
	s_add_i32 s4, s68, s59
	ds_read_b128 v[226:229], v134
	ds_read_b128 v[230:233], v134 offset:1024
	ds_read_b128 v[234:237], v134 offset:2048
	ds_read_b128 v[238:241], v134 offset:3072
	v_lshl_add_u64 v[134:135], v[210:211], 0, s[22:23]
	s_mov_b32 m0, s4
	s_nop 0
	global_load_lds_dwordx4 v[134:135], off
	v_lshl_add_u64 v[134:135], v[214:215], 0, s[22:23]
	s_add_i32 m0, s4, 0x2000
	s_nop 0
	global_load_lds_dwordx4 v[134:135], off
	s_barrier
	s_waitcnt lgkmcnt(0)
	s_setprio 1
	s_waitcnt lgkmcnt(0)
	v_mfma_f32_16x16x32_bf16 v[38:41], v[234:237], v[102:105], v[38:41]
	v_mfma_f32_16x16x32_bf16 v[162:165], v[238:241], v[114:117], v[38:41]
	v_mfma_f32_16x16x32_bf16 v[38:41], v[226:229], v[118:121], v[42:45]
	v_mfma_f32_16x16x32_bf16 v[150:153], v[230:233], v[130:133], v[38:41]
	v_mfma_f32_16x16x32_bf16 v[38:41], v[234:237], v[118:121], v[46:49]
	v_mfma_f32_16x16x32_bf16 v[134:137], v[226:229], v[102:105], v[166:169]
	v_mfma_f32_16x16x32_bf16 v[146:149], v[238:241], v[130:133], v[38:41]
	v_mfma_f32_16x16x32_bf16 v[38:41], v[226:229], v[178:181], v[54:57]
	v_mfma_f32_16x16x32_bf16 v[166:169], v[230:233], v[114:117], v[134:137]
	v_mfma_f32_16x16x32_bf16 v[134:137], v[230:233], v[190:193], v[38:41]
	v_mfma_f32_16x16x32_bf16 v[38:41], v[234:237], v[178:181], v[58:61]
	v_mfma_f32_16x16x32_bf16 v[130:133], v[238:241], v[190:193], v[38:41]
	v_mfma_f32_16x16x32_bf16 v[38:41], v[226:229], v[200:203], v[62:65]
	v_mfma_f32_16x16x32_bf16 v[118:121], v[230:233], v[222:225], v[38:41]
	v_mfma_f32_16x16x32_bf16 v[38:41], v[234:237], v[200:203], v[66:69]
	v_mfma_f32_16x16x32_bf16 v[114:117], v[238:241], v[222:225], v[38:41]
	s_setprio 0
	s_mov_b32 m0, s64
	v_lshl_add_u64 v[102:103], v[242:243], 0, s[22:23]
	s_barrier
	s_nop 2
	ds_read_b128 v[38:41], v209 offset:49152
	ds_read_b128 v[42:45], v209 offset:50176
	ds_read_b128 v[46:49], v209 offset:51200
	ds_read_b128 v[54:57], v209 offset:52224
	ds_read_b128 v[58:61], v209 offset:53248
	ds_read_b128 v[62:65], v209 offset:54272
	ds_read_b128 v[66:69], v209 offset:55296
	ds_read_b128 v[178:181], v209 offset:56320
	global_load_lds_dwordx4 v[102:103], off
	v_lshl_add_u64 v[102:103], v[244:245], 0, s[22:23]
	s_mov_b32 m0, s65
	s_nop 0
	global_load_lds_dwordx4 v[102:103], off
	s_barrier
	s_waitcnt lgkmcnt(0)
	s_setprio 1
	s_waitcnt lgkmcnt(0)
	v_mfma_f32_16x16x32_bf16 v[102:105], v[18:21], v[38:41], v[110:113]
	v_mfma_f32_16x16x32_bf16 v[110:113], v[82:85], v[42:45], v[102:105]
	v_mfma_f32_16x16x32_bf16 v[102:105], v[86:89], v[38:41], v[106:109]
	v_mfma_f32_16x16x32_bf16 v[94:97], v[18:21], v[46:49], v[94:97]
	v_mfma_f32_16x16x32_bf16 v[90:93], v[86:89], v[46:49], v[90:93]
	v_mfma_f32_16x16x32_bf16 v[78:81], v[18:21], v[58:61], v[78:81]
	v_mfma_f32_16x16x32_bf16 v[74:77], v[86:89], v[58:61], v[74:77]
	v_mfma_f32_16x16x32_bf16 v[14:17], v[18:21], v[66:69], v[14:17]
	v_mfma_f32_16x16x32_bf16 v[10:13], v[86:89], v[66:69], v[10:13]
	v_mfma_f32_16x16x32_bf16 v[106:109], v[98:101], v[42:45], v[102:105]
	v_mfma_f32_16x16x32_bf16 v[94:97], v[82:85], v[54:57], v[94:97]
	v_mfma_f32_16x16x32_bf16 v[90:93], v[98:101], v[54:57], v[90:93]
	v_mfma_f32_16x16x32_bf16 v[78:81], v[82:85], v[62:65], v[78:81]
	v_mfma_f32_16x16x32_bf16 v[74:77], v[98:101], v[62:65], v[74:77]
	v_mfma_f32_16x16x32_bf16 v[18:21], v[82:85], v[178:181], v[14:17]
	v_mfma_f32_16x16x32_bf16 v[10:13], v[98:101], v[178:181], v[10:13]
	s_setprio 0
	s_barrier
	s_add_u32 s4, s42, 0x40080
	s_addc_u32 s5, s43, 0
	s_add_i32 s42, s44, s59
	v_lshl_add_u64 v[14:15], s[4:5], 0, v[184:185]
	s_mov_b32 m0, s42
	s_nop 0
	global_load_lds_dwordx4 v[14:15], off
	v_lshl_add_u64 v[14:15], s[4:5], 0, v[182:183]
	s_add_i32 m0, s42, 0x2000
	s_nop 0
	global_load_lds_dwordx4 v[14:15], off
	s_waitcnt vmcnt(6)
	s_barrier
	s_setprio 1
	v_mfma_f32_16x16x32_bf16 v[14:17], v[226:229], v[38:41], v[22:25]
	v_mfma_f32_16x16x32_bf16 v[102:105], v[230:233], v[42:45], v[14:17]
	v_mfma_f32_16x16x32_bf16 v[14:17], v[234:237], v[38:41], v[26:29]
	v_mfma_f32_16x16x32_bf16 v[98:101], v[238:241], v[42:45], v[14:17]
	v_mfma_f32_16x16x32_bf16 v[14:17], v[226:229], v[46:49], v[30:33]
	v_mfma_f32_16x16x32_bf16 v[86:89], v[230:233], v[54:57], v[14:17]
	v_mfma_f32_16x16x32_bf16 v[14:17], v[234:237], v[46:49], v[70:73]
	v_mfma_f32_16x16x32_bf16 v[82:85], v[238:241], v[54:57], v[14:17]
	v_mfma_f32_16x16x32_bf16 v[14:17], v[226:229], v[58:61], v[50:53]
	v_mfma_f32_16x16x32_bf16 v[50:53], v[230:233], v[62:65], v[14:17]
	v_mfma_f32_16x16x32_bf16 v[14:17], v[234:237], v[58:61], v[34:37]
	v_mfma_f32_16x16x32_bf16 v[6:9], v[226:229], v[66:69], v[6:9]
	v_mfma_f32_16x16x32_bf16 v[2:5], v[234:237], v[66:69], v[2:5]
	v_mfma_f32_16x16x32_bf16 v[34:37], v[238:241], v[62:65], v[14:17]
	v_mfma_f32_16x16x32_bf16 v[6:9], v[230:233], v[178:181], v[6:9]
	v_mfma_f32_16x16x32_bf16 v[2:5], v[238:241], v[178:181], v[2:5]
	s_setprio 0
	s_add_i32 s57, s57, 2
	s_add_u32 s55, s55, 0x100
	s_addc_u32 s56, s56, 0
	s_cmp_gt_u32 s57, 13
	s_mov_b64 s[4:5], s[36:37]
	s_barrier
.LBB0_396:
	s_add_u32 s36, s4, 0x100
	s_addc_u32 s37, s5, 0
	s_add_i32 s68, 0, 0x10000
	v_add_u32_e32 v30, s68, v204
	ds_read_b128 v[14:17], v30
	ds_read_b128 v[22:25], v30 offset:1024
	ds_read_b128 v[26:29], v30 offset:2048
	ds_read_b128 v[30:33], v30 offset:3072
	s_cmp_eq_u32 s57, 12
	s_cselect_b32 s45, s46, s37
	s_cselect_b32 s44, s47, s36
	s_cselect_b32 s43, s51, s56
	s_cselect_b32 s42, s54, s55
	v_lshl_add_u64 v[178:179], s[4:5], 0, v[188:189]
	s_add_i32 m0, s60, 0xc000
	ds_read_b128 v[38:41], v209
	ds_read_b128 v[42:45], v209 offset:1024
	ds_read_b128 v[46:49], v209 offset:2048
	ds_read_b128 v[54:57], v209 offset:3072
	ds_read_b128 v[58:61], v209 offset:4096
	ds_read_b128 v[62:65], v209 offset:5120
	ds_read_b128 v[66:69], v209 offset:6144
	ds_read_b128 v[70:73], v209 offset:7168
	global_load_lds_dwordx4 v[178:179], off
	v_lshl_add_u64 v[178:179], s[4:5], 0, v[186:187]
	s_add_i32 m0, s60, 0xe000
	s_nop 0
	global_load_lds_dwordx4 v[178:179], off
	s_waitcnt lgkmcnt(8)
	s_barrier
	s_waitcnt lgkmcnt(0)
	s_setprio 1
	s_waitcnt lgkmcnt(0)
	v_mfma_f32_16x16x32_bf16 v[174:177], v[14:17], v[38:41], v[174:177]
	v_mfma_f32_16x16x32_bf16 v[170:173], v[26:29], v[38:41], v[170:173]
	v_mfma_f32_16x16x32_bf16 v[158:161], v[14:17], v[46:49], v[158:161]
	v_mfma_f32_16x16x32_bf16 v[154:157], v[26:29], v[46:49], v[154:157]
	v_mfma_f32_16x16x32_bf16 v[142:145], v[14:17], v[58:61], v[142:145]
	v_mfma_f32_16x16x32_bf16 v[138:141], v[26:29], v[58:61], v[138:141]
	v_mfma_f32_16x16x32_bf16 v[126:129], v[14:17], v[66:69], v[126:129]
	v_mfma_f32_16x16x32_bf16 v[122:125], v[26:29], v[66:69], v[122:125]
	v_mfma_f32_16x16x32_bf16 v[174:177], v[22:25], v[42:45], v[174:177]
	v_mfma_f32_16x16x32_bf16 v[170:173], v[30:33], v[42:45], v[170:173]
	v_mfma_f32_16x16x32_bf16 v[158:161], v[22:25], v[54:57], v[158:161]
	v_mfma_f32_16x16x32_bf16 v[154:157], v[30:33], v[54:57], v[154:157]
	v_mfma_f32_16x16x32_bf16 v[142:145], v[22:25], v[62:65], v[142:145]
	v_mfma_f32_16x16x32_bf16 v[138:141], v[30:33], v[62:65], v[138:141]
	v_mfma_f32_16x16x32_bf16 v[126:129], v[22:25], v[70:73], v[126:129]
	v_mfma_f32_16x16x32_bf16 v[122:125], v[30:33], v[70:73], v[122:125]
	s_setprio 0
	s_barrier
	s_add_i32 s69, 0, 0x14000
	v_add_u32_e32 v210, s69, v204
	s_add_i32 s4, s68, s59
	ds_read_b128 v[178:181], v210
	ds_read_b128 v[190:193], v210 offset:1024
	ds_read_b128 v[200:203], v210 offset:2048
	ds_read_b128 v[222:225], v210 offset:3072
	v_lshl_add_u64 v[210:211], s[42:43], 0, v[184:185]
	s_mov_b32 m0, s4
	v_lshl_add_u64 v[214:215], s[42:43], 0, v[182:183]
	global_load_lds_dwordx4 v[210:211], off
	s_add_i32 m0, s4, 0x2000
	s_nop 0
	global_load_lds_dwordx4 v[214:215], off
	s_barrier
	s_waitcnt lgkmcnt(0)
	s_setprio 1
	s_waitcnt lgkmcnt(0)
	v_mfma_f32_16x16x32_bf16 v[166:169], v[178:181], v[38:41], v[166:169]
	v_mfma_f32_16x16x32_bf16 v[38:41], v[200:203], v[38:41], v[162:165]
	v_mfma_f32_16x16x32_bf16 v[166:169], v[190:193], v[42:45], v[166:169]
	v_mfma_f32_16x16x32_bf16 v[38:41], v[222:225], v[42:45], v[38:41]
	v_mfma_f32_16x16x32_bf16 v[42:45], v[178:181], v[46:49], v[150:153]
	v_mfma_f32_16x16x32_bf16 v[46:49], v[200:203], v[46:49], v[146:149]
	v_mfma_f32_16x16x32_bf16 v[42:45], v[190:193], v[54:57], v[42:45]
	v_mfma_f32_16x16x32_bf16 v[46:49], v[222:225], v[54:57], v[46:49]
	v_mfma_f32_16x16x32_bf16 v[54:57], v[178:181], v[58:61], v[134:137]
	v_mfma_f32_16x16x32_bf16 v[58:61], v[200:203], v[58:61], v[130:133]
	v_mfma_f32_16x16x32_bf16 v[54:57], v[190:193], v[62:65], v[54:57]
	v_mfma_f32_16x16x32_bf16 v[58:61], v[222:225], v[62:65], v[58:61]
	v_mfma_f32_16x16x32_bf16 v[62:65], v[178:181], v[66:69], v[118:121]
	v_mfma_f32_16x16x32_bf16 v[66:69], v[200:203], v[66:69], v[114:117]
	v_mfma_f32_16x16x32_bf16 v[62:65], v[190:193], v[70:73], v[62:65]
	v_mfma_f32_16x16x32_bf16 v[66:69], v[222:225], v[70:73], v[66:69]
	s_setprio 0
	s_mov_b32 m0, s60
	v_lshl_add_u64 v[242:243], s[44:45], 0, v[184:185]
	s_barrier
	ds_read_b128 v[70:73], v209 offset:16384
	ds_read_b128 v[114:117], v209 offset:17408
	ds_read_b128 v[118:121], v209 offset:18432
	ds_read_b128 v[130:133], v209 offset:19456
	ds_read_b128 v[134:137], v209 offset:20480
	ds_read_b128 v[146:149], v209 offset:21504
	ds_read_b128 v[150:153], v209 offset:22528
	ds_read_b128 v[162:165], v209 offset:23552
	global_load_lds_dwordx4 v[242:243], off
	v_lshl_add_u64 v[244:245], s[44:45], 0, v[182:183]
	s_mov_b32 m0, s61
	s_nop 0
	global_load_lds_dwordx4 v[244:245], off
	s_barrier
	s_waitcnt lgkmcnt(0)
	s_setprio 1
	s_waitcnt lgkmcnt(0)
	v_mfma_f32_16x16x32_bf16 v[110:113], v[14:17], v[70:73], v[110:113]
	v_mfma_f32_16x16x32_bf16 v[106:109], v[26:29], v[70:73], v[106:109]
	v_mfma_f32_16x16x32_bf16 v[94:97], v[14:17], v[118:121], v[94:97]
	v_mfma_f32_16x16x32_bf16 v[90:93], v[26:29], v[118:121], v[90:93]
	v_mfma_f32_16x16x32_bf16 v[78:81], v[14:17], v[134:137], v[78:81]
	v_mfma_f32_16x16x32_bf16 v[74:77], v[26:29], v[134:137], v[74:77]
	v_mfma_f32_16x16x32_bf16 v[10:13], v[26:29], v[150:153], v[10:13]
	v_mfma_f32_16x16x32_bf16 v[110:113], v[22:25], v[114:117], v[110:113]
	v_mfma_f32_16x16x32_bf16 v[106:109], v[30:33], v[114:117], v[106:109]
	v_mfma_f32_16x16x32_bf16 v[94:97], v[22:25], v[130:133], v[94:97]
	v_mfma_f32_16x16x32_bf16 v[90:93], v[30:33], v[130:133], v[90:93]
	v_mfma_f32_16x16x32_bf16 v[78:81], v[22:25], v[146:149], v[78:81]
	v_mfma_f32_16x16x32_bf16 v[74:77], v[30:33], v[146:149], v[74:77]
	v_mfma_f32_16x16x32_bf16 v[14:17], v[14:17], v[150:153], v[18:21]
	v_mfma_f32_16x16x32_bf16 v[10:13], v[30:33], v[162:165], v[10:13]
	v_mfma_f32_16x16x32_bf16 v[14:17], v[22:25], v[162:165], v[14:17]
	s_setprio 0
	s_barrier
	s_add_u32 s4, s42, 0x40000
	s_addc_u32 s5, s43, 0
	s_add_i32 s68, s69, s59
	v_lshl_add_u64 v[18:19], s[4:5], 0, v[184:185]
	s_mov_b32 m0, s68
	s_nop 0
	global_load_lds_dwordx4 v[18:19], off
	v_lshl_add_u64 v[18:19], s[4:5], 0, v[182:183]
	s_add_i32 m0, s68, 0x2000
	s_nop 0
	global_load_lds_dwordx4 v[18:19], off
	s_waitcnt vmcnt(6)
	s_barrier
	s_setprio 1
	v_mfma_f32_16x16x32_bf16 v[18:21], v[178:181], v[70:73], v[102:105]
	v_mfma_f32_16x16x32_bf16 v[22:25], v[190:193], v[114:117], v[18:21]
	v_mfma_f32_16x16x32_bf16 v[18:21], v[200:203], v[70:73], v[98:101]
	v_mfma_f32_16x16x32_bf16 v[26:29], v[222:225], v[114:117], v[18:21]
	v_mfma_f32_16x16x32_bf16 v[18:21], v[178:181], v[118:121], v[86:89]
	v_mfma_f32_16x16x32_bf16 v[30:33], v[190:193], v[130:133], v[18:21]
	v_mfma_f32_16x16x32_bf16 v[18:21], v[200:203], v[118:121], v[82:85]
	v_mfma_f32_16x16x32_bf16 v[70:73], v[222:225], v[130:133], v[18:21]
	v_mfma_f32_16x16x32_bf16 v[18:21], v[178:181], v[134:137], v[50:53]
	v_mfma_f32_16x16x32_bf16 v[50:53], v[190:193], v[146:149], v[18:21]
	v_mfma_f32_16x16x32_bf16 v[18:21], v[200:203], v[134:137], v[34:37]
	v_mfma_f32_16x16x32_bf16 v[6:9], v[178:181], v[150:153], v[6:9]
	v_mfma_f32_16x16x32_bf16 v[2:5], v[200:203], v[150:153], v[2:5]
	v_mfma_f32_16x16x32_bf16 v[34:37], v[222:225], v[146:149], v[18:21]
	v_mfma_f32_16x16x32_bf16 v[6:9], v[190:193], v[162:165], v[6:9]
	v_mfma_f32_16x16x32_bf16 v[2:5], v[222:225], v[162:165], v[2:5]
	s_setprio 0
	s_add_i32 s68, 0, 0x18000
	v_add_u32_e32 v98, s68, v204
	s_barrier
	ds_read_b128 v[18:21], v98
	ds_read_b128 v[82:85], v98 offset:1024
	ds_read_b128 v[86:89], v98 offset:2048
	ds_read_b128 v[98:101], v98 offset:3072
	s_add_u32 s4, s44, 0x40000
	s_addc_u32 s5, s45, 0
	s_mov_b32 m0, s62
	v_lshl_add_u64 v[134:135], s[4:5], 0, v[184:185]
	ds_read_b128 v[102:105], v209 offset:32768
	ds_read_b128 v[114:117], v209 offset:33792
	ds_read_b128 v[118:121], v209 offset:34816
	ds_read_b128 v[130:133], v209 offset:35840
	ds_read_b128 v[178:181], v209 offset:36864
	ds_read_b128 v[190:193], v209 offset:37888
	ds_read_b128 v[200:203], v209 offset:38912
	ds_read_b128 v[222:225], v209 offset:39936
	global_load_lds_dwordx4 v[134:135], off
	v_lshl_add_u64 v[134:135], s[4:5], 0, v[182:183]
	s_mov_b32 m0, s63
	s_nop 0
	global_load_lds_dwordx4 v[134:135], off
	s_waitcnt lgkmcnt(8)
	s_barrier
	s_waitcnt lgkmcnt(0)
	s_setprio 1
	s_waitcnt lgkmcnt(0)
	v_mfma_f32_16x16x32_bf16 v[134:137], v[18:21], v[102:105], v[174:177]
	v_mfma_f32_16x16x32_bf16 v[174:177], v[82:85], v[114:117], v[134:137]
	v_mfma_f32_16x16x32_bf16 v[134:137], v[86:89], v[102:105], v[170:173]
	v_mfma_f32_16x16x32_bf16 v[170:173], v[98:101], v[114:117], v[134:137]
	v_mfma_f32_16x16x32_bf16 v[134:137], v[18:21], v[118:121], v[158:161]
	v_mfma_f32_16x16x32_bf16 v[158:161], v[82:85], v[130:133], v[134:137]
	v_mfma_f32_16x16x32_bf16 v[134:137], v[86:89], v[118:121], v[154:157]
	v_mfma_f32_16x16x32_bf16 v[154:157], v[98:101], v[130:133], v[134:137]
	v_mfma_f32_16x16x32_bf16 v[134:137], v[18:21], v[178:181], v[142:145]
	v_mfma_f32_16x16x32_bf16 v[142:145], v[82:85], v[190:193], v[134:137]
	v_mfma_f32_16x16x32_bf16 v[134:137], v[86:89], v[178:181], v[138:141]
	v_mfma_f32_16x16x32_bf16 v[126:129], v[18:21], v[200:203], v[126:129]
	v_mfma_f32_16x16x32_bf16 v[122:125], v[86:89], v[200:203], v[122:125]
	v_mfma_f32_16x16x32_bf16 v[138:141], v[98:101], v[190:193], v[134:137]
	v_mfma_f32_16x16x32_bf16 v[126:129], v[82:85], v[222:225], v[126:129]
	v_mfma_f32_16x16x32_bf16 v[122:125], v[98:101], v[222:225], v[122:125]
	s_setprio 0
	s_barrier
	s_add_i32 s44, 0, 0x1c000
	v_add_u32_e32 v134, s44, v204
	s_add_i32 s4, s68, s59
	ds_read_b128 v[226:229], v134
	ds_read_b128 v[230:233], v134 offset:1024
	ds_read_b128 v[234:237], v134 offset:2048
	ds_read_b128 v[238:241], v134 offset:3072
	v_lshl_add_u64 v[134:135], v[210:211], 0, s[22:23]
	s_mov_b32 m0, s4
	s_nop 0
	global_load_lds_dwordx4 v[134:135], off
	v_lshl_add_u64 v[134:135], v[214:215], 0, s[22:23]
	s_add_i32 m0, s4, 0x2000
	s_nop 0
	global_load_lds_dwordx4 v[134:135], off
	s_barrier
	s_waitcnt lgkmcnt(0)
	s_setprio 1
	s_waitcnt lgkmcnt(0)
	v_mfma_f32_16x16x32_bf16 v[38:41], v[234:237], v[102:105], v[38:41]
	v_mfma_f32_16x16x32_bf16 v[162:165], v[238:241], v[114:117], v[38:41]
	v_mfma_f32_16x16x32_bf16 v[38:41], v[226:229], v[118:121], v[42:45]
	v_mfma_f32_16x16x32_bf16 v[150:153], v[230:233], v[130:133], v[38:41]
	v_mfma_f32_16x16x32_bf16 v[38:41], v[234:237], v[118:121], v[46:49]
	v_mfma_f32_16x16x32_bf16 v[134:137], v[226:229], v[102:105], v[166:169]
	v_mfma_f32_16x16x32_bf16 v[146:149], v[238:241], v[130:133], v[38:41]
	v_mfma_f32_16x16x32_bf16 v[38:41], v[226:229], v[178:181], v[54:57]
	v_mfma_f32_16x16x32_bf16 v[166:169], v[230:233], v[114:117], v[134:137]
	v_mfma_f32_16x16x32_bf16 v[134:137], v[230:233], v[190:193], v[38:41]
	v_mfma_f32_16x16x32_bf16 v[38:41], v[234:237], v[178:181], v[58:61]
	v_mfma_f32_16x16x32_bf16 v[130:133], v[238:241], v[190:193], v[38:41]
	v_mfma_f32_16x16x32_bf16 v[38:41], v[226:229], v[200:203], v[62:65]
	v_mfma_f32_16x16x32_bf16 v[118:121], v[230:233], v[222:225], v[38:41]
	v_mfma_f32_16x16x32_bf16 v[38:41], v[234:237], v[200:203], v[66:69]
	v_mfma_f32_16x16x32_bf16 v[114:117], v[238:241], v[222:225], v[38:41]
	s_setprio 0
	s_mov_b32 m0, s64
	v_lshl_add_u64 v[102:103], v[242:243], 0, s[22:23]
	s_barrier
	s_nop 2
	ds_read_b128 v[38:41], v209 offset:49152
	ds_read_b128 v[42:45], v209 offset:50176
	ds_read_b128 v[46:49], v209 offset:51200
	ds_read_b128 v[54:57], v209 offset:52224
	ds_read_b128 v[58:61], v209 offset:53248
	ds_read_b128 v[62:65], v209 offset:54272
	ds_read_b128 v[66:69], v209 offset:55296
	ds_read_b128 v[178:181], v209 offset:56320
	global_load_lds_dwordx4 v[102:103], off
	v_lshl_add_u64 v[102:103], v[244:245], 0, s[22:23]
	s_mov_b32 m0, s65
	s_nop 0
	global_load_lds_dwordx4 v[102:103], off
	s_barrier
	s_waitcnt lgkmcnt(0)
	s_setprio 1
	s_waitcnt lgkmcnt(0)
	v_mfma_f32_16x16x32_bf16 v[102:105], v[18:21], v[38:41], v[110:113]
	v_mfma_f32_16x16x32_bf16 v[110:113], v[82:85], v[42:45], v[102:105]
	v_mfma_f32_16x16x32_bf16 v[102:105], v[86:89], v[38:41], v[106:109]
	v_mfma_f32_16x16x32_bf16 v[94:97], v[18:21], v[46:49], v[94:97]
	v_mfma_f32_16x16x32_bf16 v[90:93], v[86:89], v[46:49], v[90:93]
	v_mfma_f32_16x16x32_bf16 v[78:81], v[18:21], v[58:61], v[78:81]
	v_mfma_f32_16x16x32_bf16 v[74:77], v[86:89], v[58:61], v[74:77]
	v_mfma_f32_16x16x32_bf16 v[14:17], v[18:21], v[66:69], v[14:17]
	v_mfma_f32_16x16x32_bf16 v[10:13], v[86:89], v[66:69], v[10:13]
	v_mfma_f32_16x16x32_bf16 v[106:109], v[98:101], v[42:45], v[102:105]
	v_mfma_f32_16x16x32_bf16 v[94:97], v[82:85], v[54:57], v[94:97]
	v_mfma_f32_16x16x32_bf16 v[90:93], v[98:101], v[54:57], v[90:93]
	v_mfma_f32_16x16x32_bf16 v[78:81], v[82:85], v[62:65], v[78:81]
	v_mfma_f32_16x16x32_bf16 v[74:77], v[98:101], v[62:65], v[74:77]
	v_mfma_f32_16x16x32_bf16 v[18:21], v[82:85], v[178:181], v[14:17]
	v_mfma_f32_16x16x32_bf16 v[10:13], v[98:101], v[178:181], v[10:13]
	s_setprio 0
	s_barrier
	s_add_u32 s4, s42, 0x40080
	s_addc_u32 s5, s43, 0
	s_add_i32 s42, s44, s59
	v_lshl_add_u64 v[14:15], s[4:5], 0, v[184:185]
	s_mov_b32 m0, s42
	s_nop 0
	global_load_lds_dwordx4 v[14:15], off
	v_lshl_add_u64 v[14:15], s[4:5], 0, v[182:183]
	s_add_i32 m0, s42, 0x2000
	s_nop 0
	global_load_lds_dwordx4 v[14:15], off
	s_waitcnt vmcnt(6)
	s_barrier
	s_setprio 1
	v_mfma_f32_16x16x32_bf16 v[14:17], v[226:229], v[38:41], v[22:25]
	v_mfma_f32_16x16x32_bf16 v[102:105], v[230:233], v[42:45], v[14:17]
	v_mfma_f32_16x16x32_bf16 v[14:17], v[234:237], v[38:41], v[26:29]
	v_mfma_f32_16x16x32_bf16 v[98:101], v[238:241], v[42:45], v[14:17]
	v_mfma_f32_16x16x32_bf16 v[14:17], v[226:229], v[46:49], v[30:33]
	v_mfma_f32_16x16x32_bf16 v[86:89], v[230:233], v[54:57], v[14:17]
	v_mfma_f32_16x16x32_bf16 v[14:17], v[234:237], v[46:49], v[70:73]
	v_mfma_f32_16x16x32_bf16 v[82:85], v[238:241], v[54:57], v[14:17]
	v_mfma_f32_16x16x32_bf16 v[14:17], v[226:229], v[58:61], v[50:53]
	v_mfma_f32_16x16x32_bf16 v[50:53], v[230:233], v[62:65], v[14:17]
	v_mfma_f32_16x16x32_bf16 v[14:17], v[234:237], v[58:61], v[34:37]
	v_mfma_f32_16x16x32_bf16 v[6:9], v[226:229], v[66:69], v[6:9]
	v_mfma_f32_16x16x32_bf16 v[2:5], v[234:237], v[66:69], v[2:5]
	v_mfma_f32_16x16x32_bf16 v[34:37], v[238:241], v[62:65], v[14:17]
	v_mfma_f32_16x16x32_bf16 v[6:9], v[230:233], v[178:181], v[6:9]
	v_mfma_f32_16x16x32_bf16 v[2:5], v[238:241], v[178:181], v[2:5]
	s_setprio 0
	s_add_i32 s57, s57, 2
	s_add_u32 s55, s55, 0x100
	s_addc_u32 s56, s56, 0
	s_cmp_gt_u32 s57, 13
	s_mov_b64 s[4:5], s[36:37]
	s_barrier
	s_cbranch_scc0 .LBB0_396
	s_and_b64 vcc, exec, s[52:53]
	s_cbranch_vccnz .Lpk0_nonext
	v_lshl_add_u64 v[246:247], s[48:49], 0, v[188:189]
	s_add_i32 m0, s60, 0xc000
	s_nop 0
	global_load_lds_dwordx4 v[246:247], off
	v_lshl_add_u64 v[248:249], s[48:49], 0, v[186:187]
	s_add_i32 m0, s60, 0xe000
	s_nop 0
	global_load_lds_dwordx4 v[248:249], off
.Lpk0_nonext:
	v_lshl_or_b32 v202, s27, 8, v208
	s_and_b32 s4, s27, -4
	v_ashrrev_i32_e32 v203, 31, v202
	v_lshlrev_b64 v[14:15], 2, v[202:203]
	v_lshl_add_u64 v[16:17], s[10:11], 0, v[14:15]
	v_lshl_add_u64 v[22:23], s[12:13], 0, v[14:15]
	flat_load_dwordx4 v[70:73], v[16:17]
	flat_load_dwordx4 v[66:69], v[22:23]
	s_cmp_eq_u32 s4, 4
	s_cselect_b64 s[36:37], -1, 0
	s_cmp_lg_u32 s4, 4
	v_mov_b32_e32 v46, 0
	v_and_b32_e32 v210, 0x3ff, v202
	v_mov_b32_e32 v62, 0
	v_mov_b32_e32 v63, 0
	v_mov_b32_e32 v64, 0
	v_mov_b32_e32 v65, 0
	s_cbranch_scc1 .LBB0_399
	v_lshlrev_b32_e32 v14, 2, v210
	v_mov_b32_e32 v15, v0
	v_lshl_add_u64 v[14:15], s[14:15], 0, v[14:15]
	flat_load_dwordx4 v[62:65], v[14:15]

.LBB0_1098:
	s_add_i32 s76, s76, 1
	s_mov_b64 s[62:63], s[54:55]
	s_mul_i32 s54, s76, s26
	s_add_i32 s64, s54, s2
	s_cmpk_gt_i32 s64, 0x57f
	s_cselect_b64 s[60:61], -1, 0
	s_lshl_b32 s54, s64, 3
	s_and_b32 s54, s54, 56
	s_bfe_u32 s55, s64, 0x30003
	s_or_b32 s77, s54, s55
	s_ashr_i32 s58, s64, 6
	s_lshl_b32 s54, s77, 19
	s_mov_b64 s[36:37], s[56:57]
	s_add_u32 s56, s52, s54
	s_addc_u32 s57, s53, 0
	s_ashr_i32 s59, s58, 31
	s_lshl_b64 s[54:55], s[58:59], 19
	s_add_u32 s54, s4, s54
	s_addc_u32 s55, s5, s55
	s_cmpk_lt_i32 s64, 0x580
	s_cselect_b32 s59, s57, s37
	s_cselect_b32 s78, s56, s36
	s_cselect_b32 s79, s55, s63
	s_cselect_b32 s80, s54, s62
	s_add_u32 s81, s62, 0x100
	s_addc_u32 s82, s63, 0
	s_mov_b32 s83, -2
	s_add_u32 s62, s36, 0x100
	s_addc_u32 s63, s37, 0
	s_add_i32 s84, 0, 0x10000
	v_add_u32_e32 v70, s84, v170
	ds_read_b128 v[58:61], v70
	ds_read_b128 v[62:65], v70 offset:1024
	ds_read_b128 v[66:69], v70 offset:2048
	ds_read_b128 v[70:73], v70 offset:3072
	s_cmp_eq_u32 s83, 12
	s_cselect_b32 s67, s59, s63
	s_cselect_b32 s66, s78, s62
	s_cselect_b32 s65, s79, s82
	s_cselect_b32 s64, s80, s81
	v_lshl_add_u64 v[192:193], s[36:37], 0, v[168:169]
	s_add_i32 m0, s69, 0xc000
	ds_read_b128 v[78:81], v175
	ds_read_b128 v[86:89], v175 offset:1024
	ds_read_b128 v[90:93], v175 offset:2048
	ds_read_b128 v[94:97], v175 offset:3072
	ds_read_b128 v[176:179], v175 offset:4096
	ds_read_b128 v[180:183], v175 offset:5120
	ds_read_b128 v[184:187], v175 offset:6144
	ds_read_b128 v[188:191], v175 offset:7168
	s_cmp_lg_u32 s76, 1
	s_cbranch_scc1 .Lpk2_d0
	global_load_lds_dwordx4 v[192:193], off
.Lpk2_d0:
	v_lshl_add_u64 v[192:193], s[36:37], 0, v[166:167]
	s_add_i32 m0, s69, 0xe000
	s_nop 0
	s_cmp_lg_u32 s76, 1
	s_cbranch_scc1 .Lpk2_d1
	global_load_lds_dwordx4 v[192:193], off
.Lpk2_d1:
	s_waitcnt lgkmcnt(8)
	s_barrier
	s_waitcnt lgkmcnt(0)
	s_setprio 1
	s_waitcnt lgkmcnt(0)
	v_mfma_f32_16x16x32_bf16 v[158:161], v[58:61], v[78:81], 0
	v_mfma_f32_16x16x32_bf16 v[150:153], v[66:69], v[78:81], 0
	v_mfma_f32_16x16x32_bf16 v[142:145], v[58:61], v[90:93], 0
	v_mfma_f32_16x16x32_bf16 v[134:137], v[66:69], v[90:93], 0
	v_mfma_f32_16x16x32_bf16 v[126:129], v[58:61], v[176:179], 0
	v_mfma_f32_16x16x32_bf16 v[118:121], v[66:69], v[176:179], 0
	v_mfma_f32_16x16x32_bf16 v[110:113], v[58:61], v[184:187], 0
	v_mfma_f32_16x16x32_bf16 v[102:105], v[66:69], v[184:187], 0
	v_mfma_f32_16x16x32_bf16 v[158:161], v[62:65], v[86:89], v[158:161]
	v_mfma_f32_16x16x32_bf16 v[150:153], v[70:73], v[86:89], v[150:153]
	v_mfma_f32_16x16x32_bf16 v[142:145], v[62:65], v[94:97], v[142:145]
	v_mfma_f32_16x16x32_bf16 v[134:137], v[70:73], v[94:97], v[134:137]
	v_mfma_f32_16x16x32_bf16 v[126:129], v[62:65], v[180:183], v[126:129]
	v_mfma_f32_16x16x32_bf16 v[118:121], v[70:73], v[180:183], v[118:121]
	v_mfma_f32_16x16x32_bf16 v[110:113], v[62:65], v[188:191], v[110:113]
	v_mfma_f32_16x16x32_bf16 v[102:105], v[70:73], v[188:191], v[102:105]
	s_setprio 0
	s_barrier
	s_add_i32 s85, 0, 0x14000
	v_add_u32_e32 v192, s85, v170
	s_add_i32 s36, s84, s68
	ds_read_b128 v[200:203], v192
	ds_read_b128 v[204:207], v192 offset:1024
	ds_read_b128 v[208:211], v192 offset:2048
	ds_read_b128 v[222:225], v192 offset:3072
	v_lshl_add_u64 v[192:193], s[64:65], 0, v[164:165]
	s_mov_b32 m0, s36
	v_lshl_add_u64 v[214:215], s[64:65], 0, v[162:163]
	global_load_lds_dwordx4 v[192:193], off
	s_add_i32 m0, s36, 0x2000
	s_nop 0
	global_load_lds_dwordx4 v[214:215], off
	s_barrier
	s_waitcnt lgkmcnt(0)
	s_setprio 1
	s_waitcnt lgkmcnt(0)
	v_mfma_f32_16x16x32_bf16 v[154:157], v[200:203], v[78:81], 0
	v_mfma_f32_16x16x32_bf16 v[78:81], v[208:211], v[78:81], 0
	v_mfma_f32_16x16x32_bf16 v[154:157], v[204:207], v[86:89], v[154:157]
	v_mfma_f32_16x16x32_bf16 v[78:81], v[222:225], v[86:89], v[78:81]
	v_mfma_f32_16x16x32_bf16 v[86:89], v[200:203], v[90:93], 0
	v_mfma_f32_16x16x32_bf16 v[90:93], v[208:211], v[90:93], 0
	v_mfma_f32_16x16x32_bf16 v[114:117], v[208:211], v[176:179], 0
	v_mfma_f32_16x16x32_bf16 v[106:109], v[200:203], v[184:187], 0
	v_mfma_f32_16x16x32_bf16 v[98:101], v[208:211], v[184:187], 0
	v_mfma_f32_16x16x32_bf16 v[86:89], v[204:207], v[94:97], v[86:89]
	v_mfma_f32_16x16x32_bf16 v[90:93], v[222:225], v[94:97], v[90:93]
	v_mfma_f32_16x16x32_bf16 v[94:97], v[200:203], v[176:179], 0
	v_mfma_f32_16x16x32_bf16 v[114:117], v[222:225], v[180:183], v[114:117]
	v_mfma_f32_16x16x32_bf16 v[106:109], v[204:207], v[188:191], v[106:109]
	v_mfma_f32_16x16x32_bf16 v[98:101], v[222:225], v[188:191], v[98:101]
	v_mfma_f32_16x16x32_bf16 v[94:97], v[204:207], v[180:183], v[94:97]
	s_setprio 0
	s_mov_b32 m0, s69
	v_lshl_add_u64 v[234:235], s[66:67], 0, v[164:165]
	s_barrier
	ds_read_b128 v[122:125], v175 offset:16384
	ds_read_b128 v[130:133], v175 offset:17408
	ds_read_b128 v[138:141], v175 offset:18432
	ds_read_b128 v[146:149], v175 offset:19456
	ds_read_b128 v[176:179], v175 offset:20480
	ds_read_b128 v[180:183], v175 offset:21504
	ds_read_b128 v[184:187], v175 offset:22528
	ds_read_b128 v[188:191], v175 offset:23552
	global_load_lds_dwordx4 v[234:235], off
	v_lshl_add_u64 v[236:237], s[66:67], 0, v[162:163]
	s_mov_b32 m0, s70
	s_nop 0
	global_load_lds_dwordx4 v[236:237], off
	s_barrier
	s_waitcnt lgkmcnt(0)
	s_setprio 1
	s_waitcnt lgkmcnt(0)
	v_mfma_f32_16x16x32_bf16 v[82:85], v[58:61], v[122:125], 0
	v_mfma_f32_16x16x32_bf16 v[54:57], v[66:69], v[122:125], 0
	v_mfma_f32_16x16x32_bf16 v[46:49], v[58:61], v[138:141], 0
	v_mfma_f32_16x16x32_bf16 v[38:41], v[66:69], v[138:141], 0
	v_mfma_f32_16x16x32_bf16 v[30:33], v[58:61], v[176:179], 0
	v_mfma_f32_16x16x32_bf16 v[22:25], v[66:69], v[176:179], 0
	v_mfma_f32_16x16x32_bf16 v[14:17], v[58:61], v[184:187], 0
	v_mfma_f32_16x16x32_bf16 v[6:9], v[66:69], v[184:187], 0
	v_mfma_f32_16x16x32_bf16 v[82:85], v[62:65], v[130:133], v[82:85]
	v_mfma_f32_16x16x32_bf16 v[54:57], v[70:73], v[130:133], v[54:57]
	v_mfma_f32_16x16x32_bf16 v[46:49], v[62:65], v[146:149], v[46:49]
	v_mfma_f32_16x16x32_bf16 v[38:41], v[70:73], v[146:149], v[38:41]
	v_mfma_f32_16x16x32_bf16 v[30:33], v[62:65], v[180:183], v[30:33]
	v_mfma_f32_16x16x32_bf16 v[22:25], v[70:73], v[180:183], v[22:25]
	v_mfma_f32_16x16x32_bf16 v[14:17], v[62:65], v[188:191], v[14:17]
	v_mfma_f32_16x16x32_bf16 v[6:9], v[70:73], v[188:191], v[6:9]
	s_setprio 0
	s_barrier
	s_add_u32 s36, s64, 0x40000
	s_addc_u32 s37, s65, 0
	s_add_i32 s84, s85, s68
	v_lshl_add_u64 v[58:59], s[36:37], 0, v[164:165]
	s_mov_b32 m0, s84
	s_nop 0
	global_load_lds_dwordx4 v[58:59], off
	v_lshl_add_u64 v[58:59], s[36:37], 0, v[162:163]
	s_add_i32 m0, s84, 0x2000
	s_nop 0
	global_load_lds_dwordx4 v[58:59], off
	s_cmp_lg_u32 s76, 1
	s_cbranch_scc1 .Lpk2_w
	s_waitcnt vmcnt(6)
.Lpk2_w:
	s_barrier
	s_setprio 1
	v_mfma_f32_16x16x32_bf16 v[50:53], v[208:211], v[122:125], 0
	v_mfma_f32_16x16x32_bf16 v[42:45], v[200:203], v[138:141], 0
	v_mfma_f32_16x16x32_bf16 v[34:37], v[208:211], v[138:141], 0
	v_mfma_f32_16x16x32_bf16 v[26:29], v[200:203], v[176:179], 0
	v_mfma_f32_16x16x32_bf16 v[18:21], v[208:211], v[176:179], 0
	v_mfma_f32_16x16x32_bf16 v[10:13], v[200:203], v[184:187], 0
	v_mfma_f32_16x16x32_bf16 v[2:5], v[208:211], v[184:187], 0
	v_mfma_f32_16x16x32_bf16 v[58:61], v[200:203], v[122:125], 0
	v_mfma_f32_16x16x32_bf16 v[50:53], v[222:225], v[130:133], v[50:53]
	v_mfma_f32_16x16x32_bf16 v[42:45], v[204:207], v[146:149], v[42:45]
	v_mfma_f32_16x16x32_bf16 v[34:37], v[222:225], v[146:149], v[34:37]
	v_mfma_f32_16x16x32_bf16 v[26:29], v[204:207], v[180:183], v[26:29]
	v_mfma_f32_16x16x32_bf16 v[18:21], v[222:225], v[180:183], v[18:21]
	v_mfma_f32_16x16x32_bf16 v[10:13], v[204:207], v[188:191], v[10:13]
	v_mfma_f32_16x16x32_bf16 v[2:5], v[222:225], v[188:191], v[2:5]
	v_mfma_f32_16x16x32_bf16 v[58:61], v[204:207], v[130:133], v[58:61]
	s_setprio 0
	s_add_i32 s84, 0, 0x18000
	v_add_u32_e32 v74, s84, v170
	s_barrier
	ds_read_b128 v[62:65], v74
	ds_read_b128 v[66:69], v74 offset:1024
	ds_read_b128 v[70:73], v74 offset:2048
	ds_read_b128 v[74:77], v74 offset:3072
	s_add_u32 s36, s66, 0x40000
	s_addc_u32 s37, s67, 0
	s_mov_b32 m0, s71
	v_lshl_add_u64 v[138:139], s[36:37], 0, v[164:165]
	ds_read_b128 v[122:125], v175 offset:32768
	ds_read_b128 v[130:133], v175 offset:33792
	ds_read_b128 v[176:179], v175 offset:34816
	ds_read_b128 v[180:183], v175 offset:35840
	ds_read_b128 v[184:187], v175 offset:36864
	ds_read_b128 v[188:191], v175 offset:37888
	ds_read_b128 v[200:203], v175 offset:38912
	ds_read_b128 v[204:207], v175 offset:39936
	global_load_lds_dwordx4 v[138:139], off
	v_lshl_add_u64 v[138:139], s[36:37], 0, v[162:163]
	s_mov_b32 m0, s72
	s_nop 0
	global_load_lds_dwordx4 v[138:139], off
	s_waitcnt lgkmcnt(8)
	s_barrier
	s_waitcnt lgkmcnt(0)
	s_setprio 1
	s_waitcnt lgkmcnt(0)
	v_mfma_f32_16x16x32_bf16 v[138:141], v[62:65], v[122:125], v[158:161]
	v_mfma_f32_16x16x32_bf16 v[158:161], v[66:69], v[130:133], v[138:141]
	v_mfma_f32_16x16x32_bf16 v[138:141], v[70:73], v[122:125], v[150:153]
	v_mfma_f32_16x16x32_bf16 v[150:153], v[74:77], v[130:133], v[138:141]
	v_mfma_f32_16x16x32_bf16 v[138:141], v[62:65], v[176:179], v[142:145]
	v_mfma_f32_16x16x32_bf16 v[134:137], v[70:73], v[176:179], v[134:137]
	v_mfma_f32_16x16x32_bf16 v[126:129], v[62:65], v[184:187], v[126:129]
	v_mfma_f32_16x16x32_bf16 v[118:121], v[70:73], v[184:187], v[118:121]
	v_mfma_f32_16x16x32_bf16 v[110:113], v[62:65], v[200:203], v[110:113]
	v_mfma_f32_16x16x32_bf16 v[102:105], v[70:73], v[200:203], v[102:105]
	v_mfma_f32_16x16x32_bf16 v[142:145], v[66:69], v[180:183], v[138:141]
	v_mfma_f32_16x16x32_bf16 v[134:137], v[74:77], v[180:183], v[134:137]
	v_mfma_f32_16x16x32_bf16 v[126:129], v[66:69], v[188:191], v[126:129]
	v_mfma_f32_16x16x32_bf16 v[118:121], v[74:77], v[188:191], v[118:121]
	v_mfma_f32_16x16x32_bf16 v[110:113], v[66:69], v[204:207], v[110:113]
	v_mfma_f32_16x16x32_bf16 v[102:105], v[74:77], v[204:207], v[102:105]
	s_setprio 0
	s_barrier
	s_add_i32 s66, 0, 0x1c000
	v_add_u32_e32 v138, s66, v170
	s_add_i32 s36, s84, s68
	ds_read_b128 v[208:211], v138
	ds_read_b128 v[222:225], v138 offset:1024
	ds_read_b128 v[226:229], v138 offset:2048
	ds_read_b128 v[230:233], v138 offset:3072
	v_lshl_add_u64 v[138:139], v[192:193], 0, s[22:23]
	s_mov_b32 m0, s36
	s_nop 0
	global_load_lds_dwordx4 v[138:139], off
	v_lshl_add_u64 v[138:139], v[214:215], 0, s[22:23]
	s_add_i32 m0, s36, 0x2000
	s_nop 0
	global_load_lds_dwordx4 v[138:139], off
	s_barrier
	s_waitcnt lgkmcnt(0)
	s_setprio 1
	s_waitcnt lgkmcnt(0)
	v_mfma_f32_16x16x32_bf16 v[78:81], v[226:229], v[122:125], v[78:81]
	v_mfma_f32_16x16x32_bf16 v[138:141], v[208:211], v[122:125], v[154:157]
	v_mfma_f32_16x16x32_bf16 v[146:149], v[230:233], v[130:133], v[78:81]
	v_mfma_f32_16x16x32_bf16 v[78:81], v[208:211], v[176:179], v[86:89]
	v_mfma_f32_16x16x32_bf16 v[154:157], v[222:225], v[130:133], v[138:141]
	v_mfma_f32_16x16x32_bf16 v[138:141], v[222:225], v[180:183], v[78:81]
	v_mfma_f32_16x16x32_bf16 v[78:81], v[226:229], v[176:179], v[90:93]
	v_mfma_f32_16x16x32_bf16 v[130:133], v[230:233], v[180:183], v[78:81]
	v_mfma_f32_16x16x32_bf16 v[78:81], v[208:211], v[184:187], v[94:97]
	v_mfma_f32_16x16x32_bf16 v[122:125], v[222:225], v[188:191], v[78:81]
	v_mfma_f32_16x16x32_bf16 v[78:81], v[226:229], v[184:187], v[114:117]
	v_mfma_f32_16x16x32_bf16 v[114:117], v[230:233], v[188:191], v[78:81]
	v_mfma_f32_16x16x32_bf16 v[78:81], v[208:211], v[200:203], v[106:109]
	v_mfma_f32_16x16x32_bf16 v[106:109], v[222:225], v[204:207], v[78:81]
	v_mfma_f32_16x16x32_bf16 v[78:81], v[226:229], v[200:203], v[98:101]
	v_mfma_f32_16x16x32_bf16 v[98:101], v[230:233], v[204:207], v[78:81]
	s_setprio 0
	s_mov_b32 m0, s73
	v_lshl_add_u64 v[192:193], v[234:235], 0, s[22:23]
	s_barrier
	s_nop 2
	ds_read_b128 v[78:81], v175 offset:49152
	ds_read_b128 v[86:89], v175 offset:50176
	ds_read_b128 v[90:93], v175 offset:51200
	ds_read_b128 v[94:97], v175 offset:52224
	ds_read_b128 v[176:179], v175 offset:53248
	ds_read_b128 v[180:183], v175 offset:54272
	ds_read_b128 v[184:187], v175 offset:55296
	ds_read_b128 v[188:191], v175 offset:56320
	global_load_lds_dwordx4 v[192:193], off
	v_lshl_add_u64 v[192:193], v[236:237], 0, s[22:23]
	s_mov_b32 m0, s75
	s_nop 0
	global_load_lds_dwordx4 v[192:193], off
	s_barrier
	s_waitcnt lgkmcnt(0)
	s_setprio 1
	s_waitcnt lgkmcnt(0)
	v_mfma_f32_16x16x32_bf16 v[82:85], v[62:65], v[78:81], v[82:85]
	v_mfma_f32_16x16x32_bf16 v[54:57], v[70:73], v[78:81], v[54:57]
	v_mfma_f32_16x16x32_bf16 v[46:49], v[62:65], v[90:93], v[46:49]
	v_mfma_f32_16x16x32_bf16 v[38:41], v[70:73], v[90:93], v[38:41]
	v_mfma_f32_16x16x32_bf16 v[30:33], v[62:65], v[176:179], v[30:33]
	v_mfma_f32_16x16x32_bf16 v[22:25], v[70:73], v[176:179], v[22:25]
	v_mfma_f32_16x16x32_bf16 v[14:17], v[62:65], v[184:187], v[14:17]
	v_mfma_f32_16x16x32_bf16 v[6:9], v[70:73], v[184:187], v[6:9]
	v_mfma_f32_16x16x32_bf16 v[82:85], v[66:69], v[86:89], v[82:85]
	v_mfma_f32_16x16x32_bf16 v[54:57], v[74:77], v[86:89], v[54:57]
	v_mfma_f32_16x16x32_bf16 v[46:49], v[66:69], v[94:97], v[46:49]
	v_mfma_f32_16x16x32_bf16 v[38:41], v[74:77], v[94:97], v[38:41]
	v_mfma_f32_16x16x32_bf16 v[30:33], v[66:69], v[180:183], v[30:33]
	v_mfma_f32_16x16x32_bf16 v[22:25], v[74:77], v[180:183], v[22:25]
	v_mfma_f32_16x16x32_bf16 v[14:17], v[66:69], v[188:191], v[14:17]
	v_mfma_f32_16x16x32_bf16 v[6:9], v[74:77], v[188:191], v[6:9]
	s_setprio 0
	s_barrier
	s_add_u32 s36, s64, 0x40080
	s_addc_u32 s37, s65, 0
	s_add_i32 s64, s66, s68
	v_lshl_add_u64 v[62:63], s[36:37], 0, v[164:165]
	s_mov_b32 m0, s64
	s_nop 0
	global_load_lds_dwordx4 v[62:63], off
	v_lshl_add_u64 v[62:63], s[36:37], 0, v[162:163]
	s_add_i32 m0, s64, 0x2000
	s_nop 0
	global_load_lds_dwordx4 v[62:63], off
	s_waitcnt vmcnt(6)
	s_barrier
	s_setprio 1
	v_mfma_f32_16x16x32_bf16 v[58:61], v[208:211], v[78:81], v[58:61]
	v_mfma_f32_16x16x32_bf16 v[50:53], v[226:229], v[78:81], v[50:53]
	v_mfma_f32_16x16x32_bf16 v[42:45], v[208:211], v[90:93], v[42:45]
	v_mfma_f32_16x16x32_bf16 v[34:37], v[226:229], v[90:93], v[34:37]
	v_mfma_f32_16x16x32_bf16 v[26:29], v[208:211], v[176:179], v[26:29]
	v_mfma_f32_16x16x32_bf16 v[18:21], v[226:229], v[176:179], v[18:21]
	v_mfma_f32_16x16x32_bf16 v[10:13], v[208:211], v[184:187], v[10:13]
	v_mfma_f32_16x16x32_bf16 v[2:5], v[226:229], v[184:187], v[2:5]
	v_mfma_f32_16x16x32_bf16 v[74:77], v[222:225], v[86:89], v[58:61]
	v_mfma_f32_16x16x32_bf16 v[50:53], v[230:233], v[86:89], v[50:53]
	v_mfma_f32_16x16x32_bf16 v[42:45], v[222:225], v[94:97], v[42:45]
	v_mfma_f32_16x16x32_bf16 v[34:37], v[230:233], v[94:97], v[34:37]
	v_mfma_f32_16x16x32_bf16 v[26:29], v[222:225], v[180:183], v[26:29]
	v_mfma_f32_16x16x32_bf16 v[18:21], v[230:233], v[180:183], v[18:21]
	v_mfma_f32_16x16x32_bf16 v[10:13], v[222:225], v[188:191], v[10:13]
	v_mfma_f32_16x16x32_bf16 v[2:5], v[230:233], v[188:191], v[2:5]
	s_setprio 0
	s_add_i32 s83, s83, 2
	s_add_u32 s81, s81, 0x100
	s_addc_u32 s82, s82, 0
	s_cmp_gt_u32 s83, 13
	s_mov_b64 s[36:37], s[62:63]
	s_barrier
.LBB0_1099:
	s_add_u32 s62, s36, 0x100
	s_addc_u32 s63, s37, 0
	s_add_i32 s84, 0, 0x10000
	v_add_u32_e32 v70, s84, v170
	ds_read_b128 v[58:61], v70
	ds_read_b128 v[62:65], v70 offset:1024
	ds_read_b128 v[66:69], v70 offset:2048
	ds_read_b128 v[70:73], v70 offset:3072
	s_cmp_eq_u32 s83, 12
	s_cselect_b32 s67, s59, s63
	s_cselect_b32 s66, s78, s62
	s_cselect_b32 s65, s79, s82
	s_cselect_b32 s64, s80, s81
	v_lshl_add_u64 v[192:193], s[36:37], 0, v[168:169]
	s_add_i32 m0, s69, 0xc000
	ds_read_b128 v[78:81], v175
	ds_read_b128 v[86:89], v175 offset:1024
	ds_read_b128 v[90:93], v175 offset:2048
	ds_read_b128 v[94:97], v175 offset:3072
	ds_read_b128 v[176:179], v175 offset:4096
	ds_read_b128 v[180:183], v175 offset:5120
	ds_read_b128 v[184:187], v175 offset:6144
	ds_read_b128 v[188:191], v175 offset:7168
	global_load_lds_dwordx4 v[192:193], off
	v_lshl_add_u64 v[192:193], s[36:37], 0, v[166:167]
	s_add_i32 m0, s69, 0xe000
	s_nop 0
	global_load_lds_dwordx4 v[192:193], off
	s_waitcnt lgkmcnt(8)
	s_barrier
	s_waitcnt lgkmcnt(0)
	s_setprio 1
	s_waitcnt lgkmcnt(0)
	v_mfma_f32_16x16x32_bf16 v[158:161], v[58:61], v[78:81], v[158:161]
	v_mfma_f32_16x16x32_bf16 v[150:153], v[66:69], v[78:81], v[150:153]
	v_mfma_f32_16x16x32_bf16 v[142:145], v[58:61], v[90:93], v[142:145]
	v_mfma_f32_16x16x32_bf16 v[134:137], v[66:69], v[90:93], v[134:137]
	v_mfma_f32_16x16x32_bf16 v[126:129], v[58:61], v[176:179], v[126:129]
	v_mfma_f32_16x16x32_bf16 v[118:121], v[66:69], v[176:179], v[118:121]
	v_mfma_f32_16x16x32_bf16 v[110:113], v[58:61], v[184:187], v[110:113]
	v_mfma_f32_16x16x32_bf16 v[102:105], v[66:69], v[184:187], v[102:105]
	v_mfma_f32_16x16x32_bf16 v[158:161], v[62:65], v[86:89], v[158:161]
	v_mfma_f32_16x16x32_bf16 v[150:153], v[70:73], v[86:89], v[150:153]
	v_mfma_f32_16x16x32_bf16 v[142:145], v[62:65], v[94:97], v[142:145]
	v_mfma_f32_16x16x32_bf16 v[134:137], v[70:73], v[94:97], v[134:137]
	v_mfma_f32_16x16x32_bf16 v[126:129], v[62:65], v[180:183], v[126:129]
	v_mfma_f32_16x16x32_bf16 v[118:121], v[70:73], v[180:183], v[118:121]
	v_mfma_f32_16x16x32_bf16 v[110:113], v[62:65], v[188:191], v[110:113]
	v_mfma_f32_16x16x32_bf16 v[102:105], v[70:73], v[188:191], v[102:105]
	s_setprio 0
	s_barrier
	s_add_i32 s85, 0, 0x14000
	v_add_u32_e32 v192, s85, v170
	s_add_i32 s36, s84, s68
	ds_read_b128 v[200:203], v192
	ds_read_b128 v[204:207], v192 offset:1024
	ds_read_b128 v[208:211], v192 offset:2048
	ds_read_b128 v[222:225], v192 offset:3072
	v_lshl_add_u64 v[192:193], s[64:65], 0, v[164:165]
	s_mov_b32 m0, s36
	v_lshl_add_u64 v[214:215], s[64:65], 0, v[162:163]
	global_load_lds_dwordx4 v[192:193], off
	s_add_i32 m0, s36, 0x2000
	s_nop 0
	global_load_lds_dwordx4 v[214:215], off
	s_barrier
	s_waitcnt lgkmcnt(0)
	s_setprio 1
	s_waitcnt lgkmcnt(0)
	v_mfma_f32_16x16x32_bf16 v[154:157], v[200:203], v[78:81], v[154:157]
	v_mfma_f32_16x16x32_bf16 v[78:81], v[208:211], v[78:81], v[146:149]
	v_mfma_f32_16x16x32_bf16 v[154:157], v[204:207], v[86:89], v[154:157]
	v_mfma_f32_16x16x32_bf16 v[78:81], v[222:225], v[86:89], v[78:81]
	v_mfma_f32_16x16x32_bf16 v[86:89], v[200:203], v[90:93], v[138:141]
	v_mfma_f32_16x16x32_bf16 v[90:93], v[208:211], v[90:93], v[130:133]
	v_mfma_f32_16x16x32_bf16 v[114:117], v[208:211], v[176:179], v[114:117]
	v_mfma_f32_16x16x32_bf16 v[106:109], v[200:203], v[184:187], v[106:109]
	v_mfma_f32_16x16x32_bf16 v[98:101], v[208:211], v[184:187], v[98:101]
	v_mfma_f32_16x16x32_bf16 v[86:89], v[204:207], v[94:97], v[86:89]
	v_mfma_f32_16x16x32_bf16 v[90:93], v[222:225], v[94:97], v[90:93]
	v_mfma_f32_16x16x32_bf16 v[94:97], v[200:203], v[176:179], v[122:125]
	v_mfma_f32_16x16x32_bf16 v[114:117], v[222:225], v[180:183], v[114:117]
	v_mfma_f32_16x16x32_bf16 v[106:109], v[204:207], v[188:191], v[106:109]
	v_mfma_f32_16x16x32_bf16 v[98:101], v[222:225], v[188:191], v[98:101]
	v_mfma_f32_16x16x32_bf16 v[94:97], v[204:207], v[180:183], v[94:97]
	s_setprio 0
	s_mov_b32 m0, s69
	v_lshl_add_u64 v[234:235], s[66:67], 0, v[164:165]
	s_barrier
	ds_read_b128 v[122:125], v175 offset:16384
	ds_read_b128 v[130:133], v175 offset:17408
	ds_read_b128 v[138:141], v175 offset:18432
	ds_read_b128 v[146:149], v175 offset:19456
	ds_read_b128 v[176:179], v175 offset:20480
	ds_read_b128 v[180:183], v175 offset:21504
	ds_read_b128 v[184:187], v175 offset:22528
	ds_read_b128 v[188:191], v175 offset:23552
	global_load_lds_dwordx4 v[234:235], off
	v_lshl_add_u64 v[236:237], s[66:67], 0, v[162:163]
	s_mov_b32 m0, s70
	s_nop 0
	global_load_lds_dwordx4 v[236:237], off
	s_barrier
	s_waitcnt lgkmcnt(0)
	s_setprio 1
	s_waitcnt lgkmcnt(0)
	v_mfma_f32_16x16x32_bf16 v[82:85], v[58:61], v[122:125], v[82:85]
	v_mfma_f32_16x16x32_bf16 v[54:57], v[66:69], v[122:125], v[54:57]
	v_mfma_f32_16x16x32_bf16 v[46:49], v[58:61], v[138:141], v[46:49]
	v_mfma_f32_16x16x32_bf16 v[38:41], v[66:69], v[138:141], v[38:41]
	v_mfma_f32_16x16x32_bf16 v[30:33], v[58:61], v[176:179], v[30:33]
	v_mfma_f32_16x16x32_bf16 v[22:25], v[66:69], v[176:179], v[22:25]
	v_mfma_f32_16x16x32_bf16 v[14:17], v[58:61], v[184:187], v[14:17]
	v_mfma_f32_16x16x32_bf16 v[6:9], v[66:69], v[184:187], v[6:9]
	v_mfma_f32_16x16x32_bf16 v[82:85], v[62:65], v[130:133], v[82:85]
	v_mfma_f32_16x16x32_bf16 v[54:57], v[70:73], v[130:133], v[54:57]
	v_mfma_f32_16x16x32_bf16 v[46:49], v[62:65], v[146:149], v[46:49]
	v_mfma_f32_16x16x32_bf16 v[38:41], v[70:73], v[146:149], v[38:41]
	v_mfma_f32_16x16x32_bf16 v[30:33], v[62:65], v[180:183], v[30:33]
	v_mfma_f32_16x16x32_bf16 v[22:25], v[70:73], v[180:183], v[22:25]
	v_mfma_f32_16x16x32_bf16 v[14:17], v[62:65], v[188:191], v[14:17]
	v_mfma_f32_16x16x32_bf16 v[6:9], v[70:73], v[188:191], v[6:9]
	s_setprio 0
	s_barrier
	s_add_u32 s36, s64, 0x40000
	s_addc_u32 s37, s65, 0
	s_add_i32 s84, s85, s68
	v_lshl_add_u64 v[58:59], s[36:37], 0, v[164:165]
	s_mov_b32 m0, s84
	s_nop 0
	global_load_lds_dwordx4 v[58:59], off
	v_lshl_add_u64 v[58:59], s[36:37], 0, v[162:163]
	s_add_i32 m0, s84, 0x2000
	s_nop 0
	global_load_lds_dwordx4 v[58:59], off
	s_waitcnt vmcnt(6)
	s_barrier
	s_setprio 1
	v_mfma_f32_16x16x32_bf16 v[50:53], v[208:211], v[122:125], v[50:53]
	v_mfma_f32_16x16x32_bf16 v[42:45], v[200:203], v[138:141], v[42:45]
	v_mfma_f32_16x16x32_bf16 v[34:37], v[208:211], v[138:141], v[34:37]
	v_mfma_f32_16x16x32_bf16 v[26:29], v[200:203], v[176:179], v[26:29]
	v_mfma_f32_16x16x32_bf16 v[18:21], v[208:211], v[176:179], v[18:21]
	v_mfma_f32_16x16x32_bf16 v[10:13], v[200:203], v[184:187], v[10:13]
	v_mfma_f32_16x16x32_bf16 v[2:5], v[208:211], v[184:187], v[2:5]
	v_mfma_f32_16x16x32_bf16 v[58:61], v[200:203], v[122:125], v[74:77]
	v_mfma_f32_16x16x32_bf16 v[50:53], v[222:225], v[130:133], v[50:53]
	v_mfma_f32_16x16x32_bf16 v[42:45], v[204:207], v[146:149], v[42:45]
	v_mfma_f32_16x16x32_bf16 v[34:37], v[222:225], v[146:149], v[34:37]
	v_mfma_f32_16x16x32_bf16 v[26:29], v[204:207], v[180:183], v[26:29]
	v_mfma_f32_16x16x32_bf16 v[18:21], v[222:225], v[180:183], v[18:21]
	v_mfma_f32_16x16x32_bf16 v[10:13], v[204:207], v[188:191], v[10:13]
	v_mfma_f32_16x16x32_bf16 v[2:5], v[222:225], v[188:191], v[2:5]
	v_mfma_f32_16x16x32_bf16 v[58:61], v[204:207], v[130:133], v[58:61]
	s_setprio 0
	s_add_i32 s84, 0, 0x18000
	v_add_u32_e32 v74, s84, v170
	s_barrier
	ds_read_b128 v[62:65], v74
	ds_read_b128 v[66:69], v74 offset:1024
	ds_read_b128 v[70:73], v74 offset:2048
	ds_read_b128 v[74:77], v74 offset:3072
	s_add_u32 s36, s66, 0x40000
	s_addc_u32 s37, s67, 0
	s_mov_b32 m0, s71
	v_lshl_add_u64 v[138:139], s[36:37], 0, v[164:165]
	ds_read_b128 v[122:125], v175 offset:32768
	ds_read_b128 v[130:133], v175 offset:33792
	ds_read_b128 v[176:179], v175 offset:34816
	ds_read_b128 v[180:183], v175 offset:35840
	ds_read_b128 v[184:187], v175 offset:36864
	ds_read_b128 v[188:191], v175 offset:37888
	ds_read_b128 v[200:203], v175 offset:38912
	ds_read_b128 v[204:207], v175 offset:39936
	global_load_lds_dwordx4 v[138:139], off
	v_lshl_add_u64 v[138:139], s[36:37], 0, v[162:163]
	s_mov_b32 m0, s72
	s_nop 0
	global_load_lds_dwordx4 v[138:139], off
	s_waitcnt lgkmcnt(8)
	s_barrier
	s_waitcnt lgkmcnt(0)
	s_setprio 1
	s_waitcnt lgkmcnt(0)
	v_mfma_f32_16x16x32_bf16 v[138:141], v[62:65], v[122:125], v[158:161]
	v_mfma_f32_16x16x32_bf16 v[158:161], v[66:69], v[130:133], v[138:141]
	v_mfma_f32_16x16x32_bf16 v[138:141], v[70:73], v[122:125], v[150:153]
	v_mfma_f32_16x16x32_bf16 v[150:153], v[74:77], v[130:133], v[138:141]
	v_mfma_f32_16x16x32_bf16 v[138:141], v[62:65], v[176:179], v[142:145]
	v_mfma_f32_16x16x32_bf16 v[134:137], v[70:73], v[176:179], v[134:137]
	v_mfma_f32_16x16x32_bf16 v[126:129], v[62:65], v[184:187], v[126:129]
	v_mfma_f32_16x16x32_bf16 v[118:121], v[70:73], v[184:187], v[118:121]
	v_mfma_f32_16x16x32_bf16 v[110:113], v[62:65], v[200:203], v[110:113]
	v_mfma_f32_16x16x32_bf16 v[102:105], v[70:73], v[200:203], v[102:105]
	v_mfma_f32_16x16x32_bf16 v[142:145], v[66:69], v[180:183], v[138:141]
	v_mfma_f32_16x16x32_bf16 v[134:137], v[74:77], v[180:183], v[134:137]
	v_mfma_f32_16x16x32_bf16 v[126:129], v[66:69], v[188:191], v[126:129]
	v_mfma_f32_16x16x32_bf16 v[118:121], v[74:77], v[188:191], v[118:121]
	v_mfma_f32_16x16x32_bf16 v[110:113], v[66:69], v[204:207], v[110:113]
	v_mfma_f32_16x16x32_bf16 v[102:105], v[74:77], v[204:207], v[102:105]
	s_setprio 0
	s_barrier
	s_add_i32 s66, 0, 0x1c000
	v_add_u32_e32 v138, s66, v170
	s_add_i32 s36, s84, s68
	ds_read_b128 v[208:211], v138
	ds_read_b128 v[222:225], v138 offset:1024
	ds_read_b128 v[226:229], v138 offset:2048
	ds_read_b128 v[230:233], v138 offset:3072
	v_lshl_add_u64 v[138:139], v[192:193], 0, s[22:23]
	s_mov_b32 m0, s36
	s_nop 0
	global_load_lds_dwordx4 v[138:139], off
	v_lshl_add_u64 v[138:139], v[214:215], 0, s[22:23]
	s_add_i32 m0, s36, 0x2000
	s_nop 0
	global_load_lds_dwordx4 v[138:139], off
	s_barrier
	s_waitcnt lgkmcnt(0)
	s_setprio 1
	s_waitcnt lgkmcnt(0)
	v_mfma_f32_16x16x32_bf16 v[78:81], v[226:229], v[122:125], v[78:81]
	v_mfma_f32_16x16x32_bf16 v[138:141], v[208:211], v[122:125], v[154:157]
	v_mfma_f32_16x16x32_bf16 v[146:149], v[230:233], v[130:133], v[78:81]
	v_mfma_f32_16x16x32_bf16 v[78:81], v[208:211], v[176:179], v[86:89]
	v_mfma_f32_16x16x32_bf16 v[154:157], v[222:225], v[130:133], v[138:141]
	v_mfma_f32_16x16x32_bf16 v[138:141], v[222:225], v[180:183], v[78:81]
	v_mfma_f32_16x16x32_bf16 v[78:81], v[226:229], v[176:179], v[90:93]
	v_mfma_f32_16x16x32_bf16 v[130:133], v[230:233], v[180:183], v[78:81]
	v_mfma_f32_16x16x32_bf16 v[78:81], v[208:211], v[184:187], v[94:97]
	v_mfma_f32_16x16x32_bf16 v[122:125], v[222:225], v[188:191], v[78:81]
	v_mfma_f32_16x16x32_bf16 v[78:81], v[226:229], v[184:187], v[114:117]
	v_mfma_f32_16x16x32_bf16 v[114:117], v[230:233], v[188:191], v[78:81]
	v_mfma_f32_16x16x32_bf16 v[78:81], v[208:211], v[200:203], v[106:109]
	v_mfma_f32_16x16x32_bf16 v[106:109], v[222:225], v[204:207], v[78:81]
	v_mfma_f32_16x16x32_bf16 v[78:81], v[226:229], v[200:203], v[98:101]
	v_mfma_f32_16x16x32_bf16 v[98:101], v[230:233], v[204:207], v[78:81]
	s_setprio 0
	s_mov_b32 m0, s73
	v_lshl_add_u64 v[192:193], v[234:235], 0, s[22:23]
	s_barrier
	s_nop 2
	ds_read_b128 v[78:81], v175 offset:49152
	ds_read_b128 v[86:89], v175 offset:50176
	ds_read_b128 v[90:93], v175 offset:51200
	ds_read_b128 v[94:97], v175 offset:52224
	ds_read_b128 v[176:179], v175 offset:53248
	ds_read_b128 v[180:183], v175 offset:54272
	ds_read_b128 v[184:187], v175 offset:55296
	ds_read_b128 v[188:191], v175 offset:56320
	global_load_lds_dwordx4 v[192:193], off
	v_lshl_add_u64 v[192:193], v[236:237], 0, s[22:23]
	s_mov_b32 m0, s75
	s_nop 0
	global_load_lds_dwordx4 v[192:193], off
	s_barrier
	s_waitcnt lgkmcnt(0)
	s_setprio 1
	s_waitcnt lgkmcnt(0)
	v_mfma_f32_16x16x32_bf16 v[82:85], v[62:65], v[78:81], v[82:85]
	v_mfma_f32_16x16x32_bf16 v[54:57], v[70:73], v[78:81], v[54:57]
	v_mfma_f32_16x16x32_bf16 v[46:49], v[62:65], v[90:93], v[46:49]
	v_mfma_f32_16x16x32_bf16 v[38:41], v[70:73], v[90:93], v[38:41]
	v_mfma_f32_16x16x32_bf16 v[30:33], v[62:65], v[176:179], v[30:33]
	v_mfma_f32_16x16x32_bf16 v[22:25], v[70:73], v[176:179], v[22:25]
	v_mfma_f32_16x16x32_bf16 v[14:17], v[62:65], v[184:187], v[14:17]
	v_mfma_f32_16x16x32_bf16 v[6:9], v[70:73], v[184:187], v[6:9]
	v_mfma_f32_16x16x32_bf16 v[82:85], v[66:69], v[86:89], v[82:85]
	v_mfma_f32_16x16x32_bf16 v[54:57], v[74:77], v[86:89], v[54:57]
	v_mfma_f32_16x16x32_bf16 v[46:49], v[66:69], v[94:97], v[46:49]
	v_mfma_f32_16x16x32_bf16 v[38:41], v[74:77], v[94:97], v[38:41]
	v_mfma_f32_16x16x32_bf16 v[30:33], v[66:69], v[180:183], v[30:33]
	v_mfma_f32_16x16x32_bf16 v[22:25], v[74:77], v[180:183], v[22:25]
	v_mfma_f32_16x16x32_bf16 v[14:17], v[66:69], v[188:191], v[14:17]
	v_mfma_f32_16x16x32_bf16 v[6:9], v[74:77], v[188:191], v[6:9]
	s_setprio 0
	s_barrier
	s_add_u32 s36, s64, 0x40080
	s_addc_u32 s37, s65, 0
	s_add_i32 s64, s66, s68
	v_lshl_add_u64 v[62:63], s[36:37], 0, v[164:165]
	s_mov_b32 m0, s64
	s_nop 0
	global_load_lds_dwordx4 v[62:63], off
	v_lshl_add_u64 v[62:63], s[36:37], 0, v[162:163]
	s_add_i32 m0, s64, 0x2000
	s_nop 0
	global_load_lds_dwordx4 v[62:63], off
	s_waitcnt vmcnt(6)
	s_barrier
	s_setprio 1
	v_mfma_f32_16x16x32_bf16 v[58:61], v[208:211], v[78:81], v[58:61]
	v_mfma_f32_16x16x32_bf16 v[50:53], v[226:229], v[78:81], v[50:53]
	v_mfma_f32_16x16x32_bf16 v[42:45], v[208:211], v[90:93], v[42:45]
	v_mfma_f32_16x16x32_bf16 v[34:37], v[226:229], v[90:93], v[34:37]
	v_mfma_f32_16x16x32_bf16 v[26:29], v[208:211], v[176:179], v[26:29]
	v_mfma_f32_16x16x32_bf16 v[18:21], v[226:229], v[176:179], v[18:21]
	v_mfma_f32_16x16x32_bf16 v[10:13], v[208:211], v[184:187], v[10:13]
	v_mfma_f32_16x16x32_bf16 v[2:5], v[226:229], v[184:187], v[2:5]
	v_mfma_f32_16x16x32_bf16 v[74:77], v[222:225], v[86:89], v[58:61]
	v_mfma_f32_16x16x32_bf16 v[50:53], v[230:233], v[86:89], v[50:53]
	v_mfma_f32_16x16x32_bf16 v[42:45], v[222:225], v[94:97], v[42:45]
	v_mfma_f32_16x16x32_bf16 v[34:37], v[230:233], v[94:97], v[34:37]
	v_mfma_f32_16x16x32_bf16 v[26:29], v[222:225], v[180:183], v[26:29]
	v_mfma_f32_16x16x32_bf16 v[18:21], v[230:233], v[180:183], v[18:21]
	v_mfma_f32_16x16x32_bf16 v[10:13], v[222:225], v[188:191], v[10:13]
	v_mfma_f32_16x16x32_bf16 v[2:5], v[230:233], v[188:191], v[2:5]
	s_setprio 0
	s_add_i32 s83, s83, 2
	s_add_u32 s81, s81, 0x100
	s_addc_u32 s82, s82, 0
	s_cmp_gt_u32 s83, 13
	s_mov_b64 s[36:37], s[62:63]
	s_barrier
	s_cbranch_scc0 .LBB0_1099
	s_and_b64 vcc, exec, s[60:61]
	s_cbranch_vccnz .Lpk2_nonext
	v_lshl_add_u64 v[246:247], s[56:57], 0, v[168:169]
	s_add_i32 m0, s69, 0xc000
	s_nop 0
	global_load_lds_dwordx4 v[246:247], off
	v_lshl_add_u64 v[248:249], s[56:57], 0, v[166:167]
	s_add_i32 m0, s69, 0xe000
	s_nop 0
	global_load_lds_dwordx4 v[248:249], off
.Lpk2_nonext:
	v_lshl_or_b32 v58, s27, 8, v174
	v_mov_b32_e32 v177, v1
	v_ashrrev_i32_e32 v59, 31, v58
	v_lshlrev_b64 v[58:59], 2, v[58:59]
	v_lshl_add_u64 v[66:67], s[46:47], 0, v[58:59]
	v_lshl_add_u64 v[70:71], s[48:49], 0, v[58:59]
	flat_load_dwordx4 v[86:89], v[66:67]
	flat_load_dwordx4 v[78:81], v[70:71]
	flat_load_dwordx4 v[62:65], v[66:67] offset:16
	flat_load_dwordx4 v[58:61], v[70:71] offset:16
	flat_load_dwordx4 v[94:97], v[66:67] offset:512
	flat_load_dwordx4 v[90:93], v[70:71] offset:512
	s_nop 0
	flat_load_dwordx4 v[66:69], v[66:67] offset:528
	s_nop 0
	flat_load_dwordx4 v[70:73], v[70:71] offset:528
	s_lshl_b32 s3, s3, 8
	v_lshl_or_b32 v176, s27, 7, v174
	v_add_u32_e32 v184, s3, v177
	v_lshl_add_u32 v177, v177, 3, s33
	s_waitcnt vmcnt(0)
	ds_read_b64 v[178:179], v177
	s_movk_i32 s27, 0xb00
	s_and_b64 vcc, exec, s[60:61]
	s_waitcnt lgkmcnt(0)
	v_xor_b32_e32 v89, 0x80000000, v89
	v_xor_b32_e32 v88, 0x80000000, v88
	v_pk_fma_f32 v[160:161], v[88:89], v[178:179], v[160:161] op_sel_hi:[1,0,1]
	v_pk_fma_f32 v[158:159], v[86:87], v[178:179], v[158:159] op_sel_hi:[1,0,1] neg_lo:[1,0,0] neg_hi:[1,0,0]
	v_pk_fma_f32 v[160:161], v[178:179], v[160:161], v[80:81] op_sel:[1,0,0]
	v_pk_fma_f32 v[158:159], v[178:179], v[158:159], v[78:79] op_sel:[1,0,0]
	v_pk_fma_f32 v[154:155], v[94:95], v[178:179], v[154:155] op_sel_hi:[1,0,1] neg_lo:[1,0,0] neg_hi:[1,0,0]
	v_mul_f32_e32 v182, 0xbfb8aa3b, v160
	v_pk_fma_f32 v[180:181], v[178:179], v[154:155], v[90:91] op_sel:[1,0,0]
	v_mul_f32_e32 v154, 0xbfb8aa3b, v158
	v_mul_f32_e32 v155, 0xbfb8aa3b, v159
	v_mul_f32_e32 v183, 0xbfb8aa3b, v161
	v_exp_f32_e32 v154, v154
	v_exp_f32_e32 v155, v155
	v_exp_f32_e32 v182, v182
	v_exp_f32_e32 v183, v183
	v_add_f32_e32 v154, 1.0, v154
	v_add_f32_e32 v155, 1.0, v155
	v_add_f32_e32 v182, 1.0, v182
	v_add_f32_e32 v183, 1.0, v183
	v_rcp_f32_e32 v154, v154
	v_rcp_f32_e32 v155, v155
	v_rcp_f32_e32 v182, v182
	v_rcp_f32_e32 v183, v183
	v_xor_b32_e32 v97, 0x80000000, v97
	v_xor_b32_e32 v96, 0x80000000, v96
	v_xor_b32_e32 v65, 0x80000000, v65
	v_xor_b32_e32 v64, 0x80000000, v64
	v_pk_fma_f32 v[156:157], v[96:97], v[178:179], v[156:157] op_sel_hi:[1,0,1]
	v_pk_fma_f32 v[152:153], v[64:65], v[178:179], v[152:153] op_sel_hi:[1,0,1]
	v_pk_fma_f32 v[150:151], v[62:63], v[178:179], v[150:151] op_sel_hi:[1,0,1] neg_lo:[1,0,0] neg_hi:[1,0,0]
	v_pk_fma_f32 v[156:157], v[178:179], v[156:157], v[92:93] op_sel:[1,0,0]
	v_pk_mul_f32 v[160:161], v[160:161], v[182:183]
	v_pk_mul_f32 v[158:159], v[158:159], v[154:155]
	v_pk_fma_f32 v[152:153], v[178:179], v[152:153], v[60:61] op_sel:[1,0,0]
	v_pk_fma_f32 v[150:151], v[178:179], v[150:151], v[58:59] op_sel:[1,0,0]
	v_pk_mul_f32 v[154:155], v[156:157], v[160:161]
	v_pk_mul_f32 v[156:157], v[180:181], v[158:159]
	v_mul_f32_e32 v158, 0xbfb8aa3b, v150
	v_mul_f32_e32 v159, 0xbfb8aa3b, v151
	v_mul_f32_e32 v160, 0xbfb8aa3b, v152
	v_mul_f32_e32 v161, 0xbfb8aa3b, v153
	v_exp_f32_e32 v158, v158
	v_exp_f32_e32 v159, v159
	v_exp_f32_e32 v160, v160
	v_exp_f32_e32 v161, v161
	v_add_f32_e32 v158, 1.0, v158
	v_add_f32_e32 v159, 1.0, v159
	v_add_f32_e32 v160, 1.0, v160
	v_add_f32_e32 v161, 1.0, v161
	v_rcp_f32_e32 v158, v158
	v_rcp_f32_e32 v159, v159
	v_rcp_f32_e32 v160, v160
	v_rcp_f32_e32 v161, v161
	v_xor_b32_e32 v69, 0x80000000, v69
	v_xor_b32_e32 v68, 0x80000000, v68
	v_pk_fma_f32 v[148:149], v[68:69], v[178:179], v[148:149] op_sel_hi:[1,0,1]
	v_pk_fma_f32 v[146:147], v[66:67], v[178:179], v[146:147] op_sel_hi:[1,0,1] neg_lo:[1,0,0] neg_hi:[1,0,0]
	v_pk_fma_f32 v[148:149], v[178:179], v[148:149], v[72:73] op_sel:[1,0,0]
	v_pk_fma_f32 v[146:147], v[178:179], v[146:147], v[70:71] op_sel:[1,0,0]
	v_pk_mul_f32 v[152:153], v[152:153], v[160:161]
	v_pk_mul_f32 v[150:151], v[150:151], v[158:159]
	v_mul_lo_u32 v158, v184, s27
	v_pk_mul_f32 v[152:153], v[148:149], v[152:153]
	v_pk_mul_f32 v[148:149], v[146:147], v[150:151]
	v_add_lshl_u32 v150, v158, v176, 1
	v_cvt_pk_bf16_f32 v146, v156, v157
	v_cvt_pk_bf16_f32 v147, v154, v155
	v_cvt_pk_bf16_f32 v148, v148, v149
	v_cvt_pk_bf16_f32 v149, v152, v153
	buffer_store_dwordx4 v[146:149], v150, s[28:31], 0 offen sc1
	ds_read_b64 v[146:147], v177 offset:128
	s_waitcnt lgkmcnt(0)
	v_pk_fma_f32 v[142:143], v[86:87], v[146:147], v[142:143] op_sel_hi:[1,0,1] neg_lo:[1,0,0] neg_hi:[1,0,0]
	s_nop 0
	v_pk_fma_f32 v[142:143], v[146:147], v[142:143], v[78:79] op_sel:[1,0,0]
	v_pk_fma_f32 v[144:145], v[88:89], v[146:147], v[144:145] op_sel_hi:[1,0,1]
	v_mul_f32_e32 v148, 0xbfb8aa3b, v142
	v_mul_f32_e32 v149, 0xbfb8aa3b, v143
	v_pk_fma_f32 v[144:145], v[146:147], v[144:145], v[80:81] op_sel:[1,0,0]
	v_exp_f32_e32 v148, v148
	v_exp_f32_e32 v149, v149
	v_mul_f32_e32 v150, 0xbfb8aa3b, v144
	v_mul_f32_e32 v151, 0xbfb8aa3b, v145
	v_exp_f32_e32 v150, v150
	v_exp_f32_e32 v151, v151
	v_add_f32_e32 v148, 1.0, v148
	v_add_f32_e32 v149, 1.0, v149
	v_rcp_f32_e32 v148, v148
	v_rcp_f32_e32 v149, v149
	v_add_f32_e32 v150, 1.0, v150
	v_add_f32_e32 v151, 1.0, v151
	v_rcp_f32_e32 v150, v150
	v_rcp_f32_e32 v151, v151
	v_pk_fma_f32 v[138:139], v[94:95], v[146:147], v[138:139] op_sel_hi:[1,0,1] neg_lo:[1,0,0] neg_hi:[1,0,0]
	v_pk_fma_f32 v[134:135], v[62:63], v[146:147], v[134:135] op_sel_hi:[1,0,1] neg_lo:[1,0,0] neg_hi:[1,0,0]
	v_pk_fma_f32 v[138:139], v[146:147], v[138:139], v[90:91] op_sel:[1,0,0]
	v_pk_mul_f32 v[142:143], v[142:143], v[148:149]
	v_pk_fma_f32 v[134:135], v[146:147], v[134:135], v[58:59] op_sel:[1,0,0]
	v_pk_fma_f32 v[140:141], v[96:97], v[146:147], v[140:141] op_sel_hi:[1,0,1]
	v_pk_mul_f32 v[138:139], v[138:139], v[142:143]
	v_pk_fma_f32 v[136:137], v[64:65], v[146:147], v[136:137] op_sel_hi:[1,0,1]
	v_mul_f32_e32 v142, 0xbfb8aa3b, v134
	v_mul_f32_e32 v143, 0xbfb8aa3b, v135
	v_pk_fma_f32 v[140:141], v[146:147], v[140:141], v[92:93] op_sel:[1,0,0]
	v_pk_mul_f32 v[144:145], v[144:145], v[150:151]
	v_pk_fma_f32 v[136:137], v[146:147], v[136:137], v[60:61] op_sel:[1,0,0]
	v_exp_f32_e32 v142, v142
	v_exp_f32_e32 v143, v143
	v_pk_mul_f32 v[140:141], v[140:141], v[144:145]
	v_mul_f32_e32 v144, 0xbfb8aa3b, v136
	v_mul_f32_e32 v145, 0xbfb8aa3b, v137
	v_exp_f32_e32 v144, v144
	v_exp_f32_e32 v145, v145
	v_add_f32_e32 v142, 1.0, v142
	v_add_f32_e32 v143, 1.0, v143
	v_rcp_f32_e32 v142, v142
	v_rcp_f32_e32 v143, v143
	v_add_f32_e32 v144, 1.0, v144
	v_add_f32_e32 v145, 1.0, v145
	v_rcp_f32_e32 v144, v144
	v_rcp_f32_e32 v145, v145
	v_pk_fma_f32 v[130:131], v[66:67], v[146:147], v[130:131] op_sel_hi:[1,0,1] neg_lo:[1,0,0] neg_hi:[1,0,0]
	v_pk_mul_f32 v[134:135], v[134:135], v[142:143]
	v_pk_fma_f32 v[130:131], v[146:147], v[130:131], v[70:71] op_sel:[1,0,0]
	v_pk_fma_f32 v[132:133], v[68:69], v[146:147], v[132:133] op_sel_hi:[1,0,1]
	v_pk_mul_f32 v[134:135], v[130:131], v[134:135]
	v_add_u32_e32 v130, 0xb000, v176
	v_pk_fma_f32 v[132:133], v[146:147], v[132:133], v[72:73] op_sel:[1,0,0]
	v_pk_mul_f32 v[136:137], v[136:137], v[144:145]
	v_add_lshl_u32 v131, v158, v130, 1
	v_pk_mul_f32 v[136:137], v[132:133], v[136:137]
	v_cvt_pk_bf16_f32 v132, v138, v139
	v_cvt_pk_bf16_f32 v133, v140, v141
	v_cvt_pk_bf16_f32 v134, v134, v135
	s_nop 0
	v_cvt_pk_bf16_f32 v135, v136, v137
	buffer_store_dwordx4 v[132:135], v131, s[28:31], 0 offen sc1
	v_mov_b32_e32 v131, v171
	s_nop 0
	v_add_u32_e32 v138, s3, v131
	v_lshl_add_u32 v131, v131, 3, s33
	ds_read_b64 v[132:133], v131
	s_waitcnt lgkmcnt(0)
	v_pk_fma_f32 v[128:129], v[88:89], v[132:133], v[128:129] op_sel_hi:[1,0,1]
	v_pk_fma_f32 v[126:127], v[86:87], v[132:133], v[126:127] op_sel_hi:[1,0,1] neg_lo:[1,0,0] neg_hi:[1,0,0]
	v_pk_fma_f32 v[128:129], v[132:133], v[128:129], v[80:81] op_sel:[1,0,0]
	v_pk_fma_f32 v[126:127], v[132:133], v[126:127], v[78:79] op_sel:[1,0,0]
	v_mul_f32_e32 v136, 0xbfb8aa3b, v128
	v_mul_f32_e32 v134, 0xbfb8aa3b, v126
	v_mul_f32_e32 v135, 0xbfb8aa3b, v127
	v_mul_f32_e32 v137, 0xbfb8aa3b, v129
	v_exp_f32_e32 v134, v134
	v_exp_f32_e32 v135, v135
	v_exp_f32_e32 v136, v136
	v_exp_f32_e32 v137, v137
	v_add_f32_e32 v134, 1.0, v134
	v_add_f32_e32 v135, 1.0, v135
	v_add_f32_e32 v136, 1.0, v136
	v_add_f32_e32 v137, 1.0, v137
	v_rcp_f32_e32 v134, v134
	v_rcp_f32_e32 v135, v135
	v_rcp_f32_e32 v136, v136
	v_rcp_f32_e32 v137, v137
	v_pk_fma_f32 v[124:125], v[96:97], v[132:133], v[124:125] op_sel_hi:[1,0,1]
	v_pk_fma_f32 v[122:123], v[94:95], v[132:133], v[122:123] op_sel_hi:[1,0,1] neg_lo:[1,0,0] neg_hi:[1,0,0]
	v_pk_fma_f32 v[120:121], v[64:65], v[132:133], v[120:121] op_sel_hi:[1,0,1]
	v_pk_fma_f32 v[118:119], v[62:63], v[132:133], v[118:119] op_sel_hi:[1,0,1] neg_lo:[1,0,0] neg_hi:[1,0,0]
	v_pk_fma_f32 v[124:125], v[132:133], v[124:125], v[92:93] op_sel:[1,0,0]
	v_pk_fma_f32 v[122:123], v[132:133], v[122:123], v[90:91] op_sel:[1,0,0]
	v_pk_mul_f32 v[128:129], v[128:129], v[136:137]
	v_pk_mul_f32 v[126:127], v[126:127], v[134:135]
	v_pk_fma_f32 v[120:121], v[132:133], v[120:121], v[60:61] op_sel:[1,0,0]
	v_pk_fma_f32 v[118:119], v[132:133], v[118:119], v[58:59] op_sel:[1,0,0]
	v_pk_mul_f32 v[124:125], v[124:125], v[128:129]
	v_pk_mul_f32 v[122:123], v[122:123], v[126:127]
	v_mul_f32_e32 v126, 0xbfb8aa3b, v118
	v_mul_f32_e32 v127, 0xbfb8aa3b, v119
	v_mul_f32_e32 v128, 0xbfb8aa3b, v120
	v_mul_f32_e32 v129, 0xbfb8aa3b, v121
	v_exp_f32_e32 v126, v126
	v_exp_f32_e32 v127, v127
	v_exp_f32_e32 v128, v128
	v_exp_f32_e32 v129, v129
	v_add_f32_e32 v126, 1.0, v126
	v_add_f32_e32 v127, 1.0, v127
	v_add_f32_e32 v128, 1.0, v128
	v_add_f32_e32 v129, 1.0, v129
	v_rcp_f32_e32 v126, v126
	v_rcp_f32_e32 v127, v127
	v_rcp_f32_e32 v128, v128
	v_rcp_f32_e32 v129, v129
	v_pk_fma_f32 v[116:117], v[68:69], v[132:133], v[116:117] op_sel_hi:[1,0,1]
	v_pk_fma_f32 v[114:115], v[66:67], v[132:133], v[114:115] op_sel_hi:[1,0,1] neg_lo:[1,0,0] neg_hi:[1,0,0]
	v_pk_fma_f32 v[116:117], v[132:133], v[116:117], v[72:73] op_sel:[1,0,0]
	v_pk_fma_f32 v[114:115], v[132:133], v[114:115], v[70:71] op_sel:[1,0,0]
	v_pk_mul_f32 v[120:121], v[120:121], v[128:129]
	v_pk_mul_f32 v[118:119], v[118:119], v[126:127]
	v_mul_lo_u32 v126, v138, s27
	v_pk_mul_f32 v[120:121], v[116:117], v[120:121]
	v_pk_mul_f32 v[116:117], v[114:115], v[118:119]
	v_add_lshl_u32 v118, v126, v176, 1
	v_cvt_pk_bf16_f32 v114, v122, v123
	v_cvt_pk_bf16_f32 v115, v124, v125
	v_cvt_pk_bf16_f32 v116, v116, v117
	v_cvt_pk_bf16_f32 v117, v120, v121
	buffer_store_dwordx4 v[114:117], v118, s[28:31], 0 offen sc1
	ds_read_b64 v[114:115], v131 offset:128
	s_waitcnt lgkmcnt(0)
	v_pk_fma_f32 v[112:113], v[88:89], v[114:115], v[112:113] op_sel_hi:[1,0,1]
	v_pk_fma_f32 v[110:111], v[86:87], v[114:115], v[110:111] op_sel_hi:[1,0,1] neg_lo:[1,0,0] neg_hi:[1,0,0]
	v_pk_fma_f32 v[112:113], v[114:115], v[112:113], v[80:81] op_sel:[1,0,0]
	v_pk_fma_f32 v[110:111], v[114:115], v[110:111], v[78:79] op_sel:[1,0,0]
	v_mul_f32_e32 v118, 0xbfb8aa3b, v112
	v_mul_f32_e32 v116, 0xbfb8aa3b, v110
	v_mul_f32_e32 v117, 0xbfb8aa3b, v111
	v_mul_f32_e32 v119, 0xbfb8aa3b, v113
	v_exp_f32_e32 v116, v116
	v_exp_f32_e32 v117, v117
	v_exp_f32_e32 v118, v118
	v_exp_f32_e32 v119, v119
	v_add_f32_e32 v116, 1.0, v116
	v_add_f32_e32 v117, 1.0, v117
	v_add_f32_e32 v118, 1.0, v118
	v_add_f32_e32 v119, 1.0, v119
	v_rcp_f32_e32 v116, v116
	v_rcp_f32_e32 v117, v117
	v_rcp_f32_e32 v118, v118
	v_rcp_f32_e32 v119, v119
	v_pk_fma_f32 v[108:109], v[96:97], v[114:115], v[108:109] op_sel_hi:[1,0,1]
	v_pk_fma_f32 v[106:107], v[94:95], v[114:115], v[106:107] op_sel_hi:[1,0,1] neg_lo:[1,0,0] neg_hi:[1,0,0]
	v_pk_fma_f32 v[104:105], v[64:65], v[114:115], v[104:105] op_sel_hi:[1,0,1]
	v_pk_fma_f32 v[102:103], v[62:63], v[114:115], v[102:103] op_sel_hi:[1,0,1] neg_lo:[1,0,0] neg_hi:[1,0,0]
	v_pk_fma_f32 v[108:109], v[114:115], v[108:109], v[92:93] op_sel:[1,0,0]
	v_pk_fma_f32 v[106:107], v[114:115], v[106:107], v[90:91] op_sel:[1,0,0]
	v_pk_mul_f32 v[112:113], v[112:113], v[118:119]
	v_pk_mul_f32 v[110:111], v[110:111], v[116:117]
	v_pk_fma_f32 v[104:105], v[114:115], v[104:105], v[60:61] op_sel:[1,0,0]
	v_pk_fma_f32 v[102:103], v[114:115], v[102:103], v[58:59] op_sel:[1,0,0]
	v_pk_mul_f32 v[108:109], v[108:109], v[112:113]
	v_pk_mul_f32 v[106:107], v[106:107], v[110:111]
	v_mul_f32_e32 v110, 0xbfb8aa3b, v102
	v_mul_f32_e32 v111, 0xbfb8aa3b, v103
	v_mul_f32_e32 v112, 0xbfb8aa3b, v104
	v_mul_f32_e32 v113, 0xbfb8aa3b, v105
	v_exp_f32_e32 v110, v110
	v_exp_f32_e32 v111, v111
	v_exp_f32_e32 v112, v112
	v_exp_f32_e32 v113, v113
	v_add_f32_e32 v110, 1.0, v110
	v_add_f32_e32 v111, 1.0, v111
	v_add_f32_e32 v112, 1.0, v112
	v_add_f32_e32 v113, 1.0, v113
	v_rcp_f32_e32 v110, v110
	v_rcp_f32_e32 v111, v111
	v_rcp_f32_e32 v112, v112
	v_rcp_f32_e32 v113, v113
	v_pk_fma_f32 v[100:101], v[68:69], v[114:115], v[100:101] op_sel_hi:[1,0,1]
	v_pk_fma_f32 v[98:99], v[66:67], v[114:115], v[98:99] op_sel_hi:[1,0,1] neg_lo:[1,0,0] neg_hi:[1,0,0]
	v_pk_fma_f32 v[100:101], v[114:115], v[100:101], v[72:73] op_sel:[1,0,0]
	v_pk_fma_f32 v[98:99], v[114:115], v[98:99], v[70:71] op_sel:[1,0,0]
	v_pk_mul_f32 v[104:105], v[104:105], v[112:113]
	v_pk_mul_f32 v[102:103], v[102:103], v[110:111]
	v_pk_mul_f32 v[104:105], v[100:101], v[104:105]
	v_pk_mul_f32 v[100:101], v[98:99], v[102:103]
	v_add_lshl_u32 v102, v126, v130, 1
	v_cvt_pk_bf16_f32 v98, v106, v107
	v_cvt_pk_bf16_f32 v99, v108, v109
	v_cvt_pk_bf16_f32 v100, v100, v101
	v_cvt_pk_bf16_f32 v101, v104, v105
	buffer_store_dwordx4 v[98:101], v102, s[28:31], 0 offen sc1
	s_nop 1
	v_mov_b32_e32 v98, v172
	s_nop 0
	v_lshl_add_u32 v105, v98, 3, s33
	v_add_u32_e32 v104, s3, v98
	ds_read_b64 v[98:99], v105
	s_waitcnt lgkmcnt(0)
	v_pk_fma_f32 v[84:85], v[88:89], v[98:99], v[84:85] op_sel_hi:[1,0,1]
	v_pk_fma_f32 v[82:83], v[86:87], v[98:99], v[82:83] op_sel_hi:[1,0,1] neg_lo:[1,0,0] neg_hi:[1,0,0]
	v_pk_fma_f32 v[84:85], v[98:99], v[84:85], v[80:81] op_sel:[1,0,0]
	v_pk_fma_f32 v[82:83], v[98:99], v[82:83], v[78:79] op_sel:[1,0,0]
	v_mul_f32_e32 v102, 0xbfb8aa3b, v84
	v_mul_f32_e32 v100, 0xbfb8aa3b, v82
	v_mul_f32_e32 v101, 0xbfb8aa3b, v83
	v_mul_f32_e32 v103, 0xbfb8aa3b, v85
	v_exp_f32_e32 v100, v100
	v_exp_f32_e32 v101, v101
	v_exp_f32_e32 v102, v102
	v_exp_f32_e32 v103, v103
	v_add_f32_e32 v100, 1.0, v100
	v_add_f32_e32 v101, 1.0, v101
	v_add_f32_e32 v102, 1.0, v102
	v_add_f32_e32 v103, 1.0, v103
	v_rcp_f32_e32 v100, v100
	v_rcp_f32_e32 v101, v101
	v_rcp_f32_e32 v102, v102
	v_rcp_f32_e32 v103, v103
	v_pk_fma_f32 v[76:77], v[96:97], v[98:99], v[76:77] op_sel_hi:[1,0,1]
	v_pk_fma_f32 v[74:75], v[94:95], v[98:99], v[74:75] op_sel_hi:[1,0,1] neg_lo:[1,0,0] neg_hi:[1,0,0]
	v_pk_fma_f32 v[56:57], v[64:65], v[98:99], v[56:57] op_sel_hi:[1,0,1]
	v_pk_fma_f32 v[54:55], v[62:63], v[98:99], v[54:55] op_sel_hi:[1,0,1] neg_lo:[1,0,0] neg_hi:[1,0,0]
	v_pk_fma_f32 v[76:77], v[98:99], v[76:77], v[92:93] op_sel:[1,0,0]
	v_pk_fma_f32 v[74:75], v[98:99], v[74:75], v[90:91] op_sel:[1,0,0]
	v_pk_mul_f32 v[84:85], v[84:85], v[102:103]
	v_pk_mul_f32 v[82:83], v[82:83], v[100:101]
	v_pk_fma_f32 v[56:57], v[98:99], v[56:57], v[60:61] op_sel:[1,0,0]
	v_pk_fma_f32 v[54:55], v[98:99], v[54:55], v[58:59] op_sel:[1,0,0]
	v_pk_mul_f32 v[76:77], v[76:77], v[84:85]
	v_pk_mul_f32 v[74:75], v[74:75], v[82:83]
	v_mul_f32_e32 v82, 0xbfb8aa3b, v54
	v_mul_f32_e32 v83, 0xbfb8aa3b, v55
	v_mul_f32_e32 v84, 0xbfb8aa3b, v56
	v_mul_f32_e32 v85, 0xbfb8aa3b, v57
	v_exp_f32_e32 v82, v82
	v_exp_f32_e32 v83, v83
	v_exp_f32_e32 v84, v84
	v_exp_f32_e32 v85, v85
	v_add_f32_e32 v82, 1.0, v82
	v_add_f32_e32 v83, 1.0, v83
	v_add_f32_e32 v84, 1.0, v84
	v_add_f32_e32 v85, 1.0, v85
	v_rcp_f32_e32 v82, v82
	v_rcp_f32_e32 v83, v83
	v_rcp_f32_e32 v84, v84
	v_rcp_f32_e32 v85, v85
	v_pk_fma_f32 v[52:53], v[68:69], v[98:99], v[52:53] op_sel_hi:[1,0,1]
	v_pk_fma_f32 v[50:51], v[66:67], v[98:99], v[50:51] op_sel_hi:[1,0,1] neg_lo:[1,0,0] neg_hi:[1,0,0]
	v_pk_fma_f32 v[52:53], v[98:99], v[52:53], v[72:73] op_sel:[1,0,0]
	v_pk_fma_f32 v[50:51], v[98:99], v[50:51], v[70:71] op_sel:[1,0,0]
	v_pk_mul_f32 v[56:57], v[56:57], v[84:85]
	v_pk_mul_f32 v[54:55], v[54:55], v[82:83]
	v_mul_lo_u32 v82, v104, s27
	v_pk_mul_f32 v[56:57], v[52:53], v[56:57]
	v_pk_mul_f32 v[52:53], v[50:51], v[54:55]
	v_add_lshl_u32 v54, v82, v176, 1
	v_cvt_pk_bf16_f32 v50, v74, v75
	v_cvt_pk_bf16_f32 v51, v76, v77
	v_cvt_pk_bf16_f32 v52, v52, v53
	v_cvt_pk_bf16_f32 v53, v56, v57
	buffer_store_dwordx4 v[50:53], v54, s[28:31], 0 offen sc1
	ds_read_b64 v[50:51], v105 offset:128
	s_waitcnt lgkmcnt(0)
	v_pk_fma_f32 v[48:49], v[88:89], v[50:51], v[48:49] op_sel_hi:[1,0,1]
	v_pk_fma_f32 v[46:47], v[86:87], v[50:51], v[46:47] op_sel_hi:[1,0,1] neg_lo:[1,0,0] neg_hi:[1,0,0]
	v_pk_fma_f32 v[48:49], v[50:51], v[48:49], v[80:81] op_sel:[1,0,0]
	v_pk_fma_f32 v[46:47], v[50:51], v[46:47], v[78:79] op_sel:[1,0,0]
	v_mul_f32_e32 v54, 0xbfb8aa3b, v48
	v_mul_f32_e32 v52, 0xbfb8aa3b, v46
	v_mul_f32_e32 v53, 0xbfb8aa3b, v47
	v_mul_f32_e32 v55, 0xbfb8aa3b, v49
	v_exp_f32_e32 v52, v52
	v_exp_f32_e32 v53, v53
	v_exp_f32_e32 v54, v54
	v_exp_f32_e32 v55, v55
	v_add_f32_e32 v52, 1.0, v52
	v_add_f32_e32 v53, 1.0, v53
	v_add_f32_e32 v54, 1.0, v54
	v_add_f32_e32 v55, 1.0, v55
	v_rcp_f32_e32 v52, v52
	v_rcp_f32_e32 v53, v53
	v_rcp_f32_e32 v54, v54
	v_rcp_f32_e32 v55, v55
	v_pk_fma_f32 v[44:45], v[96:97], v[50:51], v[44:45] op_sel_hi:[1,0,1]
	v_pk_fma_f32 v[42:43], v[94:95], v[50:51], v[42:43] op_sel_hi:[1,0,1] neg_lo:[1,0,0] neg_hi:[1,0,0]
	v_pk_fma_f32 v[40:41], v[64:65], v[50:51], v[40:41] op_sel_hi:[1,0,1]
	v_pk_fma_f32 v[38:39], v[62:63], v[50:51], v[38:39] op_sel_hi:[1,0,1] neg_lo:[1,0,0] neg_hi:[1,0,0]
	v_pk_fma_f32 v[44:45], v[50:51], v[44:45], v[92:93] op_sel:[1,0,0]
	v_pk_fma_f32 v[42:43], v[50:51], v[42:43], v[90:91] op_sel:[1,0,0]
	v_pk_mul_f32 v[48:49], v[48:49], v[54:55]
	v_pk_mul_f32 v[46:47], v[46:47], v[52:53]
	v_pk_fma_f32 v[40:41], v[50:51], v[40:41], v[60:61] op_sel:[1,0,0]
	v_pk_fma_f32 v[38:39], v[50:51], v[38:39], v[58:59] op_sel:[1,0,0]
	v_pk_mul_f32 v[44:45], v[44:45], v[48:49]
	v_pk_mul_f32 v[42:43], v[42:43], v[46:47]
	v_mul_f32_e32 v46, 0xbfb8aa3b, v38
	v_mul_f32_e32 v47, 0xbfb8aa3b, v39
	v_mul_f32_e32 v48, 0xbfb8aa3b, v40
	v_mul_f32_e32 v49, 0xbfb8aa3b, v41
	v_exp_f32_e32 v46, v46
	v_exp_f32_e32 v47, v47
	v_exp_f32_e32 v48, v48
	v_exp_f32_e32 v49, v49
	v_add_f32_e32 v46, 1.0, v46
	v_add_f32_e32 v47, 1.0, v47
	v_add_f32_e32 v48, 1.0, v48
	v_add_f32_e32 v49, 1.0, v49
	v_rcp_f32_e32 v46, v46
	v_rcp_f32_e32 v47, v47
	v_rcp_f32_e32 v48, v48
	v_rcp_f32_e32 v49, v49
	v_pk_fma_f32 v[36:37], v[68:69], v[50:51], v[36:37] op_sel_hi:[1,0,1]
	v_pk_fma_f32 v[34:35], v[66:67], v[50:51], v[34:35] op_sel_hi:[1,0,1] neg_lo:[1,0,0] neg_hi:[1,0,0]
	v_pk_fma_f32 v[36:37], v[50:51], v[36:37], v[72:73] op_sel:[1,0,0]
	v_pk_fma_f32 v[34:35], v[50:51], v[34:35], v[70:71] op_sel:[1,0,0]
	v_pk_mul_f32 v[40:41], v[40:41], v[48:49]
	v_pk_mul_f32 v[38:39], v[38:39], v[46:47]
	v_pk_mul_f32 v[40:41], v[36:37], v[40:41]
	v_pk_mul_f32 v[36:37], v[34:35], v[38:39]
	v_add_lshl_u32 v38, v82, v130, 1
	v_cvt_pk_bf16_f32 v34, v42, v43
	v_cvt_pk_bf16_f32 v35, v44, v45
	v_cvt_pk_bf16_f32 v36, v36, v37
	v_cvt_pk_bf16_f32 v37, v40, v41
	buffer_store_dwordx4 v[34:37], v38, s[28:31], 0 offen sc1
	s_nop 1
	v_mov_b32_e32 v34, v173
	s_nop 0
	v_lshl_add_u32 v41, v34, 3, s33
	v_add_u32_e32 v40, s3, v34
	ds_read_b64 v[34:35], v41
	s_mov_b32 s3, s77
	s_waitcnt lgkmcnt(0)
	v_pk_fma_f32 v[32:33], v[88:89], v[34:35], v[32:33] op_sel_hi:[1,0,1]
	v_pk_fma_f32 v[30:31], v[86:87], v[34:35], v[30:31] op_sel_hi:[1,0,1] neg_lo:[1,0,0] neg_hi:[1,0,0]
	v_pk_fma_f32 v[32:33], v[34:35], v[32:33], v[80:81] op_sel:[1,0,0]
	v_pk_fma_f32 v[30:31], v[34:35], v[30:31], v[78:79] op_sel:[1,0,0]
	v_mul_f32_e32 v38, 0xbfb8aa3b, v32
	v_mul_f32_e32 v36, 0xbfb8aa3b, v30
	v_mul_f32_e32 v37, 0xbfb8aa3b, v31
	v_mul_f32_e32 v39, 0xbfb8aa3b, v33
	v_exp_f32_e32 v36, v36
	v_exp_f32_e32 v37, v37
	v_exp_f32_e32 v38, v38
	v_exp_f32_e32 v39, v39
	v_add_f32_e32 v36, 1.0, v36
	v_add_f32_e32 v37, 1.0, v37
	v_add_f32_e32 v38, 1.0, v38
	v_add_f32_e32 v39, 1.0, v39
	v_rcp_f32_e32 v36, v36
	v_rcp_f32_e32 v37, v37
	v_rcp_f32_e32 v38, v38
	v_rcp_f32_e32 v39, v39
	v_pk_fma_f32 v[28:29], v[96:97], v[34:35], v[28:29] op_sel_hi:[1,0,1]
	v_pk_fma_f32 v[26:27], v[94:95], v[34:35], v[26:27] op_sel_hi:[1,0,1] neg_lo:[1,0,0] neg_hi:[1,0,0]
	v_pk_fma_f32 v[24:25], v[64:65], v[34:35], v[24:25] op_sel_hi:[1,0,1]
	v_pk_fma_f32 v[22:23], v[62:63], v[34:35], v[22:23] op_sel_hi:[1,0,1] neg_lo:[1,0,0] neg_hi:[1,0,0]
	v_pk_fma_f32 v[28:29], v[34:35], v[28:29], v[92:93] op_sel:[1,0,0]
	v_pk_fma_f32 v[26:27], v[34:35], v[26:27], v[90:91] op_sel:[1,0,0]
	v_pk_mul_f32 v[32:33], v[32:33], v[38:39]
	v_pk_mul_f32 v[30:31], v[30:31], v[36:37]
	v_pk_fma_f32 v[24:25], v[34:35], v[24:25], v[60:61] op_sel:[1,0,0]
	v_pk_fma_f32 v[22:23], v[34:35], v[22:23], v[58:59] op_sel:[1,0,0]
	v_pk_mul_f32 v[28:29], v[28:29], v[32:33]
	v_pk_mul_f32 v[26:27], v[26:27], v[30:31]
	v_mul_f32_e32 v30, 0xbfb8aa3b, v22
	v_mul_f32_e32 v31, 0xbfb8aa3b, v23
	v_mul_f32_e32 v32, 0xbfb8aa3b, v24
	v_mul_f32_e32 v33, 0xbfb8aa3b, v25
	v_exp_f32_e32 v30, v30
	v_exp_f32_e32 v31, v31
	v_exp_f32_e32 v32, v32
	v_exp_f32_e32 v33, v33
	v_add_f32_e32 v30, 1.0, v30
	v_add_f32_e32 v31, 1.0, v31
	v_add_f32_e32 v32, 1.0, v32
	v_add_f32_e32 v33, 1.0, v33
	v_rcp_f32_e32 v30, v30
	v_rcp_f32_e32 v31, v31
	v_rcp_f32_e32 v32, v32
	v_rcp_f32_e32 v33, v33
	v_pk_fma_f32 v[20:21], v[68:69], v[34:35], v[20:21] op_sel_hi:[1,0,1]
	v_pk_fma_f32 v[18:19], v[66:67], v[34:35], v[18:19] op_sel_hi:[1,0,1] neg_lo:[1,0,0] neg_hi:[1,0,0]
	v_pk_fma_f32 v[20:21], v[34:35], v[20:21], v[72:73] op_sel:[1,0,0]
	v_pk_fma_f32 v[18:19], v[34:35], v[18:19], v[70:71] op_sel:[1,0,0]
	v_pk_mul_f32 v[24:25], v[24:25], v[32:33]
	v_pk_mul_f32 v[22:23], v[22:23], v[30:31]
	v_mul_lo_u32 v30, v40, s27
	v_pk_mul_f32 v[24:25], v[20:21], v[24:25]
	v_pk_mul_f32 v[20:21], v[18:19], v[22:23]
	v_add_lshl_u32 v22, v30, v176, 1
	v_cvt_pk_bf16_f32 v18, v26, v27
	v_cvt_pk_bf16_f32 v19, v28, v29
	v_cvt_pk_bf16_f32 v20, v20, v21
	v_cvt_pk_bf16_f32 v21, v24, v25
	buffer_store_dwordx4 v[18:21], v22, s[28:31], 0 offen sc1
	ds_read_b64 v[18:19], v41 offset:128
	s_mov_b32 s27, s58
	s_waitcnt lgkmcnt(0)
	v_pk_fma_f32 v[16:17], v[88:89], v[18:19], v[16:17] op_sel_hi:[1,0,1]
	v_pk_fma_f32 v[14:15], v[86:87], v[18:19], v[14:15] op_sel_hi:[1,0,1] neg_lo:[1,0,0] neg_hi:[1,0,0]
	v_pk_fma_f32 v[16:17], v[18:19], v[16:17], v[80:81] op_sel:[1,0,0]
	v_pk_fma_f32 v[14:15], v[18:19], v[14:15], v[78:79] op_sel:[1,0,0]
	v_mul_f32_e32 v22, 0xbfb8aa3b, v16
	v_mul_f32_e32 v20, 0xbfb8aa3b, v14
	v_mul_f32_e32 v21, 0xbfb8aa3b, v15
	v_mul_f32_e32 v23, 0xbfb8aa3b, v17
	v_exp_f32_e32 v20, v20
	v_exp_f32_e32 v21, v21
	v_exp_f32_e32 v22, v22
	v_exp_f32_e32 v23, v23
	v_add_f32_e32 v20, 1.0, v20
	v_add_f32_e32 v21, 1.0, v21
	v_add_f32_e32 v22, 1.0, v22
	v_add_f32_e32 v23, 1.0, v23
	v_rcp_f32_e32 v20, v20
	v_rcp_f32_e32 v21, v21
	v_rcp_f32_e32 v22, v22
	v_rcp_f32_e32 v23, v23
	v_pk_fma_f32 v[12:13], v[96:97], v[18:19], v[12:13] op_sel_hi:[1,0,1]
	v_pk_fma_f32 v[10:11], v[94:95], v[18:19], v[10:11] op_sel_hi:[1,0,1] neg_lo:[1,0,0] neg_hi:[1,0,0]
	v_pk_fma_f32 v[8:9], v[64:65], v[18:19], v[8:9] op_sel_hi:[1,0,1]
	v_pk_fma_f32 v[6:7], v[62:63], v[18:19], v[6:7] op_sel_hi:[1,0,1] neg_lo:[1,0,0] neg_hi:[1,0,0]
	v_pk_fma_f32 v[12:13], v[18:19], v[12:13], v[92:93] op_sel:[1,0,0]
	v_pk_fma_f32 v[10:11], v[18:19], v[10:11], v[90:91] op_sel:[1,0,0]
	v_pk_mul_f32 v[16:17], v[16:17], v[22:23]
	v_pk_mul_f32 v[14:15], v[14:15], v[20:21]
	v_pk_fma_f32 v[8:9], v[18:19], v[8:9], v[60:61] op_sel:[1,0,0]
	v_pk_fma_f32 v[6:7], v[18:19], v[6:7], v[58:59] op_sel:[1,0,0]
	v_pk_mul_f32 v[12:13], v[12:13], v[16:17]
	v_pk_mul_f32 v[10:11], v[10:11], v[14:15]
	v_mul_f32_e32 v14, 0xbfb8aa3b, v6
	v_mul_f32_e32 v15, 0xbfb8aa3b, v7
	v_mul_f32_e32 v16, 0xbfb8aa3b, v8
	v_mul_f32_e32 v17, 0xbfb8aa3b, v9
	v_exp_f32_e32 v14, v14
	v_exp_f32_e32 v15, v15
	v_exp_f32_e32 v16, v16
	v_exp_f32_e32 v17, v17
	v_add_f32_e32 v14, 1.0, v14
	v_add_f32_e32 v15, 1.0, v15
	v_add_f32_e32 v16, 1.0, v16
	v_add_f32_e32 v17, 1.0, v17
	v_rcp_f32_e32 v14, v14
	v_rcp_f32_e32 v15, v15
	v_rcp_f32_e32 v16, v16
	v_rcp_f32_e32 v17, v17
	v_pk_fma_f32 v[4:5], v[68:69], v[18:19], v[4:5] op_sel_hi:[1,0,1]
	v_pk_fma_f32 v[2:3], v[66:67], v[18:19], v[2:3] op_sel_hi:[1,0,1] neg_lo:[1,0,0] neg_hi:[1,0,0]
	v_pk_fma_f32 v[4:5], v[18:19], v[4:5], v[72:73] op_sel:[1,0,0]
	v_pk_fma_f32 v[2:3], v[18:19], v[2:3], v[70:71] op_sel:[1,0,0]
	v_pk_mul_f32 v[8:9], v[8:9], v[16:17]
	v_pk_mul_f32 v[6:7], v[6:7], v[14:15]
	v_pk_mul_f32 v[8:9], v[4:5], v[8:9]
	v_pk_mul_f32 v[4:5], v[2:3], v[6:7]
	v_add_lshl_u32 v6, v30, v130, 1
	v_cvt_pk_bf16_f32 v2, v10, v11
	v_cvt_pk_bf16_f32 v3, v12, v13
	v_cvt_pk_bf16_f32 v4, v4, v5
	v_cvt_pk_bf16_f32 v5, v8, v9
	buffer_store_dwordx4 v[2:5], v6, s[28:31], 0 offen sc1
	s_cbranch_vccz .LBB0_1098
	s_waitcnt vmcnt(0)
	v_readlane_b32 s76, v255, 13
	s_cmpk_gt_u32 s38, 0xff
	v_readlane_b32 s77, v255, 14
	s_cbranch_scc1 .LBB0_1103
	s_barrier
